# re-measure of v11 (unchanged) for run-to-run spread
# speedup vs baseline: 1.0447x; 1.0031x over previous
; #define PG8_STAGE(bufoff, gbase, voff) do { _Pragma("unroll") for (int _i = 0; _i < 2; ++_i) \
;         __builtin_amdgcn_global_load_lds((const unsigned*)((const char*)(gbase) + (voff)[_i]), (PG8_LAS unsigned*)(lds + (bufoff) + ldsw + _i * 8192), 16, 0, 0); } while (0)
; #define PG8_LDA(dst, b, h) do { _Pragma("unroll") for (int m = 0; m < 4; ++m) _Pragma("unroll") for (int k = 0; k < 2; ++k) dst[m][k] = *(const PG8_LAS bf16x8*)(lds + PG8_SA(b, h) + aoff + m * 2048 + k * 1024); } while (0)
; #define PG8_LDB(dst, b, h) do { _Pragma("unroll") for (int n = 0; n < 2; ++n) _Pragma("unroll") for (int k = 0; k < 2; ++k) dst[n][k] = *(const PG8_LAS bf16x8*)(lds + PG8_SB(b, h) + boff + n * 2048 + k * 1024); } while (0)
; #define PG8_MMA(ai, bj, At, Bt) do { __builtin_amdgcn_s_setprio(1); _Pragma("unroll") for (int m = 0; m < 4; ++m) _Pragma("unroll") for (int n = 0; n < 2; ++n) _Pragma("unroll") for (int k = 0; k < 2; ++k) \
;         acc[ai][bj][m][n] = __builtin_amdgcn_mfma_f32_16x16x32_bf16(Bt[n][k], At[m][k], acc[ai][bj][m][n], 0, 0, 0); __builtin_amdgcn_s_setprio(0); } while (0)
; #define PG8_WAIT_V(n) asm volatile("s_waitcnt vmcnt(" #n ")" ::: "memory")
; #define PG8_WAIT_L(n) asm volatile("s_waitcnt lgkmcnt(" #n ")" ::: "memory")
; #define PG8_BAR __builtin_amdgcn_s_barrier()
; #define PG8_SCHED __builtin_amdgcn_sched_barrier(0)
; template <class Epi, class Sched, bool ALIGN_EPI = false, bool SP2 = false>
; __device__ __forceinline__ void gemm_phase(PG8_LAS unsigned char* lds, const Gemm g, const Sched& S, const Epi& E, int tid_in) {
;     ...
;             PG8_LDB(B0, 0, 0); PG8_LDB(B1, 0, 1); PG8_SCHED; PG8_LDA(At, 0, 0); PG8_STAGE(PG8_SA(1, 1), a1 + hstep, voffA);
;             PG8_WAIT_V(8); PG8_WAIT_L(0); PG8_BAR; PG8_MMA(0, 0, At, B0); PG8_MMA(0, 1, At, B1); PG8_BAR; PG8_SCHED;
;             PG8_LDA(At, 0, 1); PG8_STAGE(PG8_SB(0, 0), b2, voffB); PG8_STAGE(PG8_SB(0, 1), b2 + hstep, voffB); PG8_STAGE(PG8_SA(0, 0), a2, voffA);
;             PG8_WAIT_V(8); PG8_WAIT_L(0); PG8_BAR; PG8_MMA(1, 0, At, B0); PG8_MMA(1, 1, At, B1); PG8_BAR; PG8_SCHED;
.LBB0_116:
	ds_read_b128 v[148:151], v175
	ds_read_b128 v[152:155], v175 offset:1024
	ds_read_b128 v[156:159], v175 offset:2048
	ds_read_b128 v[160:163], v175 offset:3072
	ds_read_b128 v[164:167], v176
	ds_read_b128 v[180:183], v176 offset:1024
	ds_read_b128 v[184:187], v176 offset:2048
	ds_read_b128 v[188:191], v176 offset:3072
	s_add_u32 s66, s6, 0xfffc0080
	s_addc_u32 s67, s7, -1
	s_cmp_eq_u32 s91, 12
	s_cselect_b32 s71, s53, s67
	s_cselect_b32 s70, s87, s66
	s_cselect_b32 s67, s43, s90
	s_cselect_b32 s66, s88, s89
	v_lshl_add_u64 v[212:213], s[6:7], 0, v[140:141]
	s_add_i32 m0, s63, 0xc000
	ds_read_b128 v[192:195], v177
	ds_read_b128 v[196:199], v177 offset:1024
	ds_read_b128 v[200:203], v177 offset:2048
	ds_read_b128 v[204:207], v177 offset:3072
	ds_read_b128 v[208:211], v177 offset:4096
	ds_read_b128 v[220:223], v177 offset:5120
	ds_read_b128 v[224:227], v177 offset:6144
	ds_read_b128 v[230:233], v177 offset:7168
	global_load_lds_dwordx4 v[212:213], off
	v_lshl_add_u64 v[212:213], s[6:7], 0, v[142:143]
	s_add_i32 m0, s63, 0xe000
	s_nop 0
	global_load_lds_dwordx4 v[212:213], off
	s_waitcnt vmcnt(8)
	s_waitcnt lgkmcnt(0)
	s_barrier
	s_setprio 1
	s_waitcnt lgkmcnt(0)
	v_mfma_f32_16x16x32_bf16 v[124:127], v[148:151], v[192:195], v[124:127]
	v_mfma_f32_16x16x32_bf16 v[120:123], v[156:159], v[192:195], v[120:123]
	v_mfma_f32_16x16x32_bf16 v[108:111], v[148:151], v[200:203], v[108:111]
	v_mfma_f32_16x16x32_bf16 v[104:107], v[156:159], v[200:203], v[104:107]
	v_mfma_f32_16x16x32_bf16 v[92:95], v[148:151], v[208:211], v[92:95]
	v_mfma_f32_16x16x32_bf16 v[88:91], v[156:159], v[208:211], v[88:91]
	v_mfma_f32_16x16x32_bf16 v[76:79], v[148:151], v[224:227], v[76:79]
	v_mfma_f32_16x16x32_bf16 v[72:75], v[156:159], v[224:227], v[72:75]
	v_mfma_f32_16x16x32_bf16 v[124:127], v[152:155], v[196:199], v[124:127]
	v_mfma_f32_16x16x32_bf16 v[120:123], v[160:163], v[196:199], v[120:123]
	v_mfma_f32_16x16x32_bf16 v[108:111], v[152:155], v[204:207], v[108:111]
	v_mfma_f32_16x16x32_bf16 v[104:107], v[160:163], v[204:207], v[104:107]
	v_mfma_f32_16x16x32_bf16 v[92:95], v[152:155], v[220:223], v[92:95]
	v_mfma_f32_16x16x32_bf16 v[88:91], v[160:163], v[220:223], v[88:91]
	v_mfma_f32_16x16x32_bf16 v[76:79], v[152:155], v[230:233], v[76:79]
	v_mfma_f32_16x16x32_bf16 v[72:75], v[160:163], v[230:233], v[72:75]
	v_mfma_f32_16x16x32_bf16 v[116:119], v[164:167], v[192:195], v[116:119]
	v_mfma_f32_16x16x32_bf16 v[112:115], v[184:187], v[192:195], v[112:115]
	v_mfma_f32_16x16x32_bf16 v[100:103], v[164:167], v[200:203], v[100:103]
	v_mfma_f32_16x16x32_bf16 v[96:99], v[184:187], v[200:203], v[96:99]
	v_mfma_f32_16x16x32_bf16 v[84:87], v[164:167], v[208:211], v[84:87]
	v_mfma_f32_16x16x32_bf16 v[80:83], v[184:187], v[208:211], v[80:83]
	v_mfma_f32_16x16x32_bf16 v[68:71], v[164:167], v[224:227], v[68:71]
	v_mfma_f32_16x16x32_bf16 v[64:67], v[184:187], v[224:227], v[64:67]
	v_mfma_f32_16x16x32_bf16 v[116:119], v[180:183], v[196:199], v[116:119]
	v_mfma_f32_16x16x32_bf16 v[112:115], v[188:191], v[196:199], v[112:115]
	v_mfma_f32_16x16x32_bf16 v[100:103], v[180:183], v[204:207], v[100:103]
	v_mfma_f32_16x16x32_bf16 v[96:99], v[188:191], v[204:207], v[96:99]
	v_mfma_f32_16x16x32_bf16 v[84:87], v[180:183], v[220:223], v[84:87]
	v_mfma_f32_16x16x32_bf16 v[80:83], v[188:191], v[220:223], v[80:83]
	v_mfma_f32_16x16x32_bf16 v[68:71], v[180:183], v[230:233], v[68:71]
	v_mfma_f32_16x16x32_bf16 v[64:67], v[188:191], v[230:233], v[64:67]
	s_setprio 0
	s_barrier
	s_add_i32 s92, s79, s69
	v_lshl_add_u64 v[212:213], s[66:67], 0, v[130:131]
	s_mov_b32 m0, s92
	ds_read_b128 v[192:195], v177 offset:16384
	ds_read_b128 v[196:199], v177 offset:17408
	ds_read_b128 v[200:203], v177 offset:18432
	ds_read_b128 v[204:207], v177 offset:19456
	ds_read_b128 v[208:211], v177 offset:20480
	ds_read_b128 v[220:223], v177 offset:21504
	ds_read_b128 v[224:227], v177 offset:22528
	ds_read_b128 v[230:233], v177 offset:23552
	global_load_lds_dwordx4 v[212:213], off
	s_add_i32 m0, s92, 0x2000
	s_add_u32 s92, s66, 0x40000
	v_lshl_add_u64 v[216:217], s[66:67], 0, v[134:135]
	s_addc_u32 s93, s67, 0
	s_add_i32 s94, s80, s69
	global_load_lds_dwordx4 v[216:217], off
	v_lshl_add_u64 v[234:235], s[92:93], 0, v[130:131]
	s_mov_b32 m0, s94
	v_lshl_add_u64 v[236:237], s[70:71], 0, v[132:133]
	global_load_lds_dwordx4 v[234:235], off
	v_lshl_add_u64 v[234:235], s[92:93], 0, v[134:135]
	s_add_i32 m0, s94, 0x2000
	s_nop 0
	global_load_lds_dwordx4 v[234:235], off
	v_lshl_add_u64 v[234:235], s[70:71], 0, v[128:129]
	s_mov_b32 m0, s63
	s_nop 0
	global_load_lds_dwordx4 v[234:235], off
	s_mov_b32 m0, s65
	s_nop 0
	global_load_lds_dwordx4 v[236:237], off
	s_waitcnt vmcnt(8)
	s_waitcnt lgkmcnt(0)
	s_barrier
; #define PG8_STAGE(bufoff, gbase, voff) do { _Pragma("unroll") for (int _i = 0; _i < 2; ++_i) \
;         __builtin_amdgcn_global_load_lds((const unsigned*)((const char*)(gbase) + (voff)[_i]), (PG8_LAS unsigned*)(lds + (bufoff) + ldsw + _i * 8192), 16, 0, 0); } while (0)
; #define PG8_LDA(dst, b, h) do { _Pragma("unroll") for (int m = 0; m < 4; ++m) _Pragma("unroll") for (int k = 0; k < 2; ++k) dst[m][k] = *(const PG8_LAS bf16x8*)(lds + PG8_SA(b, h) + aoff + m * 2048 + k * 1024); } while (0)
; #define PG8_LDB(dst, b, h) do { _Pragma("unroll") for (int n = 0; n < 2; ++n) _Pragma("unroll") for (int k = 0; k < 2; ++k) dst[n][k] = *(const PG8_LAS bf16x8*)(lds + PG8_SB(b, h) + boff + n * 2048 + k * 1024); } while (0)
; #define PG8_MMA(ai, bj, At, Bt) do { __builtin_amdgcn_s_setprio(1); _Pragma("unroll") for (int m = 0; m < 4; ++m) _Pragma("unroll") for (int n = 0; n < 2; ++n) _Pragma("unroll") for (int k = 0; k < 2; ++k) \
;         acc[ai][bj][m][n] = __builtin_amdgcn_mfma_f32_16x16x32_bf16(Bt[n][k], At[m][k], acc[ai][bj][m][n], 0, 0, 0); __builtin_amdgcn_s_setprio(0); } while (0)
; #define PG8_WAIT_V(n) asm volatile("s_waitcnt vmcnt(" #n ")" ::: "memory")
; #define PG8_WAIT_L(n) asm volatile("s_waitcnt lgkmcnt(" #n ")" ::: "memory")
; #define PG8_BAR __builtin_amdgcn_s_barrier()
; #define PG8_SCHED __builtin_amdgcn_sched_barrier(0)
; template <class Epi, class Sched, bool ALIGN_EPI = false, bool SP2 = false>
; __device__ __forceinline__ void gemm_phase(PG8_LAS unsigned char* lds, const Gemm g, const Sched& S, const Epi& E, int tid_in) {
;     ...
;             PG8_WAIT_V(8); PG8_WAIT_L(0); PG8_BAR; PG8_MMA(1, 0, At, B0); PG8_MMA(1, 1, At, B1); PG8_BAR; PG8_SCHED;
;             PG8_LDB(B0, 1, 0); PG8_LDB(B1, 1, 1); PG8_SCHED; PG8_LDA(At, 1, 0); PG8_STAGE(PG8_SA(0, 1), a2 + hstep, voffA);
;             PG8_WAIT_V(8); PG8_WAIT_L(0); PG8_BAR; PG8_MMA(0, 0, At, B0); PG8_MMA(0, 1, At, B1); PG8_BAR; PG8_SCHED;
	s_setprio 1
	s_waitcnt lgkmcnt(0)
	v_mfma_f32_16x16x32_bf16 v[60:63], v[148:151], v[192:195], v[60:63]
	v_mfma_f32_16x16x32_bf16 v[56:59], v[156:159], v[192:195], v[56:59]
	v_mfma_f32_16x16x32_bf16 v[44:47], v[148:151], v[200:203], v[44:47]
	v_mfma_f32_16x16x32_bf16 v[40:43], v[156:159], v[200:203], v[40:43]
	v_mfma_f32_16x16x32_bf16 v[28:31], v[148:151], v[208:211], v[28:31]
	v_mfma_f32_16x16x32_bf16 v[24:27], v[156:159], v[208:211], v[24:27]
	v_mfma_f32_16x16x32_bf16 v[12:15], v[148:151], v[224:227], v[12:15]
	v_mfma_f32_16x16x32_bf16 v[8:11], v[156:159], v[224:227], v[8:11]
	v_mfma_f32_16x16x32_bf16 v[60:63], v[152:155], v[196:199], v[60:63]
	v_mfma_f32_16x16x32_bf16 v[56:59], v[160:163], v[196:199], v[56:59]
	v_mfma_f32_16x16x32_bf16 v[44:47], v[152:155], v[204:207], v[44:47]
	v_mfma_f32_16x16x32_bf16 v[40:43], v[160:163], v[204:207], v[40:43]
	v_mfma_f32_16x16x32_bf16 v[28:31], v[152:155], v[220:223], v[28:31]
	v_mfma_f32_16x16x32_bf16 v[24:27], v[160:163], v[220:223], v[24:27]
	v_mfma_f32_16x16x32_bf16 v[12:15], v[152:155], v[230:233], v[12:15]
	v_mfma_f32_16x16x32_bf16 v[8:11], v[160:163], v[230:233], v[8:11]
	v_mfma_f32_16x16x32_bf16 v[52:55], v[164:167], v[192:195], v[52:55]
	v_mfma_f32_16x16x32_bf16 v[48:51], v[184:187], v[192:195], v[48:51]
	v_mfma_f32_16x16x32_bf16 v[36:39], v[164:167], v[200:203], v[36:39]
	v_mfma_f32_16x16x32_bf16 v[32:35], v[184:187], v[200:203], v[32:35]
	v_mfma_f32_16x16x32_bf16 v[20:23], v[164:167], v[208:211], v[20:23]
	v_mfma_f32_16x16x32_bf16 v[16:19], v[184:187], v[208:211], v[16:19]
	v_mfma_f32_16x16x32_bf16 v[4:7], v[164:167], v[224:227], v[4:7]
	v_mfma_f32_16x16x32_bf16 v[0:3], v[184:187], v[224:227], v[0:3]
	v_mfma_f32_16x16x32_bf16 v[52:55], v[180:183], v[196:199], v[52:55]
	v_mfma_f32_16x16x32_bf16 v[48:51], v[188:191], v[196:199], v[48:51]
	v_mfma_f32_16x16x32_bf16 v[36:39], v[180:183], v[204:207], v[36:39]
	v_mfma_f32_16x16x32_bf16 v[32:35], v[188:191], v[204:207], v[32:35]
	v_mfma_f32_16x16x32_bf16 v[20:23], v[180:183], v[220:223], v[20:23]
	v_mfma_f32_16x16x32_bf16 v[16:19], v[188:191], v[220:223], v[16:19]
	v_mfma_f32_16x16x32_bf16 v[4:7], v[180:183], v[230:233], v[4:7]
	v_mfma_f32_16x16x32_bf16 v[0:3], v[188:191], v[230:233], v[0:3]
	s_setprio 0
	s_barrier
	s_add_i32 s92, 0, 0x18000
	s_add_i32 s93, 0, 0x1c000
	v_add_u32_e32 v160, s92, v172
	v_add_u32_e32 v168, s93, v172
	ds_read_b128 v[148:151], v160
	ds_read_b128 v[152:155], v160 offset:1024
	ds_read_b128 v[156:159], v160 offset:2048
	ds_read_b128 v[160:163], v160 offset:3072
	ds_read_b128 v[164:167], v168
	ds_read_b128 v[180:183], v168 offset:1024
	ds_read_b128 v[184:187], v168 offset:2048
	ds_read_b128 v[188:191], v168 offset:3072
	s_add_u32 s70, s70, 0x40000
	s_addc_u32 s71, s71, 0
	s_mov_b32 m0, s72
	v_lshl_add_u64 v[238:239], s[70:71], 0, v[128:129]
	ds_read_b128 v[192:195], v177 offset:32768
	ds_read_b128 v[196:199], v177 offset:33792
	ds_read_b128 v[200:203], v177 offset:34816
	ds_read_b128 v[204:207], v177 offset:35840
	ds_read_b128 v[208:211], v177 offset:36864
	ds_read_b128 v[220:223], v177 offset:37888
	ds_read_b128 v[224:227], v177 offset:38912
	ds_read_b128 v[230:233], v177 offset:39936
	global_load_lds_dwordx4 v[238:239], off
	v_lshl_add_u64 v[238:239], s[70:71], 0, v[132:133]
	s_mov_b32 m0, s73
	s_nop 0
	global_load_lds_dwordx4 v[238:239], off
	s_waitcnt vmcnt(8)
	s_waitcnt lgkmcnt(0)
	s_barrier
	s_setprio 1
	s_waitcnt lgkmcnt(0)
	v_mfma_f32_16x16x32_bf16 v[124:127], v[148:151], v[192:195], v[124:127]
	v_mfma_f32_16x16x32_bf16 v[120:123], v[156:159], v[192:195], v[120:123]
	v_mfma_f32_16x16x32_bf16 v[108:111], v[148:151], v[200:203], v[108:111]
	v_mfma_f32_16x16x32_bf16 v[104:107], v[156:159], v[200:203], v[104:107]
	v_mfma_f32_16x16x32_bf16 v[92:95], v[148:151], v[208:211], v[92:95]
	v_mfma_f32_16x16x32_bf16 v[88:91], v[156:159], v[208:211], v[88:91]
	v_mfma_f32_16x16x32_bf16 v[76:79], v[148:151], v[224:227], v[76:79]
	v_mfma_f32_16x16x32_bf16 v[72:75], v[156:159], v[224:227], v[72:75]
	v_mfma_f32_16x16x32_bf16 v[124:127], v[152:155], v[196:199], v[124:127]
	v_mfma_f32_16x16x32_bf16 v[120:123], v[160:163], v[196:199], v[120:123]
	v_mfma_f32_16x16x32_bf16 v[108:111], v[152:155], v[204:207], v[108:111]
	v_mfma_f32_16x16x32_bf16 v[104:107], v[160:163], v[204:207], v[104:107]
	v_mfma_f32_16x16x32_bf16 v[92:95], v[152:155], v[220:223], v[92:95]
	v_mfma_f32_16x16x32_bf16 v[88:91], v[160:163], v[220:223], v[88:91]
	v_mfma_f32_16x16x32_bf16 v[76:79], v[152:155], v[230:233], v[76:79]
	v_mfma_f32_16x16x32_bf16 v[72:75], v[160:163], v[230:233], v[72:75]
	v_mfma_f32_16x16x32_bf16 v[116:119], v[164:167], v[192:195], v[116:119]
	v_mfma_f32_16x16x32_bf16 v[112:115], v[184:187], v[192:195], v[112:115]
	v_mfma_f32_16x16x32_bf16 v[100:103], v[164:167], v[200:203], v[100:103]
	v_mfma_f32_16x16x32_bf16 v[96:99], v[184:187], v[200:203], v[96:99]
	v_mfma_f32_16x16x32_bf16 v[84:87], v[164:167], v[208:211], v[84:87]
	v_mfma_f32_16x16x32_bf16 v[80:83], v[184:187], v[208:211], v[80:83]
	v_mfma_f32_16x16x32_bf16 v[68:71], v[164:167], v[224:227], v[68:71]
	v_mfma_f32_16x16x32_bf16 v[64:67], v[184:187], v[224:227], v[64:67]
	v_mfma_f32_16x16x32_bf16 v[116:119], v[180:183], v[196:199], v[116:119]
	v_mfma_f32_16x16x32_bf16 v[112:115], v[188:191], v[196:199], v[112:115]
	v_mfma_f32_16x16x32_bf16 v[100:103], v[180:183], v[204:207], v[100:103]
	v_mfma_f32_16x16x32_bf16 v[96:99], v[188:191], v[204:207], v[96:99]
	v_mfma_f32_16x16x32_bf16 v[84:87], v[180:183], v[220:223], v[84:87]
	v_mfma_f32_16x16x32_bf16 v[80:83], v[188:191], v[220:223], v[80:83]
	v_mfma_f32_16x16x32_bf16 v[68:71], v[180:183], v[230:233], v[68:71]
	v_mfma_f32_16x16x32_bf16 v[64:67], v[188:191], v[230:233], v[64:67]
	s_setprio 0
	s_barrier
; #define PG8_STAGE(bufoff, gbase, voff) do { _Pragma("unroll") for (int _i = 0; _i < 2; ++_i) \
;         __builtin_amdgcn_global_load_lds((const unsigned*)((const char*)(gbase) + (voff)[_i]), (PG8_LAS unsigned*)(lds + (bufoff) + ldsw + _i * 8192), 16, 0, 0); } while (0)
; #define PG8_WAIT_V(n) asm volatile("s_waitcnt vmcnt(" #n ")" ::: "memory")
; #define PG8_WAIT_L(n) asm volatile("s_waitcnt lgkmcnt(" #n ")" ::: "memory")
; template <class Epi, class Sched, bool ALIGN_EPI = false, bool SP2 = false>
; __device__ __forceinline__ void gemm_phase(PG8_LAS unsigned char* lds, const Gemm g, const Sched& S, const Epi& E, int tid_in) {
;     ...
;             PG8_LDA(At, 1, 1); PG8_STAGE(PG8_SB(1, 0), b3, voffB); PG8_STAGE(PG8_SB(1, 1), b3 + hstep, voffB); PG8_STAGE(PG8_SA(1, 0), a3, voffA);
;             PG8_WAIT_V(8); PG8_WAIT_L(0); PG8_BAR; PG8_MMA(1, 0, At, B0); PG8_MMA(1, 1, At, B1); PG8_BAR; PG8_SCHED;
;             } else {
;             PG8_LDB(B0, 0, 0); PG8_SCHED; PG8_LDA(At, 0, 0); PG8_STAGE(PG8_SA(1, 1), a1 + hstep, voffA);
;             PG8_WAIT_L(8); PG8_BAR; PG8_WAIT_L(0); PG8_MMA(0, 0, At, B0); PG8_BAR; PG8_SCHED;
;             PG8_LDB(B1, 0, 1); PG8_STAGE(PG8_SB(0, 0), b2, voffB);
;             PG8_BAR; PG8_WAIT_L(0); PG8_MMA(0, 1, At, B1); PG8_BAR;
;             PG8_LDA(At, 0, 1); PG8_STAGE(PG8_SA(0, 0), a2, voffA);
;             PG8_BAR; PG8_WAIT_L(0); PG8_MMA(1, 0, At, B0); PG8_BAR; PG8_SCHED;
;             PG8_STAGE(PG8_SB(0, 1), b2 + hstep, voffB);
;             PG8_WAIT_V(6); PG8_BAR; PG8_MMA(1, 1, At, B1); PG8_BAR;
;             PG8_LDB(B0, 1, 0); PG8_SCHED; PG8_LDA(At, 1, 0); PG8_STAGE(PG8_SA(0, 1), a2 + hstep, voffA);
;             PG8_WAIT_L(8); PG8_BAR; PG8_WAIT_L(0); PG8_MMA(0, 0, At, B0); PG8_BAR; PG8_SCHED;
;             PG8_LDB(B1, 1, 1); PG8_STAGE(PG8_SB(1, 0), b3, voffB);
;             PG8_BAR; PG8_WAIT_L(0); PG8_MMA(0, 1, At, B1); PG8_BAR;
;             PG8_LDA(At, 1, 1); PG8_STAGE(PG8_SA(1, 0), a3, voffA);
;             PG8_BAR; PG8_WAIT_L(0); PG8_MMA(1, 0, At, B0); PG8_BAR; PG8_SCHED;
;             PG8_STAGE(PG8_SB(1, 1), b3 + hstep, voffB);
;             PG8_WAIT_V(6); PG8_BAR; PG8_MMA(1, 1, At, B1); PG8_BAR;
;             }
;         }
;         if constexpr (ALIGN_EPI) { if (wr == 0) PG8_BAR; }
;         if constexpr (!Epi::AFTER_DRAIN) { E(acc, cur, wr, wc, fr, fq); S.done(cur); }
;         if (!has_next) break;
	s_add_i32 s70, s92, s69
	v_lshl_add_u64 v[212:213], v[212:213], 0, s[10:11]
	s_mov_b32 m0, s70
	ds_read_b128 v[192:195], v177 offset:49152
	ds_read_b128 v[196:199], v177 offset:50176
	ds_read_b128 v[200:203], v177 offset:51200
	ds_read_b128 v[204:207], v177 offset:52224
	ds_read_b128 v[208:211], v177 offset:53248
	ds_read_b128 v[220:223], v177 offset:54272
	ds_read_b128 v[224:227], v177 offset:55296
	ds_read_b128 v[230:233], v177 offset:56320
	global_load_lds_dwordx4 v[212:213], off
	s_add_i32 m0, s70, 0x2000
	s_add_u32 s66, s66, 0x40080
	v_lshl_add_u64 v[212:213], v[216:217], 0, s[10:11]
	s_addc_u32 s67, s67, 0
	s_add_i32 s70, s93, s69
	global_load_lds_dwordx4 v[212:213], off
	v_lshl_add_u64 v[212:213], s[66:67], 0, v[130:131]
	s_mov_b32 m0, s70
	s_nop 0
	global_load_lds_dwordx4 v[212:213], off
	v_lshl_add_u64 v[212:213], s[66:67], 0, v[134:135]
	s_add_i32 m0, s70, 0x2000
	s_nop 0
	global_load_lds_dwordx4 v[212:213], off
	v_lshl_add_u64 v[212:213], v[234:235], 0, s[10:11]
	s_mov_b32 m0, s75
	s_nop 0
	global_load_lds_dwordx4 v[212:213], off
	v_lshl_add_u64 v[212:213], v[236:237], 0, s[10:11]
	s_mov_b32 m0, s76
	s_nop 0
	global_load_lds_dwordx4 v[212:213], off
	s_waitcnt vmcnt(8)
	s_waitcnt lgkmcnt(0)
	s_barrier
	s_setprio 1
	s_waitcnt lgkmcnt(0)
	v_mfma_f32_16x16x32_bf16 v[60:63], v[148:151], v[192:195], v[60:63]
	v_mfma_f32_16x16x32_bf16 v[56:59], v[156:159], v[192:195], v[56:59]
	v_mfma_f32_16x16x32_bf16 v[44:47], v[148:151], v[200:203], v[44:47]
	v_mfma_f32_16x16x32_bf16 v[40:43], v[156:159], v[200:203], v[40:43]
	v_mfma_f32_16x16x32_bf16 v[28:31], v[148:151], v[208:211], v[28:31]
	v_mfma_f32_16x16x32_bf16 v[24:27], v[156:159], v[208:211], v[24:27]
	v_mfma_f32_16x16x32_bf16 v[12:15], v[148:151], v[224:227], v[12:15]
	v_mfma_f32_16x16x32_bf16 v[8:11], v[156:159], v[224:227], v[8:11]
	v_mfma_f32_16x16x32_bf16 v[60:63], v[152:155], v[196:199], v[60:63]
	v_mfma_f32_16x16x32_bf16 v[56:59], v[160:163], v[196:199], v[56:59]
	v_mfma_f32_16x16x32_bf16 v[44:47], v[152:155], v[204:207], v[44:47]
	v_mfma_f32_16x16x32_bf16 v[40:43], v[160:163], v[204:207], v[40:43]
	v_mfma_f32_16x16x32_bf16 v[28:31], v[152:155], v[220:223], v[28:31]
	v_mfma_f32_16x16x32_bf16 v[24:27], v[160:163], v[220:223], v[24:27]
	v_mfma_f32_16x16x32_bf16 v[12:15], v[152:155], v[230:233], v[12:15]
	v_mfma_f32_16x16x32_bf16 v[8:11], v[160:163], v[230:233], v[8:11]
	v_mfma_f32_16x16x32_bf16 v[52:55], v[164:167], v[192:195], v[52:55]
	v_mfma_f32_16x16x32_bf16 v[48:51], v[184:187], v[192:195], v[48:51]
	v_mfma_f32_16x16x32_bf16 v[36:39], v[164:167], v[200:203], v[36:39]
	v_mfma_f32_16x16x32_bf16 v[32:35], v[184:187], v[200:203], v[32:35]
	v_mfma_f32_16x16x32_bf16 v[20:23], v[164:167], v[208:211], v[20:23]
	v_mfma_f32_16x16x32_bf16 v[16:19], v[184:187], v[208:211], v[16:19]
	v_mfma_f32_16x16x32_bf16 v[4:7], v[164:167], v[224:227], v[4:7]
	v_mfma_f32_16x16x32_bf16 v[0:3], v[184:187], v[224:227], v[0:3]
	v_mfma_f32_16x16x32_bf16 v[52:55], v[180:183], v[196:199], v[52:55]
	v_mfma_f32_16x16x32_bf16 v[48:51], v[188:191], v[196:199], v[48:51]
	v_mfma_f32_16x16x32_bf16 v[36:39], v[180:183], v[204:207], v[36:39]
	v_mfma_f32_16x16x32_bf16 v[32:35], v[188:191], v[204:207], v[32:35]
	v_mfma_f32_16x16x32_bf16 v[20:23], v[180:183], v[220:223], v[20:23]
	v_mfma_f32_16x16x32_bf16 v[16:19], v[188:191], v[220:223], v[16:19]
	v_mfma_f32_16x16x32_bf16 v[4:7], v[180:183], v[230:233], v[4:7]
	v_mfma_f32_16x16x32_bf16 v[0:3], v[188:191], v[230:233], v[0:3]
	s_setprio 0
	s_barrier
	s_add_i32 s91, s91, 2
	s_add_u32 s6, s6, 0x100
	s_addc_u32 s7, s7, 0
	s_add_u32 s89, s89, 0x100
	s_addc_u32 s90, s90, 0
	s_cmp_gt_u32 s91, 13
	s_cbranch_scc0 .LBB0_116
	s_and_b64 vcc, exec, s[22:23]
	s_cbranch_vccz .LBB0_119
	s_barrier

; #define PG8_STAGE(bufoff, gbase, voff) do { _Pragma("unroll") for (int _i = 0; _i < 2; ++_i) \
;         __builtin_amdgcn_global_load_lds((const unsigned*)((const char*)(gbase) + (voff)[_i]), (PG8_LAS unsigned*)(lds + (bufoff) + ldsw + _i * 8192), 16, 0, 0); } while (0)
; #define PG8_LDA(dst, b, h) do { _Pragma("unroll") for (int m = 0; m < 4; ++m) _Pragma("unroll") for (int k = 0; k < 2; ++k) dst[m][k] = *(const PG8_LAS bf16x8*)(lds + PG8_SA(b, h) + aoff + m * 2048 + k * 1024); } while (0)
; #define PG8_LDB(dst, b, h) do { _Pragma("unroll") for (int n = 0; n < 2; ++n) _Pragma("unroll") for (int k = 0; k < 2; ++k) dst[n][k] = *(const PG8_LAS bf16x8*)(lds + PG8_SB(b, h) + boff + n * 2048 + k * 1024); } while (0)
; #define PG8_MMA(ai, bj, At, Bt) do { __builtin_amdgcn_s_setprio(1); _Pragma("unroll") for (int m = 0; m < 4; ++m) _Pragma("unroll") for (int n = 0; n < 2; ++n) _Pragma("unroll") for (int k = 0; k < 2; ++k) \
;         acc[ai][bj][m][n] = __builtin_amdgcn_mfma_f32_16x16x32_bf16(Bt[n][k], At[m][k], acc[ai][bj][m][n], 0, 0, 0); __builtin_amdgcn_s_setprio(0); } while (0)
; #define PG8_WAIT_V(n) asm volatile("s_waitcnt vmcnt(" #n ")" ::: "memory")
; #define PG8_WAIT_L(n) asm volatile("s_waitcnt lgkmcnt(" #n ")" ::: "memory")
; #define PG8_BAR __builtin_amdgcn_s_barrier()
; #define PG8_SCHED __builtin_amdgcn_sched_barrier(0)
; template <class Epi, class Sched, bool ALIGN_EPI = false, bool SP2 = false>
; __device__ __forceinline__ void gemm_phase(PG8_LAS unsigned char* lds, const Gemm g, const Sched& S, const Epi& E, int tid_in) {
;     ...
;             PG8_LDB(B0, 0, 0); PG8_LDB(B1, 0, 1); PG8_SCHED; PG8_LDA(At, 0, 0); PG8_STAGE(PG8_SA(1, 1), a1 + hstep, voffA);
;             PG8_WAIT_V(8); PG8_WAIT_L(0); PG8_BAR; PG8_MMA(0, 0, At, B0); PG8_MMA(0, 1, At, B1); PG8_BAR; PG8_SCHED;
;             PG8_LDA(At, 0, 1); PG8_STAGE(PG8_SB(0, 0), b2, voffB); PG8_STAGE(PG8_SB(0, 1), b2 + hstep, voffB); PG8_STAGE(PG8_SA(0, 0), a2, voffA);
;             PG8_WAIT_V(8); PG8_WAIT_L(0); PG8_BAR; PG8_MMA(1, 0, At, B0); PG8_MMA(1, 1, At, B1); PG8_BAR; PG8_SCHED;
.LBB0_166:
	ds_read_b128 v[148:151], v175
	ds_read_b128 v[152:155], v175 offset:1024
	ds_read_b128 v[156:159], v175 offset:2048
	ds_read_b128 v[160:163], v175 offset:3072
	ds_read_b128 v[164:167], v176
	ds_read_b128 v[180:183], v176 offset:1024
	ds_read_b128 v[184:187], v176 offset:2048
	ds_read_b128 v[188:191], v176 offset:3072
	s_add_u32 s70, s6, 0xfffc0080
	s_addc_u32 s71, s7, -1
	s_cmp_eq_u32 s95, 12
	s_cselect_b32 s73, s59, s71
	s_cselect_b32 s72, s91, s70
	s_cselect_b32 s71, s53, s94
	s_cselect_b32 s70, s92, s93
	v_lshl_add_u64 v[212:213], s[6:7], 0, v[140:141]
	s_add_i32 m0, s65, 0xc000
	ds_read_b128 v[192:195], v177
	ds_read_b128 v[196:199], v177 offset:1024
	ds_read_b128 v[200:203], v177 offset:2048
	ds_read_b128 v[204:207], v177 offset:3072
	ds_read_b128 v[208:211], v177 offset:4096
	ds_read_b128 v[220:223], v177 offset:5120
	ds_read_b128 v[224:227], v177 offset:6144
	ds_read_b128 v[230:233], v177 offset:7168
	global_load_lds_dwordx4 v[212:213], off
	v_lshl_add_u64 v[212:213], s[6:7], 0, v[142:143]
	s_add_i32 m0, s65, 0xe000
	s_nop 0
	global_load_lds_dwordx4 v[212:213], off
	s_waitcnt vmcnt(8)
	s_waitcnt lgkmcnt(0)
	s_barrier
	s_setprio 1
	s_waitcnt lgkmcnt(0)
	v_mfma_f32_16x16x32_bf16 v[124:127], v[148:151], v[192:195], v[124:127]
	v_mfma_f32_16x16x32_bf16 v[120:123], v[156:159], v[192:195], v[120:123]
	v_mfma_f32_16x16x32_bf16 v[108:111], v[148:151], v[200:203], v[108:111]
	v_mfma_f32_16x16x32_bf16 v[104:107], v[156:159], v[200:203], v[104:107]
	v_mfma_f32_16x16x32_bf16 v[92:95], v[148:151], v[208:211], v[92:95]
	v_mfma_f32_16x16x32_bf16 v[88:91], v[156:159], v[208:211], v[88:91]
	v_mfma_f32_16x16x32_bf16 v[76:79], v[148:151], v[224:227], v[76:79]
	v_mfma_f32_16x16x32_bf16 v[72:75], v[156:159], v[224:227], v[72:75]
	v_mfma_f32_16x16x32_bf16 v[124:127], v[152:155], v[196:199], v[124:127]
	v_mfma_f32_16x16x32_bf16 v[120:123], v[160:163], v[196:199], v[120:123]
	v_mfma_f32_16x16x32_bf16 v[108:111], v[152:155], v[204:207], v[108:111]
	v_mfma_f32_16x16x32_bf16 v[104:107], v[160:163], v[204:207], v[104:107]
	v_mfma_f32_16x16x32_bf16 v[92:95], v[152:155], v[220:223], v[92:95]
	v_mfma_f32_16x16x32_bf16 v[88:91], v[160:163], v[220:223], v[88:91]
	v_mfma_f32_16x16x32_bf16 v[76:79], v[152:155], v[230:233], v[76:79]
	v_mfma_f32_16x16x32_bf16 v[72:75], v[160:163], v[230:233], v[72:75]
	v_mfma_f32_16x16x32_bf16 v[116:119], v[164:167], v[192:195], v[116:119]
	v_mfma_f32_16x16x32_bf16 v[112:115], v[184:187], v[192:195], v[112:115]
	v_mfma_f32_16x16x32_bf16 v[100:103], v[164:167], v[200:203], v[100:103]
	v_mfma_f32_16x16x32_bf16 v[96:99], v[184:187], v[200:203], v[96:99]
	v_mfma_f32_16x16x32_bf16 v[84:87], v[164:167], v[208:211], v[84:87]
	v_mfma_f32_16x16x32_bf16 v[80:83], v[184:187], v[208:211], v[80:83]
	v_mfma_f32_16x16x32_bf16 v[68:71], v[164:167], v[224:227], v[68:71]
	v_mfma_f32_16x16x32_bf16 v[64:67], v[184:187], v[224:227], v[64:67]
	v_mfma_f32_16x16x32_bf16 v[116:119], v[180:183], v[196:199], v[116:119]
	v_mfma_f32_16x16x32_bf16 v[112:115], v[188:191], v[196:199], v[112:115]
	v_mfma_f32_16x16x32_bf16 v[100:103], v[180:183], v[204:207], v[100:103]
	v_mfma_f32_16x16x32_bf16 v[96:99], v[188:191], v[204:207], v[96:99]
	v_mfma_f32_16x16x32_bf16 v[84:87], v[180:183], v[220:223], v[84:87]
	v_mfma_f32_16x16x32_bf16 v[80:83], v[188:191], v[220:223], v[80:83]
	v_mfma_f32_16x16x32_bf16 v[68:71], v[180:183], v[230:233], v[68:71]
	v_mfma_f32_16x16x32_bf16 v[64:67], v[188:191], v[230:233], v[64:67]
	s_setprio 0
	s_barrier
	s_add_i32 s96, s83, s75
	v_lshl_add_u64 v[212:213], s[70:71], 0, v[130:131]
	s_mov_b32 m0, s96
	ds_read_b128 v[192:195], v177 offset:16384
	ds_read_b128 v[196:199], v177 offset:17408
	ds_read_b128 v[200:203], v177 offset:18432
	ds_read_b128 v[204:207], v177 offset:19456
	ds_read_b128 v[208:211], v177 offset:20480
	ds_read_b128 v[220:223], v177 offset:21504
	ds_read_b128 v[224:227], v177 offset:22528
	ds_read_b128 v[230:233], v177 offset:23552
	global_load_lds_dwordx4 v[212:213], off
	s_add_i32 m0, s96, 0x2000
	s_add_u32 s96, s70, 0x40000
	v_lshl_add_u64 v[216:217], s[70:71], 0, v[134:135]
	s_addc_u32 s97, s71, 0
	s_add_i32 vcc_lo, s84, s75
	global_load_lds_dwordx4 v[216:217], off
	v_lshl_add_u64 v[234:235], s[96:97], 0, v[130:131]
	s_mov_b32 m0, vcc_lo
	v_lshl_add_u64 v[236:237], s[72:73], 0, v[132:133]
	global_load_lds_dwordx4 v[234:235], off
	v_lshl_add_u64 v[234:235], s[96:97], 0, v[134:135]
	s_add_i32 m0, vcc_lo, 0x2000
	s_nop 0
	global_load_lds_dwordx4 v[234:235], off
	v_lshl_add_u64 v[234:235], s[72:73], 0, v[128:129]
	s_mov_b32 m0, s65
	s_nop 0
	global_load_lds_dwordx4 v[234:235], off
	s_mov_b32 m0, s67
	s_nop 0
	global_load_lds_dwordx4 v[236:237], off
	s_waitcnt vmcnt(8)
	s_waitcnt lgkmcnt(0)
	s_barrier
; #define PG8_STAGE(bufoff, gbase, voff) do { _Pragma("unroll") for (int _i = 0; _i < 2; ++_i) \
;         __builtin_amdgcn_global_load_lds((const unsigned*)((const char*)(gbase) + (voff)[_i]), (PG8_LAS unsigned*)(lds + (bufoff) + ldsw + _i * 8192), 16, 0, 0); } while (0)
; #define PG8_LDA(dst, b, h) do { _Pragma("unroll") for (int m = 0; m < 4; ++m) _Pragma("unroll") for (int k = 0; k < 2; ++k) dst[m][k] = *(const PG8_LAS bf16x8*)(lds + PG8_SA(b, h) + aoff + m * 2048 + k * 1024); } while (0)
; #define PG8_LDB(dst, b, h) do { _Pragma("unroll") for (int n = 0; n < 2; ++n) _Pragma("unroll") for (int k = 0; k < 2; ++k) dst[n][k] = *(const PG8_LAS bf16x8*)(lds + PG8_SB(b, h) + boff + n * 2048 + k * 1024); } while (0)
; #define PG8_MMA(ai, bj, At, Bt) do { __builtin_amdgcn_s_setprio(1); _Pragma("unroll") for (int m = 0; m < 4; ++m) _Pragma("unroll") for (int n = 0; n < 2; ++n) _Pragma("unroll") for (int k = 0; k < 2; ++k) \
;         acc[ai][bj][m][n] = __builtin_amdgcn_mfma_f32_16x16x32_bf16(Bt[n][k], At[m][k], acc[ai][bj][m][n], 0, 0, 0); __builtin_amdgcn_s_setprio(0); } while (0)
; #define PG8_WAIT_V(n) asm volatile("s_waitcnt vmcnt(" #n ")" ::: "memory")
; #define PG8_WAIT_L(n) asm volatile("s_waitcnt lgkmcnt(" #n ")" ::: "memory")
; #define PG8_BAR __builtin_amdgcn_s_barrier()
; #define PG8_SCHED __builtin_amdgcn_sched_barrier(0)
; template <class Epi, class Sched, bool ALIGN_EPI = false, bool SP2 = false>
; __device__ __forceinline__ void gemm_phase(PG8_LAS unsigned char* lds, const Gemm g, const Sched& S, const Epi& E, int tid_in) {
;     ...
;             PG8_WAIT_V(8); PG8_WAIT_L(0); PG8_BAR; PG8_MMA(1, 0, At, B0); PG8_MMA(1, 1, At, B1); PG8_BAR; PG8_SCHED;
;             PG8_LDB(B0, 1, 0); PG8_LDB(B1, 1, 1); PG8_SCHED; PG8_LDA(At, 1, 0); PG8_STAGE(PG8_SA(0, 1), a2 + hstep, voffA);
;             PG8_WAIT_V(8); PG8_WAIT_L(0); PG8_BAR; PG8_MMA(0, 0, At, B0); PG8_MMA(0, 1, At, B1); PG8_BAR; PG8_SCHED;
	s_setprio 1
	s_waitcnt lgkmcnt(0)
	v_mfma_f32_16x16x32_bf16 v[60:63], v[148:151], v[192:195], v[60:63]
	v_mfma_f32_16x16x32_bf16 v[56:59], v[156:159], v[192:195], v[56:59]
	v_mfma_f32_16x16x32_bf16 v[44:47], v[148:151], v[200:203], v[44:47]
	v_mfma_f32_16x16x32_bf16 v[40:43], v[156:159], v[200:203], v[40:43]
	v_mfma_f32_16x16x32_bf16 v[28:31], v[148:151], v[208:211], v[28:31]
	v_mfma_f32_16x16x32_bf16 v[24:27], v[156:159], v[208:211], v[24:27]
	v_mfma_f32_16x16x32_bf16 v[12:15], v[148:151], v[224:227], v[12:15]
	v_mfma_f32_16x16x32_bf16 v[8:11], v[156:159], v[224:227], v[8:11]
	v_mfma_f32_16x16x32_bf16 v[60:63], v[152:155], v[196:199], v[60:63]
	v_mfma_f32_16x16x32_bf16 v[56:59], v[160:163], v[196:199], v[56:59]
	v_mfma_f32_16x16x32_bf16 v[44:47], v[152:155], v[204:207], v[44:47]
	v_mfma_f32_16x16x32_bf16 v[40:43], v[160:163], v[204:207], v[40:43]
	v_mfma_f32_16x16x32_bf16 v[28:31], v[152:155], v[220:223], v[28:31]
	v_mfma_f32_16x16x32_bf16 v[24:27], v[160:163], v[220:223], v[24:27]
	v_mfma_f32_16x16x32_bf16 v[12:15], v[152:155], v[230:233], v[12:15]
	v_mfma_f32_16x16x32_bf16 v[8:11], v[160:163], v[230:233], v[8:11]
	v_mfma_f32_16x16x32_bf16 v[52:55], v[164:167], v[192:195], v[52:55]
	v_mfma_f32_16x16x32_bf16 v[48:51], v[184:187], v[192:195], v[48:51]
	v_mfma_f32_16x16x32_bf16 v[36:39], v[164:167], v[200:203], v[36:39]
	v_mfma_f32_16x16x32_bf16 v[32:35], v[184:187], v[200:203], v[32:35]
	v_mfma_f32_16x16x32_bf16 v[20:23], v[164:167], v[208:211], v[20:23]
	v_mfma_f32_16x16x32_bf16 v[16:19], v[184:187], v[208:211], v[16:19]
	v_mfma_f32_16x16x32_bf16 v[4:7], v[164:167], v[224:227], v[4:7]
	v_mfma_f32_16x16x32_bf16 v[0:3], v[184:187], v[224:227], v[0:3]
	v_mfma_f32_16x16x32_bf16 v[52:55], v[180:183], v[196:199], v[52:55]
	v_mfma_f32_16x16x32_bf16 v[48:51], v[188:191], v[196:199], v[48:51]
	v_mfma_f32_16x16x32_bf16 v[36:39], v[180:183], v[204:207], v[36:39]
	v_mfma_f32_16x16x32_bf16 v[32:35], v[188:191], v[204:207], v[32:35]
	v_mfma_f32_16x16x32_bf16 v[20:23], v[180:183], v[220:223], v[20:23]
	v_mfma_f32_16x16x32_bf16 v[16:19], v[188:191], v[220:223], v[16:19]
	v_mfma_f32_16x16x32_bf16 v[4:7], v[180:183], v[230:233], v[4:7]
	v_mfma_f32_16x16x32_bf16 v[0:3], v[188:191], v[230:233], v[0:3]
	s_setprio 0
	s_barrier
	s_add_i32 s96, 0, 0x18000
	s_add_i32 s97, 0, 0x1c000
	v_add_u32_e32 v160, s96, v172
	v_add_u32_e32 v168, s97, v172
	ds_read_b128 v[148:151], v160
	ds_read_b128 v[152:155], v160 offset:1024
	ds_read_b128 v[156:159], v160 offset:2048
	ds_read_b128 v[160:163], v160 offset:3072
	ds_read_b128 v[164:167], v168
	ds_read_b128 v[180:183], v168 offset:1024
	ds_read_b128 v[184:187], v168 offset:2048
	ds_read_b128 v[188:191], v168 offset:3072
	s_add_u32 s72, s72, 0x40000
	s_addc_u32 s73, s73, 0
	s_mov_b32 m0, s76
	v_lshl_add_u64 v[238:239], s[72:73], 0, v[128:129]
	ds_read_b128 v[192:195], v177 offset:32768
	ds_read_b128 v[196:199], v177 offset:33792
	ds_read_b128 v[200:203], v177 offset:34816
	ds_read_b128 v[204:207], v177 offset:35840
	ds_read_b128 v[208:211], v177 offset:36864
	ds_read_b128 v[220:223], v177 offset:37888
	ds_read_b128 v[224:227], v177 offset:38912
	ds_read_b128 v[230:233], v177 offset:39936
	global_load_lds_dwordx4 v[238:239], off
	v_lshl_add_u64 v[238:239], s[72:73], 0, v[132:133]
	s_mov_b32 m0, s77
	s_nop 0
	global_load_lds_dwordx4 v[238:239], off
	s_waitcnt vmcnt(8)
	s_waitcnt lgkmcnt(0)
	s_barrier
	s_setprio 1
	s_waitcnt lgkmcnt(0)
	v_mfma_f32_16x16x32_bf16 v[124:127], v[148:151], v[192:195], v[124:127]
	v_mfma_f32_16x16x32_bf16 v[120:123], v[156:159], v[192:195], v[120:123]
	v_mfma_f32_16x16x32_bf16 v[108:111], v[148:151], v[200:203], v[108:111]
	v_mfma_f32_16x16x32_bf16 v[104:107], v[156:159], v[200:203], v[104:107]
	v_mfma_f32_16x16x32_bf16 v[92:95], v[148:151], v[208:211], v[92:95]
	v_mfma_f32_16x16x32_bf16 v[88:91], v[156:159], v[208:211], v[88:91]
	v_mfma_f32_16x16x32_bf16 v[76:79], v[148:151], v[224:227], v[76:79]
	v_mfma_f32_16x16x32_bf16 v[72:75], v[156:159], v[224:227], v[72:75]
	v_mfma_f32_16x16x32_bf16 v[124:127], v[152:155], v[196:199], v[124:127]
	v_mfma_f32_16x16x32_bf16 v[120:123], v[160:163], v[196:199], v[120:123]
	v_mfma_f32_16x16x32_bf16 v[108:111], v[152:155], v[204:207], v[108:111]
	v_mfma_f32_16x16x32_bf16 v[104:107], v[160:163], v[204:207], v[104:107]
	v_mfma_f32_16x16x32_bf16 v[92:95], v[152:155], v[220:223], v[92:95]
	v_mfma_f32_16x16x32_bf16 v[88:91], v[160:163], v[220:223], v[88:91]
	v_mfma_f32_16x16x32_bf16 v[76:79], v[152:155], v[230:233], v[76:79]
	v_mfma_f32_16x16x32_bf16 v[72:75], v[160:163], v[230:233], v[72:75]
	v_mfma_f32_16x16x32_bf16 v[116:119], v[164:167], v[192:195], v[116:119]
	v_mfma_f32_16x16x32_bf16 v[112:115], v[184:187], v[192:195], v[112:115]
	v_mfma_f32_16x16x32_bf16 v[100:103], v[164:167], v[200:203], v[100:103]
	v_mfma_f32_16x16x32_bf16 v[96:99], v[184:187], v[200:203], v[96:99]
	v_mfma_f32_16x16x32_bf16 v[84:87], v[164:167], v[208:211], v[84:87]
	v_mfma_f32_16x16x32_bf16 v[80:83], v[184:187], v[208:211], v[80:83]
	v_mfma_f32_16x16x32_bf16 v[68:71], v[164:167], v[224:227], v[68:71]
	v_mfma_f32_16x16x32_bf16 v[64:67], v[184:187], v[224:227], v[64:67]
	v_mfma_f32_16x16x32_bf16 v[116:119], v[180:183], v[196:199], v[116:119]
	v_mfma_f32_16x16x32_bf16 v[112:115], v[188:191], v[196:199], v[112:115]
	v_mfma_f32_16x16x32_bf16 v[100:103], v[180:183], v[204:207], v[100:103]
	v_mfma_f32_16x16x32_bf16 v[96:99], v[188:191], v[204:207], v[96:99]
	v_mfma_f32_16x16x32_bf16 v[84:87], v[180:183], v[220:223], v[84:87]
	v_mfma_f32_16x16x32_bf16 v[80:83], v[188:191], v[220:223], v[80:83]
	v_mfma_f32_16x16x32_bf16 v[68:71], v[180:183], v[230:233], v[68:71]
	v_mfma_f32_16x16x32_bf16 v[64:67], v[188:191], v[230:233], v[64:67]
	s_setprio 0
	s_barrier
; #define PG8_STAGE(bufoff, gbase, voff) do { _Pragma("unroll") for (int _i = 0; _i < 2; ++_i) \
;         __builtin_amdgcn_global_load_lds((const unsigned*)((const char*)(gbase) + (voff)[_i]), (PG8_LAS unsigned*)(lds + (bufoff) + ldsw + _i * 8192), 16, 0, 0); } while (0)
; #define PG8_WAIT_V(n) asm volatile("s_waitcnt vmcnt(" #n ")" ::: "memory")
; #define PG8_WAIT_L(n) asm volatile("s_waitcnt lgkmcnt(" #n ")" ::: "memory")
; template <class Epi, class Sched, bool ALIGN_EPI = false, bool SP2 = false>
; __device__ __forceinline__ void gemm_phase(PG8_LAS unsigned char* lds, const Gemm g, const Sched& S, const Epi& E, int tid_in) {
;     ...
;             PG8_LDA(At, 1, 1); PG8_STAGE(PG8_SB(1, 0), b3, voffB); PG8_STAGE(PG8_SB(1, 1), b3 + hstep, voffB); PG8_STAGE(PG8_SA(1, 0), a3, voffA);
;             PG8_WAIT_V(8); PG8_WAIT_L(0); PG8_BAR; PG8_MMA(1, 0, At, B0); PG8_MMA(1, 1, At, B1); PG8_BAR; PG8_SCHED;
;             } else {
;             PG8_LDB(B0, 0, 0); PG8_SCHED; PG8_LDA(At, 0, 0); PG8_STAGE(PG8_SA(1, 1), a1 + hstep, voffA);
;             PG8_WAIT_L(8); PG8_BAR; PG8_WAIT_L(0); PG8_MMA(0, 0, At, B0); PG8_BAR; PG8_SCHED;
;             PG8_LDB(B1, 0, 1); PG8_STAGE(PG8_SB(0, 0), b2, voffB);
;             PG8_BAR; PG8_WAIT_L(0); PG8_MMA(0, 1, At, B1); PG8_BAR;
;             PG8_LDA(At, 0, 1); PG8_STAGE(PG8_SA(0, 0), a2, voffA);
;             PG8_BAR; PG8_WAIT_L(0); PG8_MMA(1, 0, At, B0); PG8_BAR; PG8_SCHED;
;             PG8_STAGE(PG8_SB(0, 1), b2 + hstep, voffB);
;             PG8_WAIT_V(6); PG8_BAR; PG8_MMA(1, 1, At, B1); PG8_BAR;
;             PG8_LDB(B0, 1, 0); PG8_SCHED; PG8_LDA(At, 1, 0); PG8_STAGE(PG8_SA(0, 1), a2 + hstep, voffA);
;             PG8_WAIT_L(8); PG8_BAR; PG8_WAIT_L(0); PG8_MMA(0, 0, At, B0); PG8_BAR; PG8_SCHED;
;             PG8_LDB(B1, 1, 1); PG8_STAGE(PG8_SB(1, 0), b3, voffB);
;             PG8_BAR; PG8_WAIT_L(0); PG8_MMA(0, 1, At, B1); PG8_BAR;
;             PG8_LDA(At, 1, 1); PG8_STAGE(PG8_SA(1, 0), a3, voffA);
;             PG8_BAR; PG8_WAIT_L(0); PG8_MMA(1, 0, At, B0); PG8_BAR; PG8_SCHED;
;             PG8_STAGE(PG8_SB(1, 1), b3 + hstep, voffB);
;             PG8_WAIT_V(6); PG8_BAR; PG8_MMA(1, 1, At, B1); PG8_BAR;
;             }
;         }
;         if constexpr (ALIGN_EPI) { if (wr == 0) PG8_BAR; }
;         if constexpr (!Epi::AFTER_DRAIN) { E(acc, cur, wr, wc, fr, fq); S.done(cur); }
;         if (!has_next) break;
	s_add_i32 s72, s96, s75
	v_lshl_add_u64 v[212:213], v[212:213], 0, s[22:23]
	s_mov_b32 m0, s72
	ds_read_b128 v[192:195], v177 offset:49152
	ds_read_b128 v[196:199], v177 offset:50176
	ds_read_b128 v[200:203], v177 offset:51200
	ds_read_b128 v[204:207], v177 offset:52224
	ds_read_b128 v[208:211], v177 offset:53248
	ds_read_b128 v[220:223], v177 offset:54272
	ds_read_b128 v[224:227], v177 offset:55296
	ds_read_b128 v[230:233], v177 offset:56320
	global_load_lds_dwordx4 v[212:213], off
	s_add_i32 m0, s72, 0x2000
	s_add_u32 s70, s70, 0x40080
	v_lshl_add_u64 v[212:213], v[216:217], 0, s[22:23]
	s_addc_u32 s71, s71, 0
	s_add_i32 s72, s97, s75
	global_load_lds_dwordx4 v[212:213], off
	v_lshl_add_u64 v[212:213], s[70:71], 0, v[130:131]
	s_mov_b32 m0, s72
	s_nop 0
	global_load_lds_dwordx4 v[212:213], off
	v_lshl_add_u64 v[212:213], s[70:71], 0, v[134:135]
	s_add_i32 m0, s72, 0x2000
	s_nop 0
	global_load_lds_dwordx4 v[212:213], off
	v_lshl_add_u64 v[212:213], v[234:235], 0, s[22:23]
	s_mov_b32 m0, s79
	s_nop 0
	global_load_lds_dwordx4 v[212:213], off
	v_lshl_add_u64 v[212:213], v[236:237], 0, s[22:23]
	s_mov_b32 m0, s80
	s_nop 0
	global_load_lds_dwordx4 v[212:213], off
	s_waitcnt vmcnt(8)
	s_waitcnt lgkmcnt(0)
	s_barrier
	s_setprio 1
	s_waitcnt lgkmcnt(0)
	v_mfma_f32_16x16x32_bf16 v[60:63], v[148:151], v[192:195], v[60:63]
	v_mfma_f32_16x16x32_bf16 v[56:59], v[156:159], v[192:195], v[56:59]
	v_mfma_f32_16x16x32_bf16 v[44:47], v[148:151], v[200:203], v[44:47]
	v_mfma_f32_16x16x32_bf16 v[40:43], v[156:159], v[200:203], v[40:43]
	v_mfma_f32_16x16x32_bf16 v[28:31], v[148:151], v[208:211], v[28:31]
	v_mfma_f32_16x16x32_bf16 v[24:27], v[156:159], v[208:211], v[24:27]
	v_mfma_f32_16x16x32_bf16 v[12:15], v[148:151], v[224:227], v[12:15]
	v_mfma_f32_16x16x32_bf16 v[8:11], v[156:159], v[224:227], v[8:11]
	v_mfma_f32_16x16x32_bf16 v[60:63], v[152:155], v[196:199], v[60:63]
	v_mfma_f32_16x16x32_bf16 v[56:59], v[160:163], v[196:199], v[56:59]
	v_mfma_f32_16x16x32_bf16 v[44:47], v[152:155], v[204:207], v[44:47]
	v_mfma_f32_16x16x32_bf16 v[40:43], v[160:163], v[204:207], v[40:43]
	v_mfma_f32_16x16x32_bf16 v[28:31], v[152:155], v[220:223], v[28:31]
	v_mfma_f32_16x16x32_bf16 v[24:27], v[160:163], v[220:223], v[24:27]
	v_mfma_f32_16x16x32_bf16 v[12:15], v[152:155], v[230:233], v[12:15]
	v_mfma_f32_16x16x32_bf16 v[8:11], v[160:163], v[230:233], v[8:11]
	v_mfma_f32_16x16x32_bf16 v[52:55], v[164:167], v[192:195], v[52:55]
	v_mfma_f32_16x16x32_bf16 v[48:51], v[184:187], v[192:195], v[48:51]
	v_mfma_f32_16x16x32_bf16 v[36:39], v[164:167], v[200:203], v[36:39]
	v_mfma_f32_16x16x32_bf16 v[32:35], v[184:187], v[200:203], v[32:35]
	v_mfma_f32_16x16x32_bf16 v[20:23], v[164:167], v[208:211], v[20:23]
	v_mfma_f32_16x16x32_bf16 v[16:19], v[184:187], v[208:211], v[16:19]
	v_mfma_f32_16x16x32_bf16 v[4:7], v[164:167], v[224:227], v[4:7]
	v_mfma_f32_16x16x32_bf16 v[0:3], v[184:187], v[224:227], v[0:3]
	v_mfma_f32_16x16x32_bf16 v[52:55], v[180:183], v[196:199], v[52:55]
	v_mfma_f32_16x16x32_bf16 v[48:51], v[188:191], v[196:199], v[48:51]
	v_mfma_f32_16x16x32_bf16 v[36:39], v[180:183], v[204:207], v[36:39]
	v_mfma_f32_16x16x32_bf16 v[32:35], v[188:191], v[204:207], v[32:35]
	v_mfma_f32_16x16x32_bf16 v[20:23], v[180:183], v[220:223], v[20:23]
	v_mfma_f32_16x16x32_bf16 v[16:19], v[188:191], v[220:223], v[16:19]
	v_mfma_f32_16x16x32_bf16 v[4:7], v[180:183], v[230:233], v[4:7]
	v_mfma_f32_16x16x32_bf16 v[0:3], v[188:191], v[230:233], v[0:3]
	s_setprio 0
	s_barrier
	s_add_i32 s95, s95, 2
	s_add_u32 s6, s6, 0x100
	s_addc_u32 s7, s7, 0
	s_add_u32 s93, s93, 0x100
	s_addc_u32 s94, s94, 0
	s_cmp_gt_u32 s95, 13
	s_cbranch_scc0 .LBB0_166
	s_and_b64 vcc, exec, s[24:25]
	s_cbranch_vccz .LBB0_169
	s_barrier

; #define PG8_STAGE(bufoff, gbase, voff) do { _Pragma("unroll") for (int _i = 0; _i < 2; ++_i) \
;         __builtin_amdgcn_global_load_lds((const unsigned*)((const char*)(gbase) + (voff)[_i]), (PG8_LAS unsigned*)(lds + (bufoff) + ldsw + _i * 8192), 16, 0, 0); } while (0)
; #define PG8_LDA(dst, b, h) do { _Pragma("unroll") for (int m = 0; m < 4; ++m) _Pragma("unroll") for (int k = 0; k < 2; ++k) dst[m][k] = *(const PG8_LAS bf16x8*)(lds + PG8_SA(b, h) + aoff + m * 2048 + k * 1024); } while (0)
; #define PG8_LDB(dst, b, h) do { _Pragma("unroll") for (int n = 0; n < 2; ++n) _Pragma("unroll") for (int k = 0; k < 2; ++k) dst[n][k] = *(const PG8_LAS bf16x8*)(lds + PG8_SB(b, h) + boff + n * 2048 + k * 1024); } while (0)
; #define PG8_MMA(ai, bj, At, Bt) do { __builtin_amdgcn_s_setprio(1); _Pragma("unroll") for (int m = 0; m < 4; ++m) _Pragma("unroll") for (int n = 0; n < 2; ++n) _Pragma("unroll") for (int k = 0; k < 2; ++k) \
;         acc[ai][bj][m][n] = __builtin_amdgcn_mfma_f32_16x16x32_bf16(Bt[n][k], At[m][k], acc[ai][bj][m][n], 0, 0, 0); __builtin_amdgcn_s_setprio(0); } while (0)
; #define PG8_WAIT_V(n) asm volatile("s_waitcnt vmcnt(" #n ")" ::: "memory")
; #define PG8_WAIT_L(n) asm volatile("s_waitcnt lgkmcnt(" #n ")" ::: "memory")
; #define PG8_BAR __builtin_amdgcn_s_barrier()
; #define PG8_SCHED __builtin_amdgcn_sched_barrier(0)
; template <class Epi, class Sched, bool ALIGN_EPI = false, bool SP2 = false>
; __device__ __forceinline__ void gemm_phase(PG8_LAS unsigned char* lds, const Gemm g, const Sched& S, const Epi& E, int tid_in) {
;     ...
;             const bool last = (t == nt - 2);
;             const char* a1 = cA + (size_t)(t + 1) * kstep;
;             const char* a2 = last ? nA : cA + (size_t)(t + 2) * kstep; const char* b2 = last ? nB : cB + (size_t)(t + 2) * kstep;
;             const char* a3 = a2 + kstep; const char* b3 = b2 + kstep;
;             if (last && has_next) S.a_ready(nxt);
;             if constexpr (SP2) {
;             PG8_LDB(B0, 0, 0); PG8_LDB(B1, 0, 1); PG8_SCHED; PG8_LDA(At, 0, 0); PG8_STAGE(PG8_SA(1, 1), a1 + hstep, voffA);
;             PG8_WAIT_V(8); PG8_WAIT_L(0); PG8_BAR; PG8_MMA(0, 0, At, B0); PG8_MMA(0, 1, At, B1); PG8_BAR; PG8_SCHED;
;             PG8_LDA(At, 0, 1); PG8_STAGE(PG8_SB(0, 0), b2, voffB); PG8_STAGE(PG8_SB(0, 1), b2 + hstep, voffB); PG8_STAGE(PG8_SA(0, 0), a2, voffA);
.LBB0_214:
	ds_read_b128 v[154:157], v151
	ds_read_b128 v[158:161], v151 offset:1024
	ds_read_b128 v[162:165], v151 offset:2048
	ds_read_b128 v[172:175], v151 offset:3072
	ds_read_b128 v[176:179], v152
	ds_read_b128 v[180:183], v152 offset:1024
	ds_read_b128 v[184:187], v152 offset:2048
	ds_read_b128 v[188:191], v152 offset:3072
	s_add_u32 s64, s62, 0xfffc0080
	s_addc_u32 s65, s63, -1
	s_cmp_eq_u32 s91, 12
	s_cselect_b32 s67, s43, s65
	s_cselect_b32 s66, s87, s64
	s_cselect_b32 s65, s41, s90
	s_cselect_b32 s64, s88, s89
	v_lshl_add_u64 v[146:147], s[62:63], 0, v[138:139]
	s_add_i32 m0, s61, 0xc000
	ds_read_b128 v[192:195], v153
	ds_read_b128 v[196:199], v153 offset:1024
	ds_read_b128 v[200:203], v153 offset:2048
	ds_read_b128 v[204:207], v153 offset:3072
	ds_read_b128 v[208:211], v153 offset:4096
	ds_read_b128 v[220:223], v153 offset:5120
	ds_read_b128 v[224:227], v153 offset:6144
	ds_read_b128 v[230:233], v153 offset:7168
	global_load_lds_dwordx4 v[146:147], off
	v_lshl_add_u64 v[146:147], s[62:63], 0, v[140:141]
	s_add_i32 m0, s61, 0xe000
	s_nop 0
	global_load_lds_dwordx4 v[146:147], off
	s_waitcnt vmcnt(8)
	s_waitcnt lgkmcnt(0)
	s_barrier
	s_setprio 1
	s_waitcnt lgkmcnt(0)
	v_mfma_f32_16x16x32_bf16 v[124:127], v[154:157], v[192:195], v[124:127]
	v_mfma_f32_16x16x32_bf16 v[120:123], v[162:165], v[192:195], v[120:123]
	v_mfma_f32_16x16x32_bf16 v[116:119], v[154:157], v[200:203], v[116:119]
	v_mfma_f32_16x16x32_bf16 v[108:111], v[162:165], v[200:203], v[108:111]
	v_mfma_f32_16x16x32_bf16 v[100:103], v[154:157], v[208:211], v[100:103]
	v_mfma_f32_16x16x32_bf16 v[92:95], v[162:165], v[208:211], v[92:95]
	v_mfma_f32_16x16x32_bf16 v[84:87], v[154:157], v[224:227], v[84:87]
	v_mfma_f32_16x16x32_bf16 v[76:79], v[162:165], v[224:227], v[76:79]
	v_mfma_f32_16x16x32_bf16 v[124:127], v[158:161], v[196:199], v[124:127]
	v_mfma_f32_16x16x32_bf16 v[120:123], v[172:175], v[196:199], v[120:123]
	v_mfma_f32_16x16x32_bf16 v[116:119], v[158:161], v[204:207], v[116:119]
	v_mfma_f32_16x16x32_bf16 v[108:111], v[172:175], v[204:207], v[108:111]
	v_mfma_f32_16x16x32_bf16 v[100:103], v[158:161], v[220:223], v[100:103]
	v_mfma_f32_16x16x32_bf16 v[92:95], v[172:175], v[220:223], v[92:95]
	v_mfma_f32_16x16x32_bf16 v[84:87], v[158:161], v[230:233], v[84:87]
	v_mfma_f32_16x16x32_bf16 v[76:79], v[172:175], v[230:233], v[76:79]
	v_mfma_f32_16x16x32_bf16 v[112:115], v[176:179], v[192:195], v[112:115]
	v_mfma_f32_16x16x32_bf16 v[104:107], v[184:187], v[192:195], v[104:107]
	v_mfma_f32_16x16x32_bf16 v[96:99], v[176:179], v[200:203], v[96:99]
	v_mfma_f32_16x16x32_bf16 v[88:91], v[184:187], v[200:203], v[88:91]
	v_mfma_f32_16x16x32_bf16 v[80:83], v[176:179], v[208:211], v[80:83]
	v_mfma_f32_16x16x32_bf16 v[72:75], v[184:187], v[208:211], v[72:75]
	v_mfma_f32_16x16x32_bf16 v[68:71], v[176:179], v[224:227], v[68:71]
	v_mfma_f32_16x16x32_bf16 v[64:67], v[184:187], v[224:227], v[64:67]
	v_mfma_f32_16x16x32_bf16 v[112:115], v[180:183], v[196:199], v[112:115]
	v_mfma_f32_16x16x32_bf16 v[104:107], v[188:191], v[196:199], v[104:107]
	v_mfma_f32_16x16x32_bf16 v[96:99], v[180:183], v[204:207], v[96:99]
	v_mfma_f32_16x16x32_bf16 v[88:91], v[188:191], v[204:207], v[88:91]
	v_mfma_f32_16x16x32_bf16 v[80:83], v[180:183], v[220:223], v[80:83]
	v_mfma_f32_16x16x32_bf16 v[72:75], v[188:191], v[220:223], v[72:75]
	v_mfma_f32_16x16x32_bf16 v[68:71], v[180:183], v[230:233], v[68:71]
	v_mfma_f32_16x16x32_bf16 v[64:67], v[188:191], v[230:233], v[64:67]
	s_setprio 0
	s_barrier
	s_add_i32 s92, s80, s72
	v_lshl_add_u64 v[146:147], s[64:65], 0, v[130:131]
	s_mov_b32 m0, s92
	ds_read_b128 v[192:195], v153 offset:16384
	ds_read_b128 v[196:199], v153 offset:17408
	ds_read_b128 v[200:203], v153 offset:18432
	ds_read_b128 v[204:207], v153 offset:19456
	ds_read_b128 v[208:211], v153 offset:20480
	ds_read_b128 v[220:223], v153 offset:21504
	ds_read_b128 v[224:227], v153 offset:22528
	ds_read_b128 v[230:233], v153 offset:23552
	global_load_lds_dwordx4 v[146:147], off
	s_add_i32 m0, s92, 0x2000
	s_add_u32 s92, s64, 0x40000
	v_lshl_add_u64 v[166:167], s[64:65], 0, v[134:135]
	s_addc_u32 s93, s65, 0
	s_add_i32 s94, s81, s72
	global_load_lds_dwordx4 v[166:167], off
	v_lshl_add_u64 v[212:213], s[92:93], 0, v[130:131]
	s_mov_b32 m0, s94
	v_lshl_add_u64 v[216:217], s[66:67], 0, v[132:133]
	global_load_lds_dwordx4 v[212:213], off
	v_lshl_add_u64 v[212:213], s[92:93], 0, v[134:135]
	s_add_i32 m0, s94, 0x2000
	s_nop 0
	global_load_lds_dwordx4 v[212:213], off
	v_lshl_add_u64 v[212:213], s[66:67], 0, v[128:129]
	s_mov_b32 m0, s61
	s_nop 0
	global_load_lds_dwordx4 v[212:213], off
	s_mov_b32 m0, s73
	s_nop 0
	global_load_lds_dwordx4 v[216:217], off
	s_waitcnt vmcnt(8)
	s_waitcnt lgkmcnt(0)
	s_barrier
; #define PG8_STAGE(bufoff, gbase, voff) do { _Pragma("unroll") for (int _i = 0; _i < 2; ++_i) \
;         __builtin_amdgcn_global_load_lds((const unsigned*)((const char*)(gbase) + (voff)[_i]), (PG8_LAS unsigned*)(lds + (bufoff) + ldsw + _i * 8192), 16, 0, 0); } while (0)
; #define PG8_LDA(dst, b, h) do { _Pragma("unroll") for (int m = 0; m < 4; ++m) _Pragma("unroll") for (int k = 0; k < 2; ++k) dst[m][k] = *(const PG8_LAS bf16x8*)(lds + PG8_SA(b, h) + aoff + m * 2048 + k * 1024); } while (0)
; #define PG8_LDB(dst, b, h) do { _Pragma("unroll") for (int n = 0; n < 2; ++n) _Pragma("unroll") for (int k = 0; k < 2; ++k) dst[n][k] = *(const PG8_LAS bf16x8*)(lds + PG8_SB(b, h) + boff + n * 2048 + k * 1024); } while (0)
; #define PG8_MMA(ai, bj, At, Bt) do { __builtin_amdgcn_s_setprio(1); _Pragma("unroll") for (int m = 0; m < 4; ++m) _Pragma("unroll") for (int n = 0; n < 2; ++n) _Pragma("unroll") for (int k = 0; k < 2; ++k) \
;         acc[ai][bj][m][n] = __builtin_amdgcn_mfma_f32_16x16x32_bf16(Bt[n][k], At[m][k], acc[ai][bj][m][n], 0, 0, 0); __builtin_amdgcn_s_setprio(0); } while (0)
; #define PG8_WAIT_V(n) asm volatile("s_waitcnt vmcnt(" #n ")" ::: "memory")
; #define PG8_WAIT_L(n) asm volatile("s_waitcnt lgkmcnt(" #n ")" ::: "memory")
; #define PG8_BAR __builtin_amdgcn_s_barrier()
; #define PG8_SCHED __builtin_amdgcn_sched_barrier(0)
; template <class Epi, class Sched, bool ALIGN_EPI = false, bool SP2 = false>
; __device__ __forceinline__ void gemm_phase(PG8_LAS unsigned char* lds, const Gemm g, const Sched& S, const Epi& E, int tid_in) {
;     ...
;             PG8_WAIT_V(8); PG8_WAIT_L(0); PG8_BAR; PG8_MMA(1, 0, At, B0); PG8_MMA(1, 1, At, B1); PG8_BAR; PG8_SCHED;
;             PG8_LDB(B0, 1, 0); PG8_LDB(B1, 1, 1); PG8_SCHED; PG8_LDA(At, 1, 0); PG8_STAGE(PG8_SA(0, 1), a2 + hstep, voffA);
;             PG8_WAIT_V(8); PG8_WAIT_L(0); PG8_BAR; PG8_MMA(0, 0, At, B0); PG8_MMA(0, 1, At, B1); PG8_BAR; PG8_SCHED;
	s_setprio 1
	s_waitcnt lgkmcnt(0)
	v_mfma_f32_16x16x32_bf16 v[60:63], v[154:157], v[192:195], v[60:63]
	v_mfma_f32_16x16x32_bf16 v[56:59], v[162:165], v[192:195], v[56:59]
	v_mfma_f32_16x16x32_bf16 v[52:55], v[154:157], v[200:203], v[52:55]
	v_mfma_f32_16x16x32_bf16 v[44:47], v[162:165], v[200:203], v[44:47]
	v_mfma_f32_16x16x32_bf16 v[36:39], v[154:157], v[208:211], v[36:39]
	v_mfma_f32_16x16x32_bf16 v[28:31], v[162:165], v[208:211], v[28:31]
	v_mfma_f32_16x16x32_bf16 v[20:23], v[154:157], v[224:227], v[20:23]
	v_mfma_f32_16x16x32_bf16 v[12:15], v[162:165], v[224:227], v[12:15]
	v_mfma_f32_16x16x32_bf16 v[60:63], v[158:161], v[196:199], v[60:63]
	v_mfma_f32_16x16x32_bf16 v[56:59], v[172:175], v[196:199], v[56:59]
	v_mfma_f32_16x16x32_bf16 v[52:55], v[158:161], v[204:207], v[52:55]
	v_mfma_f32_16x16x32_bf16 v[44:47], v[172:175], v[204:207], v[44:47]
	v_mfma_f32_16x16x32_bf16 v[36:39], v[158:161], v[220:223], v[36:39]
	v_mfma_f32_16x16x32_bf16 v[28:31], v[172:175], v[220:223], v[28:31]
	v_mfma_f32_16x16x32_bf16 v[20:23], v[158:161], v[230:233], v[20:23]
	v_mfma_f32_16x16x32_bf16 v[12:15], v[172:175], v[230:233], v[12:15]
	v_mfma_f32_16x16x32_bf16 v[48:51], v[176:179], v[192:195], v[48:51]
	v_mfma_f32_16x16x32_bf16 v[40:43], v[184:187], v[192:195], v[40:43]
	v_mfma_f32_16x16x32_bf16 v[32:35], v[176:179], v[200:203], v[32:35]
	v_mfma_f32_16x16x32_bf16 v[24:27], v[184:187], v[200:203], v[24:27]
	v_mfma_f32_16x16x32_bf16 v[16:19], v[176:179], v[208:211], v[16:19]
	v_mfma_f32_16x16x32_bf16 v[8:11], v[184:187], v[208:211], v[8:11]
	v_mfma_f32_16x16x32_bf16 v[4:7], v[176:179], v[224:227], v[4:7]
	v_mfma_f32_16x16x32_bf16 v[0:3], v[184:187], v[224:227], v[0:3]
	v_mfma_f32_16x16x32_bf16 v[48:51], v[180:183], v[196:199], v[48:51]
	v_mfma_f32_16x16x32_bf16 v[40:43], v[188:191], v[196:199], v[40:43]
	v_mfma_f32_16x16x32_bf16 v[32:35], v[180:183], v[204:207], v[32:35]
	v_mfma_f32_16x16x32_bf16 v[24:27], v[188:191], v[204:207], v[24:27]
	v_mfma_f32_16x16x32_bf16 v[16:19], v[180:183], v[220:223], v[16:19]
	v_mfma_f32_16x16x32_bf16 v[8:11], v[188:191], v[220:223], v[8:11]
	v_mfma_f32_16x16x32_bf16 v[4:7], v[180:183], v[230:233], v[4:7]
	v_mfma_f32_16x16x32_bf16 v[0:3], v[188:191], v[230:233], v[0:3]
	s_setprio 0
	s_barrier
	s_add_i32 s92, 0, 0x18000
	v_add_u32_e32 v136, s92, v149
	s_add_i32 s93, 0, 0x1c000
	ds_read_b128 v[154:157], v136
	ds_read_b128 v[158:161], v136 offset:1024
	ds_read_b128 v[162:165], v136 offset:2048
	ds_read_b128 v[172:175], v136 offset:3072
	v_add_u32_e32 v136, s93, v149
	ds_read_b128 v[176:179], v136
	ds_read_b128 v[180:183], v136 offset:1024
	ds_read_b128 v[184:187], v136 offset:2048
	ds_read_b128 v[188:191], v136 offset:3072
	s_add_u32 s66, s66, 0x40000
	s_addc_u32 s67, s67, 0
	s_mov_b32 m0, s74
	v_lshl_add_u64 v[234:235], s[66:67], 0, v[128:129]
	ds_read_b128 v[192:195], v153 offset:32768
	ds_read_b128 v[196:199], v153 offset:33792
	ds_read_b128 v[200:203], v153 offset:34816
	ds_read_b128 v[204:207], v153 offset:35840
	ds_read_b128 v[208:211], v153 offset:36864
	ds_read_b128 v[220:223], v153 offset:37888
	ds_read_b128 v[224:227], v153 offset:38912
	ds_read_b128 v[230:233], v153 offset:39936
	global_load_lds_dwordx4 v[234:235], off
	v_lshl_add_u64 v[234:235], s[66:67], 0, v[132:133]
	s_mov_b32 m0, s75
	s_nop 0
	global_load_lds_dwordx4 v[234:235], off
	s_waitcnt vmcnt(8)
	s_waitcnt lgkmcnt(0)
	s_barrier
	s_setprio 1
	s_waitcnt lgkmcnt(0)
	v_mfma_f32_16x16x32_bf16 v[124:127], v[154:157], v[192:195], v[124:127]
	v_mfma_f32_16x16x32_bf16 v[120:123], v[162:165], v[192:195], v[120:123]
	v_mfma_f32_16x16x32_bf16 v[116:119], v[154:157], v[200:203], v[116:119]
	v_mfma_f32_16x16x32_bf16 v[108:111], v[162:165], v[200:203], v[108:111]
	v_mfma_f32_16x16x32_bf16 v[100:103], v[154:157], v[208:211], v[100:103]
	v_mfma_f32_16x16x32_bf16 v[92:95], v[162:165], v[208:211], v[92:95]
	v_mfma_f32_16x16x32_bf16 v[84:87], v[154:157], v[224:227], v[84:87]
	v_mfma_f32_16x16x32_bf16 v[76:79], v[162:165], v[224:227], v[76:79]
	v_mfma_f32_16x16x32_bf16 v[124:127], v[158:161], v[196:199], v[124:127]
	v_mfma_f32_16x16x32_bf16 v[120:123], v[172:175], v[196:199], v[120:123]
	v_mfma_f32_16x16x32_bf16 v[116:119], v[158:161], v[204:207], v[116:119]
	v_mfma_f32_16x16x32_bf16 v[108:111], v[172:175], v[204:207], v[108:111]
	v_mfma_f32_16x16x32_bf16 v[100:103], v[158:161], v[220:223], v[100:103]
	v_mfma_f32_16x16x32_bf16 v[92:95], v[172:175], v[220:223], v[92:95]
	v_mfma_f32_16x16x32_bf16 v[84:87], v[158:161], v[230:233], v[84:87]
	v_mfma_f32_16x16x32_bf16 v[76:79], v[172:175], v[230:233], v[76:79]
	v_mfma_f32_16x16x32_bf16 v[112:115], v[176:179], v[192:195], v[112:115]
	v_mfma_f32_16x16x32_bf16 v[104:107], v[184:187], v[192:195], v[104:107]
	v_mfma_f32_16x16x32_bf16 v[96:99], v[176:179], v[200:203], v[96:99]
	v_mfma_f32_16x16x32_bf16 v[88:91], v[184:187], v[200:203], v[88:91]
	v_mfma_f32_16x16x32_bf16 v[80:83], v[176:179], v[208:211], v[80:83]
	v_mfma_f32_16x16x32_bf16 v[72:75], v[184:187], v[208:211], v[72:75]
	v_mfma_f32_16x16x32_bf16 v[68:71], v[176:179], v[224:227], v[68:71]
	v_mfma_f32_16x16x32_bf16 v[64:67], v[184:187], v[224:227], v[64:67]
	v_mfma_f32_16x16x32_bf16 v[112:115], v[180:183], v[196:199], v[112:115]
	v_mfma_f32_16x16x32_bf16 v[104:107], v[188:191], v[196:199], v[104:107]
	v_mfma_f32_16x16x32_bf16 v[96:99], v[180:183], v[204:207], v[96:99]
	v_mfma_f32_16x16x32_bf16 v[88:91], v[188:191], v[204:207], v[88:91]
	v_mfma_f32_16x16x32_bf16 v[80:83], v[180:183], v[220:223], v[80:83]
	v_mfma_f32_16x16x32_bf16 v[72:75], v[188:191], v[220:223], v[72:75]
	v_mfma_f32_16x16x32_bf16 v[68:71], v[180:183], v[230:233], v[68:71]
	v_mfma_f32_16x16x32_bf16 v[64:67], v[188:191], v[230:233], v[64:67]
	s_setprio 0
	s_barrier
; #define PG8_STAGE(bufoff, gbase, voff) do { _Pragma("unroll") for (int _i = 0; _i < 2; ++_i) \
;         __builtin_amdgcn_global_load_lds((const unsigned*)((const char*)(gbase) + (voff)[_i]), (PG8_LAS unsigned*)(lds + (bufoff) + ldsw + _i * 8192), 16, 0, 0); } while (0)
; #define PG8_LDA(dst, b, h) do { _Pragma("unroll") for (int m = 0; m < 4; ++m) _Pragma("unroll") for (int k = 0; k < 2; ++k) dst[m][k] = *(const PG8_LAS bf16x8*)(lds + PG8_SA(b, h) + aoff + m * 2048 + k * 1024); } while (0)
; #define PG8_MMA(ai, bj, At, Bt) do { __builtin_amdgcn_s_setprio(1); _Pragma("unroll") for (int m = 0; m < 4; ++m) _Pragma("unroll") for (int n = 0; n < 2; ++n) _Pragma("unroll") for (int k = 0; k < 2; ++k) \
;         acc[ai][bj][m][n] = __builtin_amdgcn_mfma_f32_16x16x32_bf16(Bt[n][k], At[m][k], acc[ai][bj][m][n], 0, 0, 0); __builtin_amdgcn_s_setprio(0); } while (0)
; #define PG8_WAIT_V(n) asm volatile("s_waitcnt vmcnt(" #n ")" ::: "memory")
; #define PG8_WAIT_L(n) asm volatile("s_waitcnt lgkmcnt(" #n ")" ::: "memory")
; #define PG8_BAR __builtin_amdgcn_s_barrier()
; #define PG8_SCHED __builtin_amdgcn_sched_barrier(0)
; template <class Epi, class Sched, bool ALIGN_EPI = false, bool SP2 = false>
; __device__ __forceinline__ void gemm_phase(PG8_LAS unsigned char* lds, const Gemm g, const Sched& S, const Epi& E, int tid_in) {
;     ...
;             PG8_LDA(At, 1, 1); PG8_STAGE(PG8_SB(1, 0), b3, voffB); PG8_STAGE(PG8_SB(1, 1), b3 + hstep, voffB); PG8_STAGE(PG8_SA(1, 0), a3, voffA);
;             PG8_WAIT_V(8); PG8_WAIT_L(0); PG8_BAR; PG8_MMA(1, 0, At, B0); PG8_MMA(1, 1, At, B1); PG8_BAR; PG8_SCHED;
;     ...
;         if constexpr (ALIGN_EPI) { if (wr == 0) PG8_BAR; }
	s_add_i32 s66, s92, s72
	v_lshl_add_u64 v[146:147], v[146:147], 0, s[10:11]
	s_mov_b32 m0, s66
	ds_read_b128 v[192:195], v153 offset:49152
	ds_read_b128 v[196:199], v153 offset:50176
	ds_read_b128 v[200:203], v153 offset:51200
	ds_read_b128 v[204:207], v153 offset:52224
	ds_read_b128 v[208:211], v153 offset:53248
	ds_read_b128 v[220:223], v153 offset:54272
	ds_read_b128 v[224:227], v153 offset:55296
	ds_read_b128 v[230:233], v153 offset:56320
	global_load_lds_dwordx4 v[146:147], off
	s_add_i32 m0, s66, 0x2000
	s_add_u32 s64, s64, 0x40080
	v_lshl_add_u64 v[146:147], v[166:167], 0, s[10:11]
	s_addc_u32 s65, s65, 0
	s_add_i32 s66, s93, s72
	global_load_lds_dwordx4 v[146:147], off
	v_lshl_add_u64 v[146:147], s[64:65], 0, v[130:131]
	s_mov_b32 m0, s66
	s_nop 0
	global_load_lds_dwordx4 v[146:147], off
	v_lshl_add_u64 v[146:147], s[64:65], 0, v[134:135]
	s_add_i32 m0, s66, 0x2000
	s_nop 0
	global_load_lds_dwordx4 v[146:147], off
	v_lshl_add_u64 v[146:147], v[212:213], 0, s[10:11]
	s_mov_b32 m0, s77
	s_nop 0
	global_load_lds_dwordx4 v[146:147], off
	v_lshl_add_u64 v[146:147], v[216:217], 0, s[10:11]
	s_mov_b32 m0, s78
	s_nop 0
	global_load_lds_dwordx4 v[146:147], off
	s_waitcnt vmcnt(8)
	s_waitcnt lgkmcnt(0)
	s_barrier
	s_setprio 1
	s_waitcnt lgkmcnt(0)
	v_mfma_f32_16x16x32_bf16 v[60:63], v[154:157], v[192:195], v[60:63]
	v_mfma_f32_16x16x32_bf16 v[56:59], v[162:165], v[192:195], v[56:59]
	v_mfma_f32_16x16x32_bf16 v[52:55], v[154:157], v[200:203], v[52:55]
	v_mfma_f32_16x16x32_bf16 v[44:47], v[162:165], v[200:203], v[44:47]
	v_mfma_f32_16x16x32_bf16 v[36:39], v[154:157], v[208:211], v[36:39]
	v_mfma_f32_16x16x32_bf16 v[28:31], v[162:165], v[208:211], v[28:31]
	v_mfma_f32_16x16x32_bf16 v[20:23], v[154:157], v[224:227], v[20:23]
	v_mfma_f32_16x16x32_bf16 v[12:15], v[162:165], v[224:227], v[12:15]
	v_mfma_f32_16x16x32_bf16 v[60:63], v[158:161], v[196:199], v[60:63]
	v_mfma_f32_16x16x32_bf16 v[56:59], v[172:175], v[196:199], v[56:59]
	v_mfma_f32_16x16x32_bf16 v[52:55], v[158:161], v[204:207], v[52:55]
	v_mfma_f32_16x16x32_bf16 v[44:47], v[172:175], v[204:207], v[44:47]
	v_mfma_f32_16x16x32_bf16 v[36:39], v[158:161], v[220:223], v[36:39]
	v_mfma_f32_16x16x32_bf16 v[28:31], v[172:175], v[220:223], v[28:31]
	v_mfma_f32_16x16x32_bf16 v[20:23], v[158:161], v[230:233], v[20:23]
	v_mfma_f32_16x16x32_bf16 v[12:15], v[172:175], v[230:233], v[12:15]
	v_mfma_f32_16x16x32_bf16 v[48:51], v[176:179], v[192:195], v[48:51]
	v_mfma_f32_16x16x32_bf16 v[40:43], v[184:187], v[192:195], v[40:43]
	v_mfma_f32_16x16x32_bf16 v[32:35], v[176:179], v[200:203], v[32:35]
	v_mfma_f32_16x16x32_bf16 v[24:27], v[184:187], v[200:203], v[24:27]
	v_mfma_f32_16x16x32_bf16 v[16:19], v[176:179], v[208:211], v[16:19]
	v_mfma_f32_16x16x32_bf16 v[8:11], v[184:187], v[208:211], v[8:11]
	v_mfma_f32_16x16x32_bf16 v[4:7], v[176:179], v[224:227], v[4:7]
	v_mfma_f32_16x16x32_bf16 v[0:3], v[184:187], v[224:227], v[0:3]
	v_mfma_f32_16x16x32_bf16 v[48:51], v[180:183], v[196:199], v[48:51]
	v_mfma_f32_16x16x32_bf16 v[40:43], v[188:191], v[196:199], v[40:43]
	v_mfma_f32_16x16x32_bf16 v[32:35], v[180:183], v[204:207], v[32:35]
	v_mfma_f32_16x16x32_bf16 v[24:27], v[188:191], v[204:207], v[24:27]
	v_mfma_f32_16x16x32_bf16 v[16:19], v[180:183], v[220:223], v[16:19]
	v_mfma_f32_16x16x32_bf16 v[8:11], v[188:191], v[220:223], v[8:11]
	v_mfma_f32_16x16x32_bf16 v[4:7], v[180:183], v[230:233], v[4:7]
	v_mfma_f32_16x16x32_bf16 v[0:3], v[188:191], v[230:233], v[0:3]
	s_setprio 0
	s_barrier
	s_add_i32 s91, s91, 2
	s_add_u32 s62, s62, 0x100
	s_addc_u32 s63, s63, 0
	s_add_u32 s89, s89, 0x100
	s_addc_u32 s90, s90, 0
	s_cmp_gt_u32 s91, 13
	s_cbranch_scc0 .LBB0_214
	s_and_b64 vcc, exec, s[18:19]
	s_cbranch_vccz .LBB0_217
	s_barrier

; #define PG8_STAGE(bufoff, gbase, voff) do { _Pragma("unroll") for (int _i = 0; _i < 2; ++_i) \
;         __builtin_amdgcn_global_load_lds((const unsigned*)((const char*)(gbase) + (voff)[_i]), (PG8_LAS unsigned*)(lds + (bufoff) + ldsw + _i * 8192), 16, 0, 0); } while (0)
; #define PG8_LDA(dst, b, h) do { _Pragma("unroll") for (int m = 0; m < 4; ++m) _Pragma("unroll") for (int k = 0; k < 2; ++k) dst[m][k] = *(const PG8_LAS bf16x8*)(lds + PG8_SA(b, h) + aoff + m * 2048 + k * 1024); } while (0)
; #define PG8_LDB(dst, b, h) do { _Pragma("unroll") for (int n = 0; n < 2; ++n) _Pragma("unroll") for (int k = 0; k < 2; ++k) dst[n][k] = *(const PG8_LAS bf16x8*)(lds + PG8_SB(b, h) + boff + n * 2048 + k * 1024); } while (0)
; #define PG8_MMA(ai, bj, At, Bt) do { __builtin_amdgcn_s_setprio(1); _Pragma("unroll") for (int m = 0; m < 4; ++m) _Pragma("unroll") for (int n = 0; n < 2; ++n) _Pragma("unroll") for (int k = 0; k < 2; ++k) \
;         acc[ai][bj][m][n] = __builtin_amdgcn_mfma_f32_16x16x32_bf16(Bt[n][k], At[m][k], acc[ai][bj][m][n], 0, 0, 0); __builtin_amdgcn_s_setprio(0); } while (0)
; #define PG8_WAIT_V(n) asm volatile("s_waitcnt vmcnt(" #n ")" ::: "memory")
; #define PG8_WAIT_L(n) asm volatile("s_waitcnt lgkmcnt(" #n ")" ::: "memory")
; #define PG8_BAR __builtin_amdgcn_s_barrier()
; #define PG8_SCHED __builtin_amdgcn_sched_barrier(0)
; template <class Epi, class Sched, bool ALIGN_EPI = false, bool SP2 = false>
; __device__ __forceinline__ void gemm_phase(PG8_LAS unsigned char* lds, const Gemm g, const Sched& S, const Epi& E, int tid_in) {
;     ...
;             const bool last = (t == nt - 2);
;             const char* a1 = cA + (size_t)(t + 1) * kstep;
;             const char* a2 = last ? nA : cA + (size_t)(t + 2) * kstep; const char* b2 = last ? nB : cB + (size_t)(t + 2) * kstep;
;             const char* a3 = a2 + kstep; const char* b3 = b2 + kstep;
;             if (last && has_next) S.a_ready(nxt);
;             if constexpr (SP2) {
;             PG8_LDB(B0, 0, 0); PG8_LDB(B1, 0, 1); PG8_SCHED; PG8_LDA(At, 0, 0); PG8_STAGE(PG8_SA(1, 1), a1 + hstep, voffA);
;             PG8_WAIT_V(8); PG8_WAIT_L(0); PG8_BAR; PG8_MMA(0, 0, At, B0); PG8_MMA(0, 1, At, B1); PG8_BAR; PG8_SCHED;
;             PG8_LDA(At, 0, 1); PG8_STAGE(PG8_SB(0, 0), b2, voffB); PG8_STAGE(PG8_SB(0, 1), b2 + hstep, voffB); PG8_STAGE(PG8_SA(0, 0), a2, voffA);
.LBB0_302:
	ds_read_b128 v[146:149], v154
	ds_read_b128 v[158:161], v154 offset:1024
	ds_read_b128 v[162:165], v154 offset:2048
	ds_read_b128 v[166:169], v154 offset:3072
	ds_read_b128 v[170:173], v155
	ds_read_b128 v[174:177], v155 offset:1024
	ds_read_b128 v[178:181], v155 offset:2048
	ds_read_b128 v[182:185], v155 offset:3072
	s_add_u32 s62, s60, 0xfff80080
	s_addc_u32 s63, s61, -1
	s_cmp_eq_u32 s85, 28
	s_cselect_b32 s65, s43, s63
	s_cselect_b32 s64, s57, s62
	s_cselect_b32 s63, s41, s84
	s_cselect_b32 s62, s82, s83
	v_lshl_add_u64 v[222:223], s[60:61], 0, v[138:139]
	s_add_i32 m0, s59, 0xc000
	ds_read_b128 v[186:189], v156
	ds_read_b128 v[190:193], v156 offset:1024
	ds_read_b128 v[194:197], v156 offset:2048
	ds_read_b128 v[198:201], v156 offset:3072
	ds_read_b128 v[202:205], v156 offset:4096
	ds_read_b128 v[206:209], v156 offset:5120
	ds_read_b128 v[210:213], v156 offset:6144
	ds_read_b128 v[218:221], v156 offset:7168
	global_load_lds_dwordx4 v[222:223], off
	v_lshl_add_u64 v[222:223], s[60:61], 0, v[140:141]
	s_add_i32 m0, s59, 0xe000
	s_nop 0
	global_load_lds_dwordx4 v[222:223], off
	s_waitcnt vmcnt(8)
	s_waitcnt lgkmcnt(0)
	s_barrier
	s_setprio 1
	s_waitcnt lgkmcnt(0)
	v_mfma_f32_16x16x32_bf16 v[124:127], v[146:149], v[186:189], v[124:127]
	v_mfma_f32_16x16x32_bf16 v[120:123], v[162:165], v[186:189], v[120:123]
	v_mfma_f32_16x16x32_bf16 v[108:111], v[146:149], v[194:197], v[108:111]
	v_mfma_f32_16x16x32_bf16 v[104:107], v[162:165], v[194:197], v[104:107]
	v_mfma_f32_16x16x32_bf16 v[92:95], v[146:149], v[202:205], v[92:95]
	v_mfma_f32_16x16x32_bf16 v[88:91], v[162:165], v[202:205], v[88:91]
	v_mfma_f32_16x16x32_bf16 v[76:79], v[146:149], v[210:213], v[76:79]
	v_mfma_f32_16x16x32_bf16 v[72:75], v[162:165], v[210:213], v[72:75]
	v_mfma_f32_16x16x32_bf16 v[124:127], v[158:161], v[190:193], v[124:127]
	v_mfma_f32_16x16x32_bf16 v[120:123], v[166:169], v[190:193], v[120:123]
	v_mfma_f32_16x16x32_bf16 v[108:111], v[158:161], v[198:201], v[108:111]
	v_mfma_f32_16x16x32_bf16 v[104:107], v[166:169], v[198:201], v[104:107]
	v_mfma_f32_16x16x32_bf16 v[92:95], v[158:161], v[206:209], v[92:95]
	v_mfma_f32_16x16x32_bf16 v[88:91], v[166:169], v[206:209], v[88:91]
	v_mfma_f32_16x16x32_bf16 v[76:79], v[158:161], v[218:221], v[76:79]
	v_mfma_f32_16x16x32_bf16 v[72:75], v[166:169], v[218:221], v[72:75]
	v_mfma_f32_16x16x32_bf16 v[116:119], v[170:173], v[186:189], v[116:119]
	v_mfma_f32_16x16x32_bf16 v[112:115], v[178:181], v[186:189], v[112:115]
	v_mfma_f32_16x16x32_bf16 v[100:103], v[170:173], v[194:197], v[100:103]
	v_mfma_f32_16x16x32_bf16 v[96:99], v[178:181], v[194:197], v[96:99]
	v_mfma_f32_16x16x32_bf16 v[84:87], v[170:173], v[202:205], v[84:87]
	v_mfma_f32_16x16x32_bf16 v[80:83], v[178:181], v[202:205], v[80:83]
	v_mfma_f32_16x16x32_bf16 v[68:71], v[170:173], v[210:213], v[68:71]
	v_mfma_f32_16x16x32_bf16 v[64:67], v[178:181], v[210:213], v[64:67]
	v_mfma_f32_16x16x32_bf16 v[116:119], v[174:177], v[190:193], v[116:119]
	v_mfma_f32_16x16x32_bf16 v[112:115], v[182:185], v[190:193], v[112:115]
	v_mfma_f32_16x16x32_bf16 v[100:103], v[174:177], v[198:201], v[100:103]
	v_mfma_f32_16x16x32_bf16 v[96:99], v[182:185], v[198:201], v[96:99]
	v_mfma_f32_16x16x32_bf16 v[84:87], v[174:177], v[206:209], v[84:87]
	v_mfma_f32_16x16x32_bf16 v[80:83], v[182:185], v[206:209], v[80:83]
	v_mfma_f32_16x16x32_bf16 v[68:71], v[174:177], v[218:221], v[68:71]
	v_mfma_f32_16x16x32_bf16 v[64:67], v[182:185], v[218:221], v[64:67]
	s_setprio 0
	s_barrier
	s_add_i32 s86, s80, s71
	v_lshl_add_u64 v[222:223], s[62:63], 0, v[130:131]
	s_mov_b32 m0, s86
	ds_read_b128 v[186:189], v156 offset:16384
	ds_read_b128 v[190:193], v156 offset:17408
	ds_read_b128 v[194:197], v156 offset:18432
	ds_read_b128 v[198:201], v156 offset:19456
	ds_read_b128 v[202:205], v156 offset:20480
	ds_read_b128 v[206:209], v156 offset:21504
	ds_read_b128 v[210:213], v156 offset:22528
	ds_read_b128 v[218:221], v156 offset:23552
	global_load_lds_dwordx4 v[222:223], off
	s_add_i32 m0, s86, 0x2000
	s_add_u32 s86, s62, 0x80000
	v_lshl_add_u64 v[224:225], s[62:63], 0, v[134:135]
	s_addc_u32 s87, s63, 0
	s_add_i32 s88, s81, s71
	global_load_lds_dwordx4 v[224:225], off
	v_lshl_add_u64 v[226:227], s[86:87], 0, v[130:131]
	s_mov_b32 m0, s88
	v_lshl_add_u64 v[228:229], s[64:65], 0, v[132:133]
	global_load_lds_dwordx4 v[226:227], off
	v_lshl_add_u64 v[226:227], s[86:87], 0, v[134:135]
	s_add_i32 m0, s88, 0x2000
	s_nop 0
	global_load_lds_dwordx4 v[226:227], off
	v_lshl_add_u64 v[226:227], s[64:65], 0, v[128:129]
	s_mov_b32 m0, s59
	s_nop 0
	global_load_lds_dwordx4 v[226:227], off
	s_mov_b32 m0, s72
	s_nop 0
	global_load_lds_dwordx4 v[228:229], off
	s_waitcnt vmcnt(8)
	s_waitcnt lgkmcnt(0)
	s_barrier
; #define PG8_STAGE(bufoff, gbase, voff) do { _Pragma("unroll") for (int _i = 0; _i < 2; ++_i) \
;         __builtin_amdgcn_global_load_lds((const unsigned*)((const char*)(gbase) + (voff)[_i]), (PG8_LAS unsigned*)(lds + (bufoff) + ldsw + _i * 8192), 16, 0, 0); } while (0)
; #define PG8_LDA(dst, b, h) do { _Pragma("unroll") for (int m = 0; m < 4; ++m) _Pragma("unroll") for (int k = 0; k < 2; ++k) dst[m][k] = *(const PG8_LAS bf16x8*)(lds + PG8_SA(b, h) + aoff + m * 2048 + k * 1024); } while (0)
; #define PG8_LDB(dst, b, h) do { _Pragma("unroll") for (int n = 0; n < 2; ++n) _Pragma("unroll") for (int k = 0; k < 2; ++k) dst[n][k] = *(const PG8_LAS bf16x8*)(lds + PG8_SB(b, h) + boff + n * 2048 + k * 1024); } while (0)
; #define PG8_MMA(ai, bj, At, Bt) do { __builtin_amdgcn_s_setprio(1); _Pragma("unroll") for (int m = 0; m < 4; ++m) _Pragma("unroll") for (int n = 0; n < 2; ++n) _Pragma("unroll") for (int k = 0; k < 2; ++k) \
;         acc[ai][bj][m][n] = __builtin_amdgcn_mfma_f32_16x16x32_bf16(Bt[n][k], At[m][k], acc[ai][bj][m][n], 0, 0, 0); __builtin_amdgcn_s_setprio(0); } while (0)
; #define PG8_WAIT_V(n) asm volatile("s_waitcnt vmcnt(" #n ")" ::: "memory")
; #define PG8_WAIT_L(n) asm volatile("s_waitcnt lgkmcnt(" #n ")" ::: "memory")
; #define PG8_BAR __builtin_amdgcn_s_barrier()
; #define PG8_SCHED __builtin_amdgcn_sched_barrier(0)
; template <class Epi, class Sched, bool ALIGN_EPI = false, bool SP2 = false>
; __device__ __forceinline__ void gemm_phase(PG8_LAS unsigned char* lds, const Gemm g, const Sched& S, const Epi& E, int tid_in) {
;     ...
;             PG8_WAIT_V(8); PG8_WAIT_L(0); PG8_BAR; PG8_MMA(1, 0, At, B0); PG8_MMA(1, 1, At, B1); PG8_BAR; PG8_SCHED;
;             PG8_LDB(B0, 1, 0); PG8_LDB(B1, 1, 1); PG8_SCHED; PG8_LDA(At, 1, 0); PG8_STAGE(PG8_SA(0, 1), a2 + hstep, voffA);
;             PG8_WAIT_V(8); PG8_WAIT_L(0); PG8_BAR; PG8_MMA(0, 0, At, B0); PG8_MMA(0, 1, At, B1); PG8_BAR; PG8_SCHED;
	s_setprio 1
	s_waitcnt lgkmcnt(0)
	v_mfma_f32_16x16x32_bf16 v[60:63], v[146:149], v[186:189], v[60:63]
	v_mfma_f32_16x16x32_bf16 v[56:59], v[162:165], v[186:189], v[56:59]
	v_mfma_f32_16x16x32_bf16 v[44:47], v[146:149], v[194:197], v[44:47]
	v_mfma_f32_16x16x32_bf16 v[40:43], v[162:165], v[194:197], v[40:43]
	v_mfma_f32_16x16x32_bf16 v[28:31], v[146:149], v[202:205], v[28:31]
	v_mfma_f32_16x16x32_bf16 v[24:27], v[162:165], v[202:205], v[24:27]
	v_mfma_f32_16x16x32_bf16 v[12:15], v[146:149], v[210:213], v[12:15]
	v_mfma_f32_16x16x32_bf16 v[8:11], v[162:165], v[210:213], v[8:11]
	v_mfma_f32_16x16x32_bf16 v[60:63], v[158:161], v[190:193], v[60:63]
	v_mfma_f32_16x16x32_bf16 v[56:59], v[166:169], v[190:193], v[56:59]
	v_mfma_f32_16x16x32_bf16 v[44:47], v[158:161], v[198:201], v[44:47]
	v_mfma_f32_16x16x32_bf16 v[40:43], v[166:169], v[198:201], v[40:43]
	v_mfma_f32_16x16x32_bf16 v[28:31], v[158:161], v[206:209], v[28:31]
	v_mfma_f32_16x16x32_bf16 v[24:27], v[166:169], v[206:209], v[24:27]
	v_mfma_f32_16x16x32_bf16 v[12:15], v[158:161], v[218:221], v[12:15]
	v_mfma_f32_16x16x32_bf16 v[8:11], v[166:169], v[218:221], v[8:11]
	v_mfma_f32_16x16x32_bf16 v[52:55], v[170:173], v[186:189], v[52:55]
	v_mfma_f32_16x16x32_bf16 v[48:51], v[178:181], v[186:189], v[48:51]
	v_mfma_f32_16x16x32_bf16 v[36:39], v[170:173], v[194:197], v[36:39]
	v_mfma_f32_16x16x32_bf16 v[32:35], v[178:181], v[194:197], v[32:35]
	v_mfma_f32_16x16x32_bf16 v[20:23], v[170:173], v[202:205], v[20:23]
	v_mfma_f32_16x16x32_bf16 v[16:19], v[178:181], v[202:205], v[16:19]
	v_mfma_f32_16x16x32_bf16 v[4:7], v[170:173], v[210:213], v[4:7]
	v_mfma_f32_16x16x32_bf16 v[0:3], v[178:181], v[210:213], v[0:3]
	v_mfma_f32_16x16x32_bf16 v[52:55], v[174:177], v[190:193], v[52:55]
	v_mfma_f32_16x16x32_bf16 v[48:51], v[182:185], v[190:193], v[48:51]
	v_mfma_f32_16x16x32_bf16 v[36:39], v[174:177], v[198:201], v[36:39]
	v_mfma_f32_16x16x32_bf16 v[32:35], v[182:185], v[198:201], v[32:35]
	v_mfma_f32_16x16x32_bf16 v[20:23], v[174:177], v[206:209], v[20:23]
	v_mfma_f32_16x16x32_bf16 v[16:19], v[182:185], v[206:209], v[16:19]
	v_mfma_f32_16x16x32_bf16 v[4:7], v[174:177], v[218:221], v[4:7]
	v_mfma_f32_16x16x32_bf16 v[0:3], v[182:185], v[218:221], v[0:3]
	s_setprio 0
	s_barrier
	s_add_i32 s86, 0, 0x18000
	v_add_u32_e32 v157, s86, v151
	s_add_i32 s87, 0, 0x1c000
	ds_read_b128 v[146:149], v157
	ds_read_b128 v[158:161], v157 offset:1024
	ds_read_b128 v[162:165], v157 offset:2048
	ds_read_b128 v[166:169], v157 offset:3072
	v_add_u32_e32 v157, s87, v151
	ds_read_b128 v[170:173], v157
	ds_read_b128 v[174:177], v157 offset:1024
	ds_read_b128 v[178:181], v157 offset:2048
	ds_read_b128 v[182:185], v157 offset:3072
	s_add_u32 s64, s64, 0x80000
	s_addc_u32 s65, s65, 0
	s_mov_b32 m0, s73
	v_lshl_add_u64 v[230:231], s[64:65], 0, v[128:129]
	ds_read_b128 v[186:189], v156 offset:32768
	ds_read_b128 v[190:193], v156 offset:33792
	ds_read_b128 v[194:197], v156 offset:34816
	ds_read_b128 v[198:201], v156 offset:35840
	ds_read_b128 v[202:205], v156 offset:36864
	ds_read_b128 v[206:209], v156 offset:37888
	ds_read_b128 v[210:213], v156 offset:38912
	ds_read_b128 v[218:221], v156 offset:39936
	global_load_lds_dwordx4 v[230:231], off
	v_lshl_add_u64 v[230:231], s[64:65], 0, v[132:133]
	s_mov_b32 m0, s74
	s_nop 0
	global_load_lds_dwordx4 v[230:231], off
	s_waitcnt vmcnt(8)
	s_waitcnt lgkmcnt(0)
	s_barrier
	s_setprio 1
	s_waitcnt lgkmcnt(0)
	v_mfma_f32_16x16x32_bf16 v[124:127], v[146:149], v[186:189], v[124:127]
	v_mfma_f32_16x16x32_bf16 v[120:123], v[162:165], v[186:189], v[120:123]
	v_mfma_f32_16x16x32_bf16 v[108:111], v[146:149], v[194:197], v[108:111]
	v_mfma_f32_16x16x32_bf16 v[104:107], v[162:165], v[194:197], v[104:107]
	v_mfma_f32_16x16x32_bf16 v[92:95], v[146:149], v[202:205], v[92:95]
	v_mfma_f32_16x16x32_bf16 v[88:91], v[162:165], v[202:205], v[88:91]
	v_mfma_f32_16x16x32_bf16 v[76:79], v[146:149], v[210:213], v[76:79]
	v_mfma_f32_16x16x32_bf16 v[72:75], v[162:165], v[210:213], v[72:75]
	v_mfma_f32_16x16x32_bf16 v[124:127], v[158:161], v[190:193], v[124:127]
	v_mfma_f32_16x16x32_bf16 v[120:123], v[166:169], v[190:193], v[120:123]
	v_mfma_f32_16x16x32_bf16 v[108:111], v[158:161], v[198:201], v[108:111]
	v_mfma_f32_16x16x32_bf16 v[104:107], v[166:169], v[198:201], v[104:107]
	v_mfma_f32_16x16x32_bf16 v[92:95], v[158:161], v[206:209], v[92:95]
	v_mfma_f32_16x16x32_bf16 v[88:91], v[166:169], v[206:209], v[88:91]
	v_mfma_f32_16x16x32_bf16 v[76:79], v[158:161], v[218:221], v[76:79]
	v_mfma_f32_16x16x32_bf16 v[72:75], v[166:169], v[218:221], v[72:75]
	v_mfma_f32_16x16x32_bf16 v[116:119], v[170:173], v[186:189], v[116:119]
	v_mfma_f32_16x16x32_bf16 v[112:115], v[178:181], v[186:189], v[112:115]
	v_mfma_f32_16x16x32_bf16 v[100:103], v[170:173], v[194:197], v[100:103]
	v_mfma_f32_16x16x32_bf16 v[96:99], v[178:181], v[194:197], v[96:99]
	v_mfma_f32_16x16x32_bf16 v[84:87], v[170:173], v[202:205], v[84:87]
	v_mfma_f32_16x16x32_bf16 v[80:83], v[178:181], v[202:205], v[80:83]
	v_mfma_f32_16x16x32_bf16 v[68:71], v[170:173], v[210:213], v[68:71]
	v_mfma_f32_16x16x32_bf16 v[64:67], v[178:181], v[210:213], v[64:67]
	v_mfma_f32_16x16x32_bf16 v[116:119], v[174:177], v[190:193], v[116:119]
	v_mfma_f32_16x16x32_bf16 v[112:115], v[182:185], v[190:193], v[112:115]
	v_mfma_f32_16x16x32_bf16 v[100:103], v[174:177], v[198:201], v[100:103]
	v_mfma_f32_16x16x32_bf16 v[96:99], v[182:185], v[198:201], v[96:99]
	v_mfma_f32_16x16x32_bf16 v[84:87], v[174:177], v[206:209], v[84:87]
	v_mfma_f32_16x16x32_bf16 v[80:83], v[182:185], v[206:209], v[80:83]
	v_mfma_f32_16x16x32_bf16 v[68:71], v[174:177], v[218:221], v[68:71]
	v_mfma_f32_16x16x32_bf16 v[64:67], v[182:185], v[218:221], v[64:67]
	s_setprio 0
	s_barrier
; #define PG8_STAGE(bufoff, gbase, voff) do { _Pragma("unroll") for (int _i = 0; _i < 2; ++_i) \
;         __builtin_amdgcn_global_load_lds((const unsigned*)((const char*)(gbase) + (voff)[_i]), (PG8_LAS unsigned*)(lds + (bufoff) + ldsw + _i * 8192), 16, 0, 0); } while (0)
; #define PG8_LDA(dst, b, h) do { _Pragma("unroll") for (int m = 0; m < 4; ++m) _Pragma("unroll") for (int k = 0; k < 2; ++k) dst[m][k] = *(const PG8_LAS bf16x8*)(lds + PG8_SA(b, h) + aoff + m * 2048 + k * 1024); } while (0)
; #define PG8_MMA(ai, bj, At, Bt) do { __builtin_amdgcn_s_setprio(1); _Pragma("unroll") for (int m = 0; m < 4; ++m) _Pragma("unroll") for (int n = 0; n < 2; ++n) _Pragma("unroll") for (int k = 0; k < 2; ++k) \
;         acc[ai][bj][m][n] = __builtin_amdgcn_mfma_f32_16x16x32_bf16(Bt[n][k], At[m][k], acc[ai][bj][m][n], 0, 0, 0); __builtin_amdgcn_s_setprio(0); } while (0)
; #define PG8_WAIT_V(n) asm volatile("s_waitcnt vmcnt(" #n ")" ::: "memory")
; #define PG8_WAIT_L(n) asm volatile("s_waitcnt lgkmcnt(" #n ")" ::: "memory")
; #define PG8_BAR __builtin_amdgcn_s_barrier()
; #define PG8_SCHED __builtin_amdgcn_sched_barrier(0)
; template <class Epi, class Sched, bool ALIGN_EPI = false, bool SP2 = false>
; __device__ __forceinline__ void gemm_phase(PG8_LAS unsigned char* lds, const Gemm g, const Sched& S, const Epi& E, int tid_in) {
;     ...
;             PG8_LDA(At, 1, 1); PG8_STAGE(PG8_SB(1, 0), b3, voffB); PG8_STAGE(PG8_SB(1, 1), b3 + hstep, voffB); PG8_STAGE(PG8_SA(1, 0), a3, voffA);
;             PG8_WAIT_V(8); PG8_WAIT_L(0); PG8_BAR; PG8_MMA(1, 0, At, B0); PG8_MMA(1, 1, At, B1); PG8_BAR; PG8_SCHED;
;     ...
;         if constexpr (ALIGN_EPI) { if (wr == 0) PG8_BAR; }
	s_add_i32 s64, s86, s71
	v_lshl_add_u64 v[222:223], v[222:223], 0, s[20:21]
	s_mov_b32 m0, s64
	ds_read_b128 v[186:189], v156 offset:49152
	ds_read_b128 v[190:193], v156 offset:50176
	ds_read_b128 v[194:197], v156 offset:51200
	ds_read_b128 v[198:201], v156 offset:52224
	ds_read_b128 v[202:205], v156 offset:53248
	ds_read_b128 v[206:209], v156 offset:54272
	ds_read_b128 v[210:213], v156 offset:55296
	ds_read_b128 v[218:221], v156 offset:56320
	global_load_lds_dwordx4 v[222:223], off
	s_add_i32 m0, s64, 0x2000
	s_add_u32 s62, s62, 0x80080
	v_lshl_add_u64 v[222:223], v[224:225], 0, s[20:21]
	s_addc_u32 s63, s63, 0
	s_add_i32 s64, s87, s71
	global_load_lds_dwordx4 v[222:223], off
	v_lshl_add_u64 v[222:223], s[62:63], 0, v[130:131]
	s_mov_b32 m0, s64
	s_nop 0
	global_load_lds_dwordx4 v[222:223], off
	v_lshl_add_u64 v[222:223], s[62:63], 0, v[134:135]
	s_add_i32 m0, s64, 0x2000
	s_nop 0
	global_load_lds_dwordx4 v[222:223], off
	v_lshl_add_u64 v[222:223], v[226:227], 0, s[20:21]
	s_mov_b32 m0, s76
	s_nop 0
	global_load_lds_dwordx4 v[222:223], off
	v_lshl_add_u64 v[222:223], v[228:229], 0, s[20:21]
	s_mov_b32 m0, s77
	s_nop 0
	global_load_lds_dwordx4 v[222:223], off
	s_waitcnt vmcnt(8)
	s_waitcnt lgkmcnt(0)
	s_barrier
	s_setprio 1
	s_waitcnt lgkmcnt(0)
	v_mfma_f32_16x16x32_bf16 v[60:63], v[146:149], v[186:189], v[60:63]
	v_mfma_f32_16x16x32_bf16 v[56:59], v[162:165], v[186:189], v[56:59]
	v_mfma_f32_16x16x32_bf16 v[44:47], v[146:149], v[194:197], v[44:47]
	v_mfma_f32_16x16x32_bf16 v[40:43], v[162:165], v[194:197], v[40:43]
	v_mfma_f32_16x16x32_bf16 v[28:31], v[146:149], v[202:205], v[28:31]
	v_mfma_f32_16x16x32_bf16 v[24:27], v[162:165], v[202:205], v[24:27]
	v_mfma_f32_16x16x32_bf16 v[12:15], v[146:149], v[210:213], v[12:15]
	v_mfma_f32_16x16x32_bf16 v[8:11], v[162:165], v[210:213], v[8:11]
	v_mfma_f32_16x16x32_bf16 v[60:63], v[158:161], v[190:193], v[60:63]
	v_mfma_f32_16x16x32_bf16 v[56:59], v[166:169], v[190:193], v[56:59]
	v_mfma_f32_16x16x32_bf16 v[44:47], v[158:161], v[198:201], v[44:47]
	v_mfma_f32_16x16x32_bf16 v[40:43], v[166:169], v[198:201], v[40:43]
	v_mfma_f32_16x16x32_bf16 v[28:31], v[158:161], v[206:209], v[28:31]
	v_mfma_f32_16x16x32_bf16 v[24:27], v[166:169], v[206:209], v[24:27]
	v_mfma_f32_16x16x32_bf16 v[12:15], v[158:161], v[218:221], v[12:15]
	v_mfma_f32_16x16x32_bf16 v[8:11], v[166:169], v[218:221], v[8:11]
	v_mfma_f32_16x16x32_bf16 v[52:55], v[170:173], v[186:189], v[52:55]
	v_mfma_f32_16x16x32_bf16 v[48:51], v[178:181], v[186:189], v[48:51]
	v_mfma_f32_16x16x32_bf16 v[36:39], v[170:173], v[194:197], v[36:39]
	v_mfma_f32_16x16x32_bf16 v[32:35], v[178:181], v[194:197], v[32:35]
	v_mfma_f32_16x16x32_bf16 v[20:23], v[170:173], v[202:205], v[20:23]
	v_mfma_f32_16x16x32_bf16 v[16:19], v[178:181], v[202:205], v[16:19]
	v_mfma_f32_16x16x32_bf16 v[4:7], v[170:173], v[210:213], v[4:7]
	v_mfma_f32_16x16x32_bf16 v[0:3], v[178:181], v[210:213], v[0:3]
	v_mfma_f32_16x16x32_bf16 v[52:55], v[174:177], v[190:193], v[52:55]
	v_mfma_f32_16x16x32_bf16 v[48:51], v[182:185], v[190:193], v[48:51]
	v_mfma_f32_16x16x32_bf16 v[36:39], v[174:177], v[198:201], v[36:39]
	v_mfma_f32_16x16x32_bf16 v[32:35], v[182:185], v[198:201], v[32:35]
	v_mfma_f32_16x16x32_bf16 v[20:23], v[174:177], v[206:209], v[20:23]
	v_mfma_f32_16x16x32_bf16 v[16:19], v[182:185], v[206:209], v[16:19]
	v_mfma_f32_16x16x32_bf16 v[4:7], v[174:177], v[218:221], v[4:7]
	v_mfma_f32_16x16x32_bf16 v[0:3], v[182:185], v[218:221], v[0:3]
	s_setprio 0
	s_barrier
	s_add_i32 s85, s85, 2
	s_add_u32 s60, s60, 0x100
	s_addc_u32 s61, s61, 0
	s_add_u32 s83, s83, 0x100
	s_addc_u32 s84, s84, 0
	s_cmp_gt_u32 s85, 29
	s_cbranch_scc0 .LBB0_302
	s_and_b64 vcc, exec, s[22:23]
	s_cbranch_vccz .LBB0_305
	s_barrier

; #define PG8_STAGE(bufoff, gbase, voff) do { _Pragma("unroll") for (int _i = 0; _i < 2; ++_i) \
;         __builtin_amdgcn_global_load_lds((const unsigned*)((const char*)(gbase) + (voff)[_i]), (PG8_LAS unsigned*)(lds + (bufoff) + ldsw + _i * 8192), 16, 0, 0); } while (0)
; #define PG8_LDA(dst, b, h) do { _Pragma("unroll") for (int m = 0; m < 4; ++m) _Pragma("unroll") for (int k = 0; k < 2; ++k) dst[m][k] = *(const PG8_LAS bf16x8*)(lds + PG8_SA(b, h) + aoff + m * 2048 + k * 1024); } while (0)
; #define PG8_LDB(dst, b, h) do { _Pragma("unroll") for (int n = 0; n < 2; ++n) _Pragma("unroll") for (int k = 0; k < 2; ++k) dst[n][k] = *(const PG8_LAS bf16x8*)(lds + PG8_SB(b, h) + boff + n * 2048 + k * 1024); } while (0)
; #define PG8_MMA(ai, bj, At, Bt) do { __builtin_amdgcn_s_setprio(1); _Pragma("unroll") for (int m = 0; m < 4; ++m) _Pragma("unroll") for (int n = 0; n < 2; ++n) _Pragma("unroll") for (int k = 0; k < 2; ++k) \
;         acc[ai][bj][m][n] = __builtin_amdgcn_mfma_f32_16x16x32_bf16(Bt[n][k], At[m][k], acc[ai][bj][m][n], 0, 0, 0); __builtin_amdgcn_s_setprio(0); } while (0)
; #define PG8_WAIT_V(n) asm volatile("s_waitcnt vmcnt(" #n ")" ::: "memory")
; #define PG8_WAIT_L(n) asm volatile("s_waitcnt lgkmcnt(" #n ")" ::: "memory")
; #define PG8_BAR __builtin_amdgcn_s_barrier()
; #define PG8_SCHED __builtin_amdgcn_sched_barrier(0)
; template <class Epi, class Sched, bool ALIGN_EPI = false, bool SP2 = false>
; __device__ __forceinline__ void gemm_phase(PG8_LAS unsigned char* lds, const Gemm g, const Sched& S, const Epi& E, int tid_in) {
;     ...
;             const bool last = (t == nt - 2);
;             const char* a1 = cA + (size_t)(t + 1) * kstep;
;             const char* a2 = last ? nA : cA + (size_t)(t + 2) * kstep; const char* b2 = last ? nB : cB + (size_t)(t + 2) * kstep;
;             const char* a3 = a2 + kstep; const char* b3 = b2 + kstep;
;             if (last && has_next) S.a_ready(nxt);
;             if constexpr (SP2) {
;             PG8_LDB(B0, 0, 0); PG8_LDB(B1, 0, 1); PG8_SCHED; PG8_LDA(At, 0, 0); PG8_STAGE(PG8_SA(1, 1), a1 + hstep, voffA);
;             PG8_WAIT_V(8); PG8_WAIT_L(0); PG8_BAR; PG8_MMA(0, 0, At, B0); PG8_MMA(0, 1, At, B1); PG8_BAR; PG8_SCHED;
;             PG8_LDA(At, 0, 1); PG8_STAGE(PG8_SB(0, 0), b2, voffB); PG8_STAGE(PG8_SB(0, 1), b2 + hstep, voffB); PG8_STAGE(PG8_SA(0, 0), a2, voffA);
.LBB0_352:
	ds_read_b128 v[148:151], v161
	ds_read_b128 v[152:155], v161 offset:1024
	ds_read_b128 v[166:169], v161 offset:2048
	ds_read_b128 v[170:173], v161 offset:3072
	ds_read_b128 v[174:177], v162
	ds_read_b128 v[178:181], v162 offset:1024
	ds_read_b128 v[182:185], v162 offset:2048
	ds_read_b128 v[186:189], v162 offset:3072
	s_add_u32 s64, s62, 0xfffc0080
	s_addc_u32 s65, s63, -1
	s_cmp_eq_u32 s92, 12
	s_cselect_b32 s67, s9, s65
	s_cselect_b32 s66, s11, s64
	s_cselect_b32 s65, s55, s91
	s_cselect_b32 s64, s57, s90
	v_lshl_add_u64 v[156:157], s[62:63], 0, v[140:141]
	s_add_i32 m0, s74, 0xc000
	ds_read_b128 v[190:193], v163
	ds_read_b128 v[194:197], v163 offset:1024
	ds_read_b128 v[198:201], v163 offset:2048
	ds_read_b128 v[202:205], v163 offset:3072
	ds_read_b128 v[206:209], v163 offset:4096
	ds_read_b128 v[210:213], v163 offset:5120
	ds_read_b128 v[216:219], v163 offset:6144
	ds_read_b128 v[220:223], v163 offset:7168
	global_load_lds_dwordx4 v[156:157], off
	v_lshl_add_u64 v[156:157], s[62:63], 0, v[142:143]
	s_add_i32 m0, s74, 0xe000
	s_nop 0
	global_load_lds_dwordx4 v[156:157], off
	s_waitcnt vmcnt(8)
	s_waitcnt lgkmcnt(0)
	s_barrier
	s_setprio 1
	s_waitcnt lgkmcnt(0)
	v_mfma_f32_16x16x32_bf16 v[124:127], v[148:151], v[190:193], v[124:127]
	v_mfma_f32_16x16x32_bf16 v[120:123], v[166:169], v[190:193], v[120:123]
	v_mfma_f32_16x16x32_bf16 v[108:111], v[148:151], v[198:201], v[108:111]
	v_mfma_f32_16x16x32_bf16 v[104:107], v[166:169], v[198:201], v[104:107]
	v_mfma_f32_16x16x32_bf16 v[92:95], v[148:151], v[206:209], v[92:95]
	v_mfma_f32_16x16x32_bf16 v[88:91], v[166:169], v[206:209], v[88:91]
	v_mfma_f32_16x16x32_bf16 v[76:79], v[148:151], v[216:219], v[76:79]
	v_mfma_f32_16x16x32_bf16 v[72:75], v[166:169], v[216:219], v[72:75]
	v_mfma_f32_16x16x32_bf16 v[124:127], v[152:155], v[194:197], v[124:127]
	v_mfma_f32_16x16x32_bf16 v[120:123], v[170:173], v[194:197], v[120:123]
	v_mfma_f32_16x16x32_bf16 v[108:111], v[152:155], v[202:205], v[108:111]
	v_mfma_f32_16x16x32_bf16 v[104:107], v[170:173], v[202:205], v[104:107]
	v_mfma_f32_16x16x32_bf16 v[92:95], v[152:155], v[210:213], v[92:95]
	v_mfma_f32_16x16x32_bf16 v[88:91], v[170:173], v[210:213], v[88:91]
	v_mfma_f32_16x16x32_bf16 v[76:79], v[152:155], v[220:223], v[76:79]
	v_mfma_f32_16x16x32_bf16 v[72:75], v[170:173], v[220:223], v[72:75]
	v_mfma_f32_16x16x32_bf16 v[116:119], v[174:177], v[190:193], v[116:119]
	v_mfma_f32_16x16x32_bf16 v[112:115], v[182:185], v[190:193], v[112:115]
	v_mfma_f32_16x16x32_bf16 v[100:103], v[174:177], v[198:201], v[100:103]
	v_mfma_f32_16x16x32_bf16 v[96:99], v[182:185], v[198:201], v[96:99]
	v_mfma_f32_16x16x32_bf16 v[84:87], v[174:177], v[206:209], v[84:87]
	v_mfma_f32_16x16x32_bf16 v[80:83], v[182:185], v[206:209], v[80:83]
	v_mfma_f32_16x16x32_bf16 v[68:71], v[174:177], v[216:219], v[68:71]
	v_mfma_f32_16x16x32_bf16 v[64:67], v[182:185], v[216:219], v[64:67]
	v_mfma_f32_16x16x32_bf16 v[116:119], v[178:181], v[194:197], v[116:119]
	v_mfma_f32_16x16x32_bf16 v[112:115], v[186:189], v[194:197], v[112:115]
	v_mfma_f32_16x16x32_bf16 v[100:103], v[178:181], v[202:205], v[100:103]
	v_mfma_f32_16x16x32_bf16 v[96:99], v[186:189], v[202:205], v[96:99]
	v_mfma_f32_16x16x32_bf16 v[84:87], v[178:181], v[210:213], v[84:87]
	v_mfma_f32_16x16x32_bf16 v[80:83], v[186:189], v[210:213], v[80:83]
	v_mfma_f32_16x16x32_bf16 v[68:71], v[178:181], v[220:223], v[68:71]
	v_mfma_f32_16x16x32_bf16 v[64:67], v[186:189], v[220:223], v[64:67]
	s_setprio 0
	s_barrier
	s_add_i32 s93, s83, s73
	v_lshl_add_u64 v[156:157], s[64:65], 0, v[130:131]
	s_mov_b32 m0, s93
	ds_read_b128 v[190:193], v163 offset:16384
	ds_read_b128 v[194:197], v163 offset:17408
	ds_read_b128 v[198:201], v163 offset:18432
	ds_read_b128 v[202:205], v163 offset:19456
	ds_read_b128 v[206:209], v163 offset:20480
	ds_read_b128 v[210:213], v163 offset:21504
	ds_read_b128 v[216:219], v163 offset:22528
	ds_read_b128 v[220:223], v163 offset:23552
	global_load_lds_dwordx4 v[156:157], off
	s_add_i32 m0, s93, 0x2000
	s_add_u32 s94, s64, 0x40000
	v_lshl_add_u64 v[224:225], s[64:65], 0, v[134:135]
	s_addc_u32 s95, s65, 0
	s_add_i32 s93, s84, s73
	global_load_lds_dwordx4 v[224:225], off
	v_lshl_add_u64 v[226:227], s[94:95], 0, v[130:131]
	s_mov_b32 m0, s93
	v_lshl_add_u64 v[228:229], s[66:67], 0, v[132:133]
	global_load_lds_dwordx4 v[226:227], off
	v_lshl_add_u64 v[226:227], s[94:95], 0, v[134:135]
	s_add_i32 m0, s93, 0x2000
	s_nop 0
	global_load_lds_dwordx4 v[226:227], off
	v_lshl_add_u64 v[226:227], s[66:67], 0, v[128:129]
	s_mov_b32 m0, s74
	s_nop 0
	global_load_lds_dwordx4 v[226:227], off
	s_mov_b32 m0, s75
	s_nop 0
	global_load_lds_dwordx4 v[228:229], off
	s_waitcnt vmcnt(8)
	s_waitcnt lgkmcnt(0)
	s_barrier
; #define PG8_STAGE(bufoff, gbase, voff) do { _Pragma("unroll") for (int _i = 0; _i < 2; ++_i) \
;         __builtin_amdgcn_global_load_lds((const unsigned*)((const char*)(gbase) + (voff)[_i]), (PG8_LAS unsigned*)(lds + (bufoff) + ldsw + _i * 8192), 16, 0, 0); } while (0)
; #define PG8_LDA(dst, b, h) do { _Pragma("unroll") for (int m = 0; m < 4; ++m) _Pragma("unroll") for (int k = 0; k < 2; ++k) dst[m][k] = *(const PG8_LAS bf16x8*)(lds + PG8_SA(b, h) + aoff + m * 2048 + k * 1024); } while (0)
; #define PG8_LDB(dst, b, h) do { _Pragma("unroll") for (int n = 0; n < 2; ++n) _Pragma("unroll") for (int k = 0; k < 2; ++k) dst[n][k] = *(const PG8_LAS bf16x8*)(lds + PG8_SB(b, h) + boff + n * 2048 + k * 1024); } while (0)
; #define PG8_MMA(ai, bj, At, Bt) do { __builtin_amdgcn_s_setprio(1); _Pragma("unroll") for (int m = 0; m < 4; ++m) _Pragma("unroll") for (int n = 0; n < 2; ++n) _Pragma("unroll") for (int k = 0; k < 2; ++k) \
;         acc[ai][bj][m][n] = __builtin_amdgcn_mfma_f32_16x16x32_bf16(Bt[n][k], At[m][k], acc[ai][bj][m][n], 0, 0, 0); __builtin_amdgcn_s_setprio(0); } while (0)
; #define PG8_WAIT_V(n) asm volatile("s_waitcnt vmcnt(" #n ")" ::: "memory")
; #define PG8_WAIT_L(n) asm volatile("s_waitcnt lgkmcnt(" #n ")" ::: "memory")
; #define PG8_BAR __builtin_amdgcn_s_barrier()
; #define PG8_SCHED __builtin_amdgcn_sched_barrier(0)
; template <class Epi, class Sched, bool ALIGN_EPI = false, bool SP2 = false>
; __device__ __forceinline__ void gemm_phase(PG8_LAS unsigned char* lds, const Gemm g, const Sched& S, const Epi& E, int tid_in) {
;     ...
;             PG8_WAIT_V(8); PG8_WAIT_L(0); PG8_BAR; PG8_MMA(1, 0, At, B0); PG8_MMA(1, 1, At, B1); PG8_BAR; PG8_SCHED;
;             PG8_LDB(B0, 1, 0); PG8_LDB(B1, 1, 1); PG8_SCHED; PG8_LDA(At, 1, 0); PG8_STAGE(PG8_SA(0, 1), a2 + hstep, voffA);
;             PG8_WAIT_V(8); PG8_WAIT_L(0); PG8_BAR; PG8_MMA(0, 0, At, B0); PG8_MMA(0, 1, At, B1); PG8_BAR; PG8_SCHED;
	s_setprio 1
	s_waitcnt lgkmcnt(0)
	v_mfma_f32_16x16x32_bf16 v[60:63], v[148:151], v[190:193], v[60:63]
	v_mfma_f32_16x16x32_bf16 v[56:59], v[166:169], v[190:193], v[56:59]
	v_mfma_f32_16x16x32_bf16 v[44:47], v[148:151], v[198:201], v[44:47]
	v_mfma_f32_16x16x32_bf16 v[40:43], v[166:169], v[198:201], v[40:43]
	v_mfma_f32_16x16x32_bf16 v[28:31], v[148:151], v[206:209], v[28:31]
	v_mfma_f32_16x16x32_bf16 v[24:27], v[166:169], v[206:209], v[24:27]
	v_mfma_f32_16x16x32_bf16 v[12:15], v[148:151], v[216:219], v[12:15]
	v_mfma_f32_16x16x32_bf16 v[8:11], v[166:169], v[216:219], v[8:11]
	v_mfma_f32_16x16x32_bf16 v[60:63], v[152:155], v[194:197], v[60:63]
	v_mfma_f32_16x16x32_bf16 v[56:59], v[170:173], v[194:197], v[56:59]
	v_mfma_f32_16x16x32_bf16 v[44:47], v[152:155], v[202:205], v[44:47]
	v_mfma_f32_16x16x32_bf16 v[40:43], v[170:173], v[202:205], v[40:43]
	v_mfma_f32_16x16x32_bf16 v[28:31], v[152:155], v[210:213], v[28:31]
	v_mfma_f32_16x16x32_bf16 v[24:27], v[170:173], v[210:213], v[24:27]
	v_mfma_f32_16x16x32_bf16 v[12:15], v[152:155], v[220:223], v[12:15]
	v_mfma_f32_16x16x32_bf16 v[8:11], v[170:173], v[220:223], v[8:11]
	v_mfma_f32_16x16x32_bf16 v[52:55], v[174:177], v[190:193], v[52:55]
	v_mfma_f32_16x16x32_bf16 v[48:51], v[182:185], v[190:193], v[48:51]
	v_mfma_f32_16x16x32_bf16 v[36:39], v[174:177], v[198:201], v[36:39]
	v_mfma_f32_16x16x32_bf16 v[32:35], v[182:185], v[198:201], v[32:35]
	v_mfma_f32_16x16x32_bf16 v[20:23], v[174:177], v[206:209], v[20:23]
	v_mfma_f32_16x16x32_bf16 v[16:19], v[182:185], v[206:209], v[16:19]
	v_mfma_f32_16x16x32_bf16 v[4:7], v[174:177], v[216:219], v[4:7]
	v_mfma_f32_16x16x32_bf16 v[0:3], v[182:185], v[216:219], v[0:3]
	v_mfma_f32_16x16x32_bf16 v[52:55], v[178:181], v[194:197], v[52:55]
	v_mfma_f32_16x16x32_bf16 v[48:51], v[186:189], v[194:197], v[48:51]
	v_mfma_f32_16x16x32_bf16 v[36:39], v[178:181], v[202:205], v[36:39]
	v_mfma_f32_16x16x32_bf16 v[32:35], v[186:189], v[202:205], v[32:35]
	v_mfma_f32_16x16x32_bf16 v[20:23], v[178:181], v[210:213], v[20:23]
	v_mfma_f32_16x16x32_bf16 v[16:19], v[186:189], v[210:213], v[16:19]
	v_mfma_f32_16x16x32_bf16 v[4:7], v[178:181], v[220:223], v[4:7]
	v_mfma_f32_16x16x32_bf16 v[0:3], v[186:189], v[220:223], v[0:3]
	s_setprio 0
	s_barrier
	s_add_i32 s93, 0, 0x18000
	v_add_u32_e32 v138, s93, v159
	s_add_i32 s94, 0, 0x1c000
	ds_read_b128 v[148:151], v138
	ds_read_b128 v[152:155], v138 offset:1024
	ds_read_b128 v[166:169], v138 offset:2048
	ds_read_b128 v[170:173], v138 offset:3072
	v_add_u32_e32 v138, s94, v159
	ds_read_b128 v[174:177], v138
	ds_read_b128 v[178:181], v138 offset:1024
	ds_read_b128 v[182:185], v138 offset:2048
	ds_read_b128 v[186:189], v138 offset:3072
	s_add_u32 s66, s66, 0x40000
	s_addc_u32 s67, s67, 0
	s_mov_b32 m0, s76
	v_lshl_add_u64 v[230:231], s[66:67], 0, v[128:129]
	ds_read_b128 v[190:193], v163 offset:32768
	ds_read_b128 v[194:197], v163 offset:33792
	ds_read_b128 v[198:201], v163 offset:34816
	ds_read_b128 v[202:205], v163 offset:35840
	ds_read_b128 v[206:209], v163 offset:36864
	ds_read_b128 v[210:213], v163 offset:37888
	ds_read_b128 v[216:219], v163 offset:38912
	ds_read_b128 v[220:223], v163 offset:39936
	global_load_lds_dwordx4 v[230:231], off
	v_lshl_add_u64 v[230:231], s[66:67], 0, v[132:133]
	s_mov_b32 m0, s77
	s_nop 0
	global_load_lds_dwordx4 v[230:231], off
	s_waitcnt vmcnt(8)
	s_waitcnt lgkmcnt(0)
	s_barrier
	s_setprio 1
	s_waitcnt lgkmcnt(0)
	v_mfma_f32_16x16x32_bf16 v[124:127], v[148:151], v[190:193], v[124:127]
	v_mfma_f32_16x16x32_bf16 v[120:123], v[166:169], v[190:193], v[120:123]
	v_mfma_f32_16x16x32_bf16 v[108:111], v[148:151], v[198:201], v[108:111]
	v_mfma_f32_16x16x32_bf16 v[104:107], v[166:169], v[198:201], v[104:107]
	v_mfma_f32_16x16x32_bf16 v[92:95], v[148:151], v[206:209], v[92:95]
	v_mfma_f32_16x16x32_bf16 v[88:91], v[166:169], v[206:209], v[88:91]
	v_mfma_f32_16x16x32_bf16 v[76:79], v[148:151], v[216:219], v[76:79]
	v_mfma_f32_16x16x32_bf16 v[72:75], v[166:169], v[216:219], v[72:75]
	v_mfma_f32_16x16x32_bf16 v[124:127], v[152:155], v[194:197], v[124:127]
	v_mfma_f32_16x16x32_bf16 v[120:123], v[170:173], v[194:197], v[120:123]
	v_mfma_f32_16x16x32_bf16 v[108:111], v[152:155], v[202:205], v[108:111]
	v_mfma_f32_16x16x32_bf16 v[104:107], v[170:173], v[202:205], v[104:107]
	v_mfma_f32_16x16x32_bf16 v[92:95], v[152:155], v[210:213], v[92:95]
	v_mfma_f32_16x16x32_bf16 v[88:91], v[170:173], v[210:213], v[88:91]
	v_mfma_f32_16x16x32_bf16 v[76:79], v[152:155], v[220:223], v[76:79]
	v_mfma_f32_16x16x32_bf16 v[72:75], v[170:173], v[220:223], v[72:75]
	v_mfma_f32_16x16x32_bf16 v[116:119], v[174:177], v[190:193], v[116:119]
	v_mfma_f32_16x16x32_bf16 v[112:115], v[182:185], v[190:193], v[112:115]
	v_mfma_f32_16x16x32_bf16 v[100:103], v[174:177], v[198:201], v[100:103]
	v_mfma_f32_16x16x32_bf16 v[96:99], v[182:185], v[198:201], v[96:99]
	v_mfma_f32_16x16x32_bf16 v[84:87], v[174:177], v[206:209], v[84:87]
	v_mfma_f32_16x16x32_bf16 v[80:83], v[182:185], v[206:209], v[80:83]
	v_mfma_f32_16x16x32_bf16 v[68:71], v[174:177], v[216:219], v[68:71]
	v_mfma_f32_16x16x32_bf16 v[64:67], v[182:185], v[216:219], v[64:67]
	v_mfma_f32_16x16x32_bf16 v[116:119], v[178:181], v[194:197], v[116:119]
	v_mfma_f32_16x16x32_bf16 v[112:115], v[186:189], v[194:197], v[112:115]
	v_mfma_f32_16x16x32_bf16 v[100:103], v[178:181], v[202:205], v[100:103]
	v_mfma_f32_16x16x32_bf16 v[96:99], v[186:189], v[202:205], v[96:99]
	v_mfma_f32_16x16x32_bf16 v[84:87], v[178:181], v[210:213], v[84:87]
	v_mfma_f32_16x16x32_bf16 v[80:83], v[186:189], v[210:213], v[80:83]
	v_mfma_f32_16x16x32_bf16 v[68:71], v[178:181], v[220:223], v[68:71]
	v_mfma_f32_16x16x32_bf16 v[64:67], v[186:189], v[220:223], v[64:67]
	s_setprio 0
	s_barrier
; #define PG8_STAGE(bufoff, gbase, voff) do { _Pragma("unroll") for (int _i = 0; _i < 2; ++_i) \
;         __builtin_amdgcn_global_load_lds((const unsigned*)((const char*)(gbase) + (voff)[_i]), (PG8_LAS unsigned*)(lds + (bufoff) + ldsw + _i * 8192), 16, 0, 0); } while (0)
; #define PG8_LDA(dst, b, h) do { _Pragma("unroll") for (int m = 0; m < 4; ++m) _Pragma("unroll") for (int k = 0; k < 2; ++k) dst[m][k] = *(const PG8_LAS bf16x8*)(lds + PG8_SA(b, h) + aoff + m * 2048 + k * 1024); } while (0)
; #define PG8_MMA(ai, bj, At, Bt) do { __builtin_amdgcn_s_setprio(1); _Pragma("unroll") for (int m = 0; m < 4; ++m) _Pragma("unroll") for (int n = 0; n < 2; ++n) _Pragma("unroll") for (int k = 0; k < 2; ++k) \
;         acc[ai][bj][m][n] = __builtin_amdgcn_mfma_f32_16x16x32_bf16(Bt[n][k], At[m][k], acc[ai][bj][m][n], 0, 0, 0); __builtin_amdgcn_s_setprio(0); } while (0)
; #define PG8_WAIT_V(n) asm volatile("s_waitcnt vmcnt(" #n ")" ::: "memory")
; #define PG8_WAIT_L(n) asm volatile("s_waitcnt lgkmcnt(" #n ")" ::: "memory")
; #define PG8_BAR __builtin_amdgcn_s_barrier()
; #define PG8_SCHED __builtin_amdgcn_sched_barrier(0)
; template <class Epi, class Sched, bool ALIGN_EPI = false, bool SP2 = false>
; __device__ __forceinline__ void gemm_phase(PG8_LAS unsigned char* lds, const Gemm g, const Sched& S, const Epi& E, int tid_in) {
;     ...
;             PG8_LDA(At, 1, 1); PG8_STAGE(PG8_SB(1, 0), b3, voffB); PG8_STAGE(PG8_SB(1, 1), b3 + hstep, voffB); PG8_STAGE(PG8_SA(1, 0), a3, voffA);
;             PG8_WAIT_V(8); PG8_WAIT_L(0); PG8_BAR; PG8_MMA(1, 0, At, B0); PG8_MMA(1, 1, At, B1); PG8_BAR; PG8_SCHED;
;     ...
;         if constexpr (ALIGN_EPI) { if (wr == 0) PG8_BAR; }
	s_add_i32 s66, s93, s73
	v_lshl_add_u64 v[156:157], v[156:157], 0, s[18:19]
	s_mov_b32 m0, s66
	ds_read_b128 v[190:193], v163 offset:49152
	ds_read_b128 v[194:197], v163 offset:50176
	ds_read_b128 v[198:201], v163 offset:51200
	ds_read_b128 v[202:205], v163 offset:52224
	ds_read_b128 v[206:209], v163 offset:53248
	ds_read_b128 v[210:213], v163 offset:54272
	ds_read_b128 v[216:219], v163 offset:55296
	ds_read_b128 v[220:223], v163 offset:56320
	global_load_lds_dwordx4 v[156:157], off
	s_add_i32 m0, s66, 0x2000
	s_add_u32 s64, s64, 0x40080
	v_lshl_add_u64 v[156:157], v[224:225], 0, s[18:19]
	s_addc_u32 s65, s65, 0
	s_add_i32 s66, s94, s73
	global_load_lds_dwordx4 v[156:157], off
	v_lshl_add_u64 v[156:157], s[64:65], 0, v[130:131]
	s_mov_b32 m0, s66
	s_nop 0
	global_load_lds_dwordx4 v[156:157], off
	v_lshl_add_u64 v[156:157], s[64:65], 0, v[134:135]
	s_add_i32 m0, s66, 0x2000
	s_nop 0
	global_load_lds_dwordx4 v[156:157], off
	v_lshl_add_u64 v[156:157], v[226:227], 0, s[18:19]
	s_mov_b32 m0, s79
	s_nop 0
	global_load_lds_dwordx4 v[156:157], off
	v_lshl_add_u64 v[156:157], v[228:229], 0, s[18:19]
	s_mov_b32 m0, s80
	s_nop 0
	global_load_lds_dwordx4 v[156:157], off
	s_waitcnt vmcnt(8)
	s_waitcnt lgkmcnt(0)
	s_barrier
	s_setprio 1
	s_waitcnt lgkmcnt(0)
	v_mfma_f32_16x16x32_bf16 v[60:63], v[148:151], v[190:193], v[60:63]
	v_mfma_f32_16x16x32_bf16 v[56:59], v[166:169], v[190:193], v[56:59]
	v_mfma_f32_16x16x32_bf16 v[44:47], v[148:151], v[198:201], v[44:47]
	v_mfma_f32_16x16x32_bf16 v[40:43], v[166:169], v[198:201], v[40:43]
	v_mfma_f32_16x16x32_bf16 v[28:31], v[148:151], v[206:209], v[28:31]
	v_mfma_f32_16x16x32_bf16 v[24:27], v[166:169], v[206:209], v[24:27]
	v_mfma_f32_16x16x32_bf16 v[12:15], v[148:151], v[216:219], v[12:15]
	v_mfma_f32_16x16x32_bf16 v[8:11], v[166:169], v[216:219], v[8:11]
	v_mfma_f32_16x16x32_bf16 v[60:63], v[152:155], v[194:197], v[60:63]
	v_mfma_f32_16x16x32_bf16 v[56:59], v[170:173], v[194:197], v[56:59]
	v_mfma_f32_16x16x32_bf16 v[44:47], v[152:155], v[202:205], v[44:47]
	v_mfma_f32_16x16x32_bf16 v[40:43], v[170:173], v[202:205], v[40:43]
	v_mfma_f32_16x16x32_bf16 v[28:31], v[152:155], v[210:213], v[28:31]
	v_mfma_f32_16x16x32_bf16 v[24:27], v[170:173], v[210:213], v[24:27]
	v_mfma_f32_16x16x32_bf16 v[12:15], v[152:155], v[220:223], v[12:15]
	v_mfma_f32_16x16x32_bf16 v[8:11], v[170:173], v[220:223], v[8:11]
	v_mfma_f32_16x16x32_bf16 v[52:55], v[174:177], v[190:193], v[52:55]
	v_mfma_f32_16x16x32_bf16 v[48:51], v[182:185], v[190:193], v[48:51]
	v_mfma_f32_16x16x32_bf16 v[36:39], v[174:177], v[198:201], v[36:39]
	v_mfma_f32_16x16x32_bf16 v[32:35], v[182:185], v[198:201], v[32:35]
	v_mfma_f32_16x16x32_bf16 v[20:23], v[174:177], v[206:209], v[20:23]
	v_mfma_f32_16x16x32_bf16 v[16:19], v[182:185], v[206:209], v[16:19]
	v_mfma_f32_16x16x32_bf16 v[4:7], v[174:177], v[216:219], v[4:7]
	v_mfma_f32_16x16x32_bf16 v[0:3], v[182:185], v[216:219], v[0:3]
	v_mfma_f32_16x16x32_bf16 v[52:55], v[178:181], v[194:197], v[52:55]
	v_mfma_f32_16x16x32_bf16 v[48:51], v[186:189], v[194:197], v[48:51]
	v_mfma_f32_16x16x32_bf16 v[36:39], v[178:181], v[202:205], v[36:39]
	v_mfma_f32_16x16x32_bf16 v[32:35], v[186:189], v[202:205], v[32:35]
	v_mfma_f32_16x16x32_bf16 v[20:23], v[178:181], v[210:213], v[20:23]
	v_mfma_f32_16x16x32_bf16 v[16:19], v[186:189], v[210:213], v[16:19]
	v_mfma_f32_16x16x32_bf16 v[4:7], v[178:181], v[220:223], v[4:7]
	v_mfma_f32_16x16x32_bf16 v[0:3], v[186:189], v[220:223], v[0:3]
	s_setprio 0
	s_barrier
	s_add_i32 s92, s92, 2
	s_add_u32 s62, s62, 0x100
	s_addc_u32 s63, s63, 0
	s_add_u32 s90, s90, 0x100
	s_addc_u32 s91, s91, 0
	s_cmp_gt_u32 s92, 13
	s_cbranch_scc0 .LBB0_352
	s_and_b64 vcc, exec, s[20:21]
	s_cbranch_vccz .LBB0_355
	s_barrier

; #define PG8_STAGE(bufoff, gbase, voff) do { _Pragma("unroll") for (int _i = 0; _i < 2; ++_i) \
;         __builtin_amdgcn_global_load_lds((const unsigned*)((const char*)(gbase) + (voff)[_i]), (PG8_LAS unsigned*)(lds + (bufoff) + ldsw + _i * 8192), 16, 0, 0); } while (0)
; #define PG8_LDA(dst, b, h) do { _Pragma("unroll") for (int m = 0; m < 4; ++m) _Pragma("unroll") for (int k = 0; k < 2; ++k) dst[m][k] = *(const PG8_LAS bf16x8*)(lds + PG8_SA(b, h) + aoff + m * 2048 + k * 1024); } while (0)
; #define PG8_LDB(dst, b, h) do { _Pragma("unroll") for (int n = 0; n < 2; ++n) _Pragma("unroll") for (int k = 0; k < 2; ++k) dst[n][k] = *(const PG8_LAS bf16x8*)(lds + PG8_SB(b, h) + boff + n * 2048 + k * 1024); } while (0)
; #define PG8_MMA(ai, bj, At, Bt) do { __builtin_amdgcn_s_setprio(1); _Pragma("unroll") for (int m = 0; m < 4; ++m) _Pragma("unroll") for (int n = 0; n < 2; ++n) _Pragma("unroll") for (int k = 0; k < 2; ++k) \
;         acc[ai][bj][m][n] = __builtin_amdgcn_mfma_f32_16x16x32_bf16(Bt[n][k], At[m][k], acc[ai][bj][m][n], 0, 0, 0); __builtin_amdgcn_s_setprio(0); } while (0)
; #define PG8_WAIT_V(n) asm volatile("s_waitcnt vmcnt(" #n ")" ::: "memory")
; #define PG8_WAIT_L(n) asm volatile("s_waitcnt lgkmcnt(" #n ")" ::: "memory")
; #define PG8_BAR __builtin_amdgcn_s_barrier()
; #define PG8_SCHED __builtin_amdgcn_sched_barrier(0)
; template <class Epi, class Sched, bool ALIGN_EPI = false, bool SP2 = false>
; __device__ __forceinline__ void gemm_phase(PG8_LAS unsigned char* lds, const Gemm g, const Sched& S, const Epi& E, int tid_in) {
;     ...
;             const bool last = (t == nt - 2);
;             const char* a1 = cA + (size_t)(t + 1) * kstep;
;             const char* a2 = last ? nA : cA + (size_t)(t + 2) * kstep; const char* b2 = last ? nB : cB + (size_t)(t + 2) * kstep;
;             const char* a3 = a2 + kstep; const char* b3 = b2 + kstep;
;             if (last && has_next) S.a_ready(nxt);
;             if constexpr (SP2) {
;             PG8_LDB(B0, 0, 0); PG8_LDB(B1, 0, 1); PG8_SCHED; PG8_LDA(At, 0, 0); PG8_STAGE(PG8_SA(1, 1), a1 + hstep, voffA);
;             PG8_WAIT_V(8); PG8_WAIT_L(0); PG8_BAR; PG8_MMA(0, 0, At, B0); PG8_MMA(0, 1, At, B1); PG8_BAR; PG8_SCHED;
;             PG8_LDA(At, 0, 1); PG8_STAGE(PG8_SB(0, 0), b2, voffB); PG8_STAGE(PG8_SB(0, 1), b2 + hstep, voffB); PG8_STAGE(PG8_SA(0, 0), a2, voffA);
.LBB0_452:
	ds_read_b128 v[104:107], v167
	ds_read_b128 v[108:111], v167 offset:1024
	ds_read_b128 v[154:157], v167 offset:2048
	ds_read_b128 v[158:161], v167 offset:3072
	ds_read_b128 v[170:173], v168
	ds_read_b128 v[174:177], v168 offset:1024
	ds_read_b128 v[178:181], v168 offset:2048
	ds_read_b128 v[182:185], v168 offset:3072
	s_add_u32 s50, s46, 0xfff80080
	s_addc_u32 s51, s47, -1
	s_cmp_eq_u32 s73, 28
	s_cselect_b32 s53, s23, s51
	s_cselect_b32 s52, s67, s50
	s_cselect_b32 s51, s21, s72
	s_cselect_b32 s50, s68, s71
	v_lshl_add_u64 v[162:163], s[46:47], 0, v[146:147]
	s_add_i32 m0, s45, 0xc000
	ds_read_b128 v[186:189], v169
	ds_read_b128 v[190:193], v169 offset:1024
	ds_read_b128 v[194:197], v169 offset:2048
	ds_read_b128 v[198:201], v169 offset:3072
	ds_read_b128 v[202:205], v169 offset:4096
	ds_read_b128 v[206:209], v169 offset:5120
	ds_read_b128 v[210:213], v169 offset:6144
	ds_read_b128 v[216:219], v169 offset:7168
	global_load_lds_dwordx4 v[162:163], off
	v_lshl_add_u64 v[162:163], s[46:47], 0, v[148:149]
	s_add_i32 m0, s45, 0xe000
	s_nop 0
	global_load_lds_dwordx4 v[162:163], off
	s_waitcnt vmcnt(8)
	s_waitcnt lgkmcnt(0)
	s_barrier
	s_setprio 1
	s_waitcnt lgkmcnt(0)
	v_mfma_f32_16x16x32_bf16 v[132:135], v[104:107], v[186:189], v[132:135]
	v_mfma_f32_16x16x32_bf16 v[128:131], v[154:157], v[186:189], v[128:131]
	v_mfma_f32_16x16x32_bf16 v[124:127], v[104:107], v[194:197], v[124:127]
	v_mfma_f32_16x16x32_bf16 v[120:123], v[154:157], v[194:197], v[120:123]
	v_mfma_f32_16x16x32_bf16 v[116:119], v[104:107], v[202:205], v[116:119]
	v_mfma_f32_16x16x32_bf16 v[112:115], v[154:157], v[202:205], v[112:115]
	v_mfma_f32_16x16x32_bf16 v[100:103], v[104:107], v[210:213], v[100:103]
	v_mfma_f32_16x16x32_bf16 v[96:99], v[154:157], v[210:213], v[96:99]
	v_mfma_f32_16x16x32_bf16 v[132:135], v[108:111], v[190:193], v[132:135]
	v_mfma_f32_16x16x32_bf16 v[128:131], v[158:161], v[190:193], v[128:131]
	v_mfma_f32_16x16x32_bf16 v[124:127], v[108:111], v[198:201], v[124:127]
	v_mfma_f32_16x16x32_bf16 v[120:123], v[158:161], v[198:201], v[120:123]
	v_mfma_f32_16x16x32_bf16 v[116:119], v[108:111], v[206:209], v[116:119]
	v_mfma_f32_16x16x32_bf16 v[112:115], v[158:161], v[206:209], v[112:115]
	v_mfma_f32_16x16x32_bf16 v[100:103], v[108:111], v[216:219], v[100:103]
	v_mfma_f32_16x16x32_bf16 v[96:99], v[158:161], v[216:219], v[96:99]
	v_mfma_f32_16x16x32_bf16 v[60:63], v[170:173], v[186:189], v[60:63]
	v_mfma_f32_16x16x32_bf16 v[56:59], v[178:181], v[186:189], v[56:59]
	v_mfma_f32_16x16x32_bf16 v[52:55], v[170:173], v[194:197], v[52:55]
	v_mfma_f32_16x16x32_bf16 v[48:51], v[178:181], v[194:197], v[48:51]
	v_mfma_f32_16x16x32_bf16 v[44:47], v[170:173], v[202:205], v[44:47]
	v_mfma_f32_16x16x32_bf16 v[40:43], v[178:181], v[202:205], v[40:43]
	v_mfma_f32_16x16x32_bf16 v[36:39], v[170:173], v[210:213], v[36:39]
	v_mfma_f32_16x16x32_bf16 v[32:35], v[178:181], v[210:213], v[32:35]
	v_mfma_f32_16x16x32_bf16 v[60:63], v[174:177], v[190:193], v[60:63]
	v_mfma_f32_16x16x32_bf16 v[56:59], v[182:185], v[190:193], v[56:59]
	v_mfma_f32_16x16x32_bf16 v[52:55], v[174:177], v[198:201], v[52:55]
	v_mfma_f32_16x16x32_bf16 v[48:51], v[182:185], v[198:201], v[48:51]
	v_mfma_f32_16x16x32_bf16 v[44:47], v[174:177], v[206:209], v[44:47]
	v_mfma_f32_16x16x32_bf16 v[40:43], v[182:185], v[206:209], v[40:43]
	v_mfma_f32_16x16x32_bf16 v[36:39], v[174:177], v[216:219], v[36:39]
	v_mfma_f32_16x16x32_bf16 v[32:35], v[182:185], v[216:219], v[32:35]
	s_setprio 0
	s_barrier
	s_add_i32 s74, s64, s56
	v_lshl_add_u64 v[162:163], s[50:51], 0, v[140:141]
	s_mov_b32 m0, s74
	ds_read_b128 v[186:189], v169 offset:16384
	ds_read_b128 v[190:193], v169 offset:17408
	ds_read_b128 v[194:197], v169 offset:18432
	ds_read_b128 v[198:201], v169 offset:19456
	ds_read_b128 v[202:205], v169 offset:20480
	ds_read_b128 v[206:209], v169 offset:21504
	ds_read_b128 v[210:213], v169 offset:22528
	ds_read_b128 v[216:219], v169 offset:23552
	global_load_lds_dwordx4 v[162:163], off
	s_add_i32 m0, s74, 0x2000
	s_add_u32 s74, s50, 0x80000
	v_lshl_add_u64 v[220:221], s[50:51], 0, v[144:145]
	s_addc_u32 s75, s51, 0
	s_add_i32 s76, s65, s56
	global_load_lds_dwordx4 v[220:221], off
	v_lshl_add_u64 v[222:223], s[74:75], 0, v[140:141]
	s_mov_b32 m0, s76
	v_lshl_add_u64 v[224:225], s[52:53], 0, v[142:143]
	global_load_lds_dwordx4 v[222:223], off
	v_lshl_add_u64 v[222:223], s[74:75], 0, v[144:145]
	s_add_i32 m0, s76, 0x2000
	s_nop 0
	global_load_lds_dwordx4 v[222:223], off
	v_lshl_add_u64 v[222:223], s[52:53], 0, v[138:139]
	s_mov_b32 m0, s45
	s_nop 0
	global_load_lds_dwordx4 v[222:223], off
	s_mov_b32 m0, s57
	s_nop 0
	global_load_lds_dwordx4 v[224:225], off
	s_waitcnt vmcnt(8)
	s_waitcnt lgkmcnt(0)
	s_barrier
; #define PG8_STAGE(bufoff, gbase, voff) do { _Pragma("unroll") for (int _i = 0; _i < 2; ++_i) \
;         __builtin_amdgcn_global_load_lds((const unsigned*)((const char*)(gbase) + (voff)[_i]), (PG8_LAS unsigned*)(lds + (bufoff) + ldsw + _i * 8192), 16, 0, 0); } while (0)
; #define PG8_LDA(dst, b, h) do { _Pragma("unroll") for (int m = 0; m < 4; ++m) _Pragma("unroll") for (int k = 0; k < 2; ++k) dst[m][k] = *(const PG8_LAS bf16x8*)(lds + PG8_SA(b, h) + aoff + m * 2048 + k * 1024); } while (0)
; #define PG8_LDB(dst, b, h) do { _Pragma("unroll") for (int n = 0; n < 2; ++n) _Pragma("unroll") for (int k = 0; k < 2; ++k) dst[n][k] = *(const PG8_LAS bf16x8*)(lds + PG8_SB(b, h) + boff + n * 2048 + k * 1024); } while (0)
; #define PG8_MMA(ai, bj, At, Bt) do { __builtin_amdgcn_s_setprio(1); _Pragma("unroll") for (int m = 0; m < 4; ++m) _Pragma("unroll") for (int n = 0; n < 2; ++n) _Pragma("unroll") for (int k = 0; k < 2; ++k) \
;         acc[ai][bj][m][n] = __builtin_amdgcn_mfma_f32_16x16x32_bf16(Bt[n][k], At[m][k], acc[ai][bj][m][n], 0, 0, 0); __builtin_amdgcn_s_setprio(0); } while (0)
; #define PG8_WAIT_V(n) asm volatile("s_waitcnt vmcnt(" #n ")" ::: "memory")
; #define PG8_WAIT_L(n) asm volatile("s_waitcnt lgkmcnt(" #n ")" ::: "memory")
; #define PG8_BAR __builtin_amdgcn_s_barrier()
; #define PG8_SCHED __builtin_amdgcn_sched_barrier(0)
; template <class Epi, class Sched, bool ALIGN_EPI = false, bool SP2 = false>
; __device__ __forceinline__ void gemm_phase(PG8_LAS unsigned char* lds, const Gemm g, const Sched& S, const Epi& E, int tid_in) {
;     ...
;             PG8_WAIT_V(8); PG8_WAIT_L(0); PG8_BAR; PG8_MMA(1, 0, At, B0); PG8_MMA(1, 1, At, B1); PG8_BAR; PG8_SCHED;
;             PG8_LDB(B0, 1, 0); PG8_LDB(B1, 1, 1); PG8_SCHED; PG8_LDA(At, 1, 0); PG8_STAGE(PG8_SA(0, 1), a2 + hstep, voffA);
;             PG8_WAIT_V(8); PG8_WAIT_L(0); PG8_BAR; PG8_MMA(0, 0, At, B0); PG8_MMA(0, 1, At, B1); PG8_BAR; PG8_SCHED;
	s_setprio 1
	s_waitcnt lgkmcnt(0)
	v_mfma_f32_16x16x32_bf16 v[92:95], v[104:107], v[186:189], v[92:95]
	v_mfma_f32_16x16x32_bf16 v[88:91], v[154:157], v[186:189], v[88:91]
	v_mfma_f32_16x16x32_bf16 v[84:87], v[104:107], v[194:197], v[84:87]
	v_mfma_f32_16x16x32_bf16 v[80:83], v[154:157], v[194:197], v[80:83]
	v_mfma_f32_16x16x32_bf16 v[76:79], v[104:107], v[202:205], v[76:79]
	v_mfma_f32_16x16x32_bf16 v[72:75], v[154:157], v[202:205], v[72:75]
	v_mfma_f32_16x16x32_bf16 v[68:71], v[104:107], v[210:213], v[68:71]
	v_mfma_f32_16x16x32_bf16 v[64:67], v[154:157], v[210:213], v[64:67]
	v_mfma_f32_16x16x32_bf16 v[92:95], v[108:111], v[190:193], v[92:95]
	v_mfma_f32_16x16x32_bf16 v[88:91], v[158:161], v[190:193], v[88:91]
	v_mfma_f32_16x16x32_bf16 v[84:87], v[108:111], v[198:201], v[84:87]
	v_mfma_f32_16x16x32_bf16 v[80:83], v[158:161], v[198:201], v[80:83]
	v_mfma_f32_16x16x32_bf16 v[76:79], v[108:111], v[206:209], v[76:79]
	v_mfma_f32_16x16x32_bf16 v[72:75], v[158:161], v[206:209], v[72:75]
	v_mfma_f32_16x16x32_bf16 v[68:71], v[108:111], v[216:219], v[68:71]
	v_mfma_f32_16x16x32_bf16 v[64:67], v[158:161], v[216:219], v[64:67]
	v_mfma_f32_16x16x32_bf16 v[28:31], v[170:173], v[186:189], v[28:31]
	v_mfma_f32_16x16x32_bf16 v[24:27], v[178:181], v[186:189], v[24:27]
	v_mfma_f32_16x16x32_bf16 v[20:23], v[170:173], v[194:197], v[20:23]
	v_mfma_f32_16x16x32_bf16 v[16:19], v[178:181], v[194:197], v[16:19]
	v_mfma_f32_16x16x32_bf16 v[12:15], v[170:173], v[202:205], v[12:15]
	v_mfma_f32_16x16x32_bf16 v[8:11], v[178:181], v[202:205], v[8:11]
	v_mfma_f32_16x16x32_bf16 v[4:7], v[170:173], v[210:213], v[4:7]
	v_mfma_f32_16x16x32_bf16 v[0:3], v[178:181], v[210:213], v[0:3]
	v_mfma_f32_16x16x32_bf16 v[28:31], v[174:177], v[190:193], v[28:31]
	v_mfma_f32_16x16x32_bf16 v[24:27], v[182:185], v[190:193], v[24:27]
	v_mfma_f32_16x16x32_bf16 v[20:23], v[174:177], v[198:201], v[20:23]
	v_mfma_f32_16x16x32_bf16 v[16:19], v[182:185], v[198:201], v[16:19]
	v_mfma_f32_16x16x32_bf16 v[12:15], v[174:177], v[206:209], v[12:15]
	v_mfma_f32_16x16x32_bf16 v[8:11], v[182:185], v[206:209], v[8:11]
	v_mfma_f32_16x16x32_bf16 v[4:7], v[174:177], v[216:219], v[4:7]
	v_mfma_f32_16x16x32_bf16 v[0:3], v[182:185], v[216:219], v[0:3]
	s_setprio 0
	s_barrier
	s_add_i32 s74, 0, 0x18000
	s_add_i32 s75, 0, 0x1c000
	v_add_u32_e32 v158, s74, v165
	v_add_u32_e32 v182, s75, v165
	ds_read_b128 v[104:107], v158
	ds_read_b128 v[108:111], v158 offset:1024
	ds_read_b128 v[154:157], v158 offset:2048
	ds_read_b128 v[158:161], v158 offset:3072
	ds_read_b128 v[170:173], v182
	ds_read_b128 v[174:177], v182 offset:1024
	ds_read_b128 v[178:181], v182 offset:2048
	ds_read_b128 v[182:185], v182 offset:3072
	s_add_u32 s52, s52, 0x80000
	s_addc_u32 s53, s53, 0
	s_mov_b32 m0, s58
	v_lshl_add_u64 v[226:227], s[52:53], 0, v[138:139]
	ds_read_b128 v[186:189], v169 offset:32768
	ds_read_b128 v[190:193], v169 offset:33792
	ds_read_b128 v[194:197], v169 offset:34816
	ds_read_b128 v[198:201], v169 offset:35840
	ds_read_b128 v[202:205], v169 offset:36864
	ds_read_b128 v[206:209], v169 offset:37888
	ds_read_b128 v[210:213], v169 offset:38912
	ds_read_b128 v[216:219], v169 offset:39936
	global_load_lds_dwordx4 v[226:227], off
	v_lshl_add_u64 v[226:227], s[52:53], 0, v[142:143]
	s_mov_b32 m0, s59
	s_nop 0
	global_load_lds_dwordx4 v[226:227], off
	s_waitcnt vmcnt(8)
	s_waitcnt lgkmcnt(0)
	s_barrier
	s_setprio 1
	s_waitcnt lgkmcnt(0)
	v_mfma_f32_16x16x32_bf16 v[132:135], v[104:107], v[186:189], v[132:135]
	v_mfma_f32_16x16x32_bf16 v[128:131], v[154:157], v[186:189], v[128:131]
	v_mfma_f32_16x16x32_bf16 v[124:127], v[104:107], v[194:197], v[124:127]
	v_mfma_f32_16x16x32_bf16 v[120:123], v[154:157], v[194:197], v[120:123]
	v_mfma_f32_16x16x32_bf16 v[116:119], v[104:107], v[202:205], v[116:119]
	v_mfma_f32_16x16x32_bf16 v[112:115], v[154:157], v[202:205], v[112:115]
	v_mfma_f32_16x16x32_bf16 v[100:103], v[104:107], v[210:213], v[100:103]
	v_mfma_f32_16x16x32_bf16 v[96:99], v[154:157], v[210:213], v[96:99]
	v_mfma_f32_16x16x32_bf16 v[132:135], v[108:111], v[190:193], v[132:135]
	v_mfma_f32_16x16x32_bf16 v[128:131], v[158:161], v[190:193], v[128:131]
	v_mfma_f32_16x16x32_bf16 v[124:127], v[108:111], v[198:201], v[124:127]
	v_mfma_f32_16x16x32_bf16 v[120:123], v[158:161], v[198:201], v[120:123]
	v_mfma_f32_16x16x32_bf16 v[116:119], v[108:111], v[206:209], v[116:119]
	v_mfma_f32_16x16x32_bf16 v[112:115], v[158:161], v[206:209], v[112:115]
	v_mfma_f32_16x16x32_bf16 v[100:103], v[108:111], v[216:219], v[100:103]
	v_mfma_f32_16x16x32_bf16 v[96:99], v[158:161], v[216:219], v[96:99]
	v_mfma_f32_16x16x32_bf16 v[60:63], v[170:173], v[186:189], v[60:63]
	v_mfma_f32_16x16x32_bf16 v[56:59], v[178:181], v[186:189], v[56:59]
	v_mfma_f32_16x16x32_bf16 v[52:55], v[170:173], v[194:197], v[52:55]
	v_mfma_f32_16x16x32_bf16 v[48:51], v[178:181], v[194:197], v[48:51]
	v_mfma_f32_16x16x32_bf16 v[44:47], v[170:173], v[202:205], v[44:47]
	v_mfma_f32_16x16x32_bf16 v[40:43], v[178:181], v[202:205], v[40:43]
	v_mfma_f32_16x16x32_bf16 v[36:39], v[170:173], v[210:213], v[36:39]
	v_mfma_f32_16x16x32_bf16 v[32:35], v[178:181], v[210:213], v[32:35]
	v_mfma_f32_16x16x32_bf16 v[60:63], v[174:177], v[190:193], v[60:63]
	v_mfma_f32_16x16x32_bf16 v[56:59], v[182:185], v[190:193], v[56:59]
	v_mfma_f32_16x16x32_bf16 v[52:55], v[174:177], v[198:201], v[52:55]
	v_mfma_f32_16x16x32_bf16 v[48:51], v[182:185], v[198:201], v[48:51]
	v_mfma_f32_16x16x32_bf16 v[44:47], v[174:177], v[206:209], v[44:47]
	v_mfma_f32_16x16x32_bf16 v[40:43], v[182:185], v[206:209], v[40:43]
	v_mfma_f32_16x16x32_bf16 v[36:39], v[174:177], v[216:219], v[36:39]
	v_mfma_f32_16x16x32_bf16 v[32:35], v[182:185], v[216:219], v[32:35]
	s_setprio 0
	s_barrier
; #define PG8_STAGE(bufoff, gbase, voff) do { _Pragma("unroll") for (int _i = 0; _i < 2; ++_i) \
;         __builtin_amdgcn_global_load_lds((const unsigned*)((const char*)(gbase) + (voff)[_i]), (PG8_LAS unsigned*)(lds + (bufoff) + ldsw + _i * 8192), 16, 0, 0); } while (0)
; #define PG8_LDA(dst, b, h) do { _Pragma("unroll") for (int m = 0; m < 4; ++m) _Pragma("unroll") for (int k = 0; k < 2; ++k) dst[m][k] = *(const PG8_LAS bf16x8*)(lds + PG8_SA(b, h) + aoff + m * 2048 + k * 1024); } while (0)
; #define PG8_MMA(ai, bj, At, Bt) do { __builtin_amdgcn_s_setprio(1); _Pragma("unroll") for (int m = 0; m < 4; ++m) _Pragma("unroll") for (int n = 0; n < 2; ++n) _Pragma("unroll") for (int k = 0; k < 2; ++k) \
;         acc[ai][bj][m][n] = __builtin_amdgcn_mfma_f32_16x16x32_bf16(Bt[n][k], At[m][k], acc[ai][bj][m][n], 0, 0, 0); __builtin_amdgcn_s_setprio(0); } while (0)
; #define PG8_WAIT_V(n) asm volatile("s_waitcnt vmcnt(" #n ")" ::: "memory")
; #define PG8_WAIT_L(n) asm volatile("s_waitcnt lgkmcnt(" #n ")" ::: "memory")
; #define PG8_BAR __builtin_amdgcn_s_barrier()
; #define PG8_SCHED __builtin_amdgcn_sched_barrier(0)
; template <class Epi, class Sched, bool ALIGN_EPI = false, bool SP2 = false>
; __device__ __forceinline__ void gemm_phase(PG8_LAS unsigned char* lds, const Gemm g, const Sched& S, const Epi& E, int tid_in) {
;     ...
;             PG8_LDA(At, 1, 1); PG8_STAGE(PG8_SB(1, 0), b3, voffB); PG8_STAGE(PG8_SB(1, 1), b3 + hstep, voffB); PG8_STAGE(PG8_SA(1, 0), a3, voffA);
;             PG8_WAIT_V(8); PG8_WAIT_L(0); PG8_BAR; PG8_MMA(1, 0, At, B0); PG8_MMA(1, 1, At, B1); PG8_BAR; PG8_SCHED;
;     ...
;         if constexpr (ALIGN_EPI) { if (wr == 0) PG8_BAR; }
	s_add_i32 s52, s74, s56
	v_lshl_add_u64 v[162:163], v[162:163], 0, s[8:9]
	s_mov_b32 m0, s52
	ds_read_b128 v[186:189], v169 offset:49152
	ds_read_b128 v[190:193], v169 offset:50176
	ds_read_b128 v[194:197], v169 offset:51200
	ds_read_b128 v[198:201], v169 offset:52224
	ds_read_b128 v[202:205], v169 offset:53248
	ds_read_b128 v[206:209], v169 offset:54272
	ds_read_b128 v[210:213], v169 offset:55296
	ds_read_b128 v[216:219], v169 offset:56320
	global_load_lds_dwordx4 v[162:163], off
	s_add_i32 m0, s52, 0x2000
	s_add_u32 s50, s50, 0x80080
	v_lshl_add_u64 v[162:163], v[220:221], 0, s[8:9]
	s_addc_u32 s51, s51, 0
	s_add_i32 s52, s75, s56
	global_load_lds_dwordx4 v[162:163], off
	v_lshl_add_u64 v[162:163], s[50:51], 0, v[140:141]
	s_mov_b32 m0, s52
	s_nop 0
	global_load_lds_dwordx4 v[162:163], off
	v_lshl_add_u64 v[162:163], s[50:51], 0, v[144:145]
	s_add_i32 m0, s52, 0x2000
	s_nop 0
	global_load_lds_dwordx4 v[162:163], off
	v_lshl_add_u64 v[162:163], v[222:223], 0, s[8:9]
	s_mov_b32 m0, s61
	s_nop 0
	global_load_lds_dwordx4 v[162:163], off
	v_lshl_add_u64 v[162:163], v[224:225], 0, s[8:9]
	s_mov_b32 m0, s62
	s_nop 0
	global_load_lds_dwordx4 v[162:163], off
	s_waitcnt vmcnt(8)
	s_waitcnt lgkmcnt(0)
	s_barrier
	s_setprio 1
	s_waitcnt lgkmcnt(0)
	v_mfma_f32_16x16x32_bf16 v[92:95], v[104:107], v[186:189], v[92:95]
	v_mfma_f32_16x16x32_bf16 v[88:91], v[154:157], v[186:189], v[88:91]
	v_mfma_f32_16x16x32_bf16 v[84:87], v[104:107], v[194:197], v[84:87]
	v_mfma_f32_16x16x32_bf16 v[80:83], v[154:157], v[194:197], v[80:83]
	v_mfma_f32_16x16x32_bf16 v[76:79], v[104:107], v[202:205], v[76:79]
	v_mfma_f32_16x16x32_bf16 v[72:75], v[154:157], v[202:205], v[72:75]
	v_mfma_f32_16x16x32_bf16 v[68:71], v[104:107], v[210:213], v[68:71]
	v_mfma_f32_16x16x32_bf16 v[64:67], v[154:157], v[210:213], v[64:67]
	v_mfma_f32_16x16x32_bf16 v[92:95], v[108:111], v[190:193], v[92:95]
	v_mfma_f32_16x16x32_bf16 v[88:91], v[158:161], v[190:193], v[88:91]
	v_mfma_f32_16x16x32_bf16 v[84:87], v[108:111], v[198:201], v[84:87]
	v_mfma_f32_16x16x32_bf16 v[80:83], v[158:161], v[198:201], v[80:83]
	v_mfma_f32_16x16x32_bf16 v[76:79], v[108:111], v[206:209], v[76:79]
	v_mfma_f32_16x16x32_bf16 v[72:75], v[158:161], v[206:209], v[72:75]
	v_mfma_f32_16x16x32_bf16 v[68:71], v[108:111], v[216:219], v[68:71]
	v_mfma_f32_16x16x32_bf16 v[64:67], v[158:161], v[216:219], v[64:67]
	v_mfma_f32_16x16x32_bf16 v[28:31], v[170:173], v[186:189], v[28:31]
	v_mfma_f32_16x16x32_bf16 v[24:27], v[178:181], v[186:189], v[24:27]
	v_mfma_f32_16x16x32_bf16 v[20:23], v[170:173], v[194:197], v[20:23]
	v_mfma_f32_16x16x32_bf16 v[16:19], v[178:181], v[194:197], v[16:19]
	v_mfma_f32_16x16x32_bf16 v[12:15], v[170:173], v[202:205], v[12:15]
	v_mfma_f32_16x16x32_bf16 v[8:11], v[178:181], v[202:205], v[8:11]
	v_mfma_f32_16x16x32_bf16 v[4:7], v[170:173], v[210:213], v[4:7]
	v_mfma_f32_16x16x32_bf16 v[0:3], v[178:181], v[210:213], v[0:3]
	v_mfma_f32_16x16x32_bf16 v[28:31], v[174:177], v[190:193], v[28:31]
	v_mfma_f32_16x16x32_bf16 v[24:27], v[182:185], v[190:193], v[24:27]
	v_mfma_f32_16x16x32_bf16 v[20:23], v[174:177], v[198:201], v[20:23]
	v_mfma_f32_16x16x32_bf16 v[16:19], v[182:185], v[198:201], v[16:19]
	v_mfma_f32_16x16x32_bf16 v[12:15], v[174:177], v[206:209], v[12:15]
	v_mfma_f32_16x16x32_bf16 v[8:11], v[182:185], v[206:209], v[8:11]
	v_mfma_f32_16x16x32_bf16 v[4:7], v[174:177], v[216:219], v[4:7]
	v_mfma_f32_16x16x32_bf16 v[0:3], v[182:185], v[216:219], v[0:3]
	s_setprio 0
	s_barrier
	s_add_i32 s73, s73, 2
	s_add_u32 s46, s46, 0x100
	s_addc_u32 s47, s47, 0
	s_add_u32 s71, s71, 0x100
	s_addc_u32 s72, s72, 0
	s_cmp_gt_u32 s73, 29
	s_cbranch_scc0 .LBB0_452
	s_and_b64 vcc, exec, s[10:11]
	s_cbranch_vccz .LBB0_455
	s_barrier

; #define PG8_STAGE(bufoff, gbase, voff) do { _Pragma("unroll") for (int _i = 0; _i < 2; ++_i) \
;         __builtin_amdgcn_global_load_lds((const unsigned*)((const char*)(gbase) + (voff)[_i]), (PG8_LAS unsigned*)(lds + (bufoff) + ldsw + _i * 8192), 16, 0, 0); } while (0)
; #define PG8_LDA(dst, b, h) do { _Pragma("unroll") for (int m = 0; m < 4; ++m) _Pragma("unroll") for (int k = 0; k < 2; ++k) dst[m][k] = *(const PG8_LAS bf16x8*)(lds + PG8_SA(b, h) + aoff + m * 2048 + k * 1024); } while (0)
; #define PG8_LDB(dst, b, h) do { _Pragma("unroll") for (int n = 0; n < 2; ++n) _Pragma("unroll") for (int k = 0; k < 2; ++k) dst[n][k] = *(const PG8_LAS bf16x8*)(lds + PG8_SB(b, h) + boff + n * 2048 + k * 1024); } while (0)
; #define PG8_MMA(ai, bj, At, Bt) do { __builtin_amdgcn_s_setprio(1); _Pragma("unroll") for (int m = 0; m < 4; ++m) _Pragma("unroll") for (int n = 0; n < 2; ++n) _Pragma("unroll") for (int k = 0; k < 2; ++k) \
;         acc[ai][bj][m][n] = __builtin_amdgcn_mfma_f32_16x16x32_bf16(Bt[n][k], At[m][k], acc[ai][bj][m][n], 0, 0, 0); __builtin_amdgcn_s_setprio(0); } while (0)
; #define PG8_WAIT_V(n) asm volatile("s_waitcnt vmcnt(" #n ")" ::: "memory")
; #define PG8_WAIT_L(n) asm volatile("s_waitcnt lgkmcnt(" #n ")" ::: "memory")
; #define PG8_BAR __builtin_amdgcn_s_barrier()
; #define PG8_SCHED __builtin_amdgcn_sched_barrier(0)
; template <class Epi, class Sched, bool ALIGN_EPI = false, bool SP2 = false>
; __device__ __forceinline__ void gemm_phase(PG8_LAS unsigned char* lds, const Gemm g, const Sched& S, const Epi& E, int tid_in) {
;     ...
;             const bool last = (t == nt - 2);
;             const char* a1 = cA + (size_t)(t + 1) * kstep;
;             const char* a2 = last ? nA : cA + (size_t)(t + 2) * kstep; const char* b2 = last ? nB : cB + (size_t)(t + 2) * kstep;
;             const char* a3 = a2 + kstep; const char* b3 = b2 + kstep;
;             if (last && has_next) S.a_ready(nxt);
;             if constexpr (SP2) {
;             PG8_LDB(B0, 0, 0); PG8_LDB(B1, 0, 1); PG8_SCHED; PG8_LDA(At, 0, 0); PG8_STAGE(PG8_SA(1, 1), a1 + hstep, voffA);
;             PG8_WAIT_V(8); PG8_WAIT_L(0); PG8_BAR; PG8_MMA(0, 0, At, B0); PG8_MMA(0, 1, At, B1); PG8_BAR; PG8_SCHED;
;             PG8_LDA(At, 0, 1); PG8_STAGE(PG8_SB(0, 0), b2, voffB); PG8_STAGE(PG8_SB(0, 1), b2 + hstep, voffB); PG8_STAGE(PG8_SA(0, 0), a2, voffA);
.LBB0_484:
	ds_read_b128 v[144:147], v153
	ds_read_b128 v[156:159], v153 offset:1024
	ds_read_b128 v[160:163], v153 offset:2048
	ds_read_b128 v[164:167], v153 offset:3072
	ds_read_b128 v[168:171], v154
	ds_read_b128 v[172:175], v154 offset:1024
	ds_read_b128 v[176:179], v154 offset:2048
	ds_read_b128 v[180:183], v154 offset:3072
	s_add_u32 s38, s36, 0xfff80080
	s_addc_u32 s39, s37, -1
	s_cmp_eq_u32 s59, 28
	s_cselect_b32 s41, s21, s39
	s_cselect_b32 s40, s55, s38
	s_cselect_b32 s39, s19, s58
	s_cselect_b32 s38, s56, s57
	v_lshl_add_u64 v[148:149], s[36:37], 0, v[136:137]
	s_add_i32 m0, s31, 0xc000
	ds_read_b128 v[184:187], v155
	ds_read_b128 v[188:191], v155 offset:1024
	ds_read_b128 v[192:195], v155 offset:2048
	ds_read_b128 v[196:199], v155 offset:3072
	ds_read_b128 v[200:203], v155 offset:4096
	ds_read_b128 v[204:207], v155 offset:5120
	ds_read_b128 v[208:211], v155 offset:6144
	ds_read_b128 v[212:215], v155 offset:7168
	global_load_lds_dwordx4 v[148:149], off
	v_lshl_add_u64 v[148:149], s[36:37], 0, v[138:139]
	s_add_i32 m0, s31, 0xe000
	s_nop 0
	global_load_lds_dwordx4 v[148:149], off
	s_waitcnt vmcnt(8)
	s_waitcnt lgkmcnt(0)
	s_barrier
	s_setprio 1
	s_waitcnt lgkmcnt(0)
	v_mfma_f32_16x16x32_bf16 v[124:127], v[144:147], v[184:187], v[124:127]
	v_mfma_f32_16x16x32_bf16 v[120:123], v[160:163], v[184:187], v[120:123]
	v_mfma_f32_16x16x32_bf16 v[108:111], v[144:147], v[192:195], v[108:111]
	v_mfma_f32_16x16x32_bf16 v[104:107], v[160:163], v[192:195], v[104:107]
	v_mfma_f32_16x16x32_bf16 v[92:95], v[144:147], v[200:203], v[92:95]
	v_mfma_f32_16x16x32_bf16 v[88:91], v[160:163], v[200:203], v[88:91]
	v_mfma_f32_16x16x32_bf16 v[76:79], v[144:147], v[208:211], v[76:79]
	v_mfma_f32_16x16x32_bf16 v[72:75], v[160:163], v[208:211], v[72:75]
	v_mfma_f32_16x16x32_bf16 v[124:127], v[156:159], v[188:191], v[124:127]
	v_mfma_f32_16x16x32_bf16 v[120:123], v[164:167], v[188:191], v[120:123]
	v_mfma_f32_16x16x32_bf16 v[108:111], v[156:159], v[196:199], v[108:111]
	v_mfma_f32_16x16x32_bf16 v[104:107], v[164:167], v[196:199], v[104:107]
	v_mfma_f32_16x16x32_bf16 v[92:95], v[156:159], v[204:207], v[92:95]
	v_mfma_f32_16x16x32_bf16 v[88:91], v[164:167], v[204:207], v[88:91]
	v_mfma_f32_16x16x32_bf16 v[76:79], v[156:159], v[212:215], v[76:79]
	v_mfma_f32_16x16x32_bf16 v[72:75], v[164:167], v[212:215], v[72:75]
	v_mfma_f32_16x16x32_bf16 v[116:119], v[168:171], v[184:187], v[116:119]
	v_mfma_f32_16x16x32_bf16 v[112:115], v[176:179], v[184:187], v[112:115]
	v_mfma_f32_16x16x32_bf16 v[100:103], v[168:171], v[192:195], v[100:103]
	v_mfma_f32_16x16x32_bf16 v[96:99], v[176:179], v[192:195], v[96:99]
	v_mfma_f32_16x16x32_bf16 v[84:87], v[168:171], v[200:203], v[84:87]
	v_mfma_f32_16x16x32_bf16 v[80:83], v[176:179], v[200:203], v[80:83]
	v_mfma_f32_16x16x32_bf16 v[68:71], v[168:171], v[208:211], v[68:71]
	v_mfma_f32_16x16x32_bf16 v[64:67], v[176:179], v[208:211], v[64:67]
	v_mfma_f32_16x16x32_bf16 v[116:119], v[172:175], v[188:191], v[116:119]
	v_mfma_f32_16x16x32_bf16 v[112:115], v[180:183], v[188:191], v[112:115]
	v_mfma_f32_16x16x32_bf16 v[100:103], v[172:175], v[196:199], v[100:103]
	v_mfma_f32_16x16x32_bf16 v[96:99], v[180:183], v[196:199], v[96:99]
	v_mfma_f32_16x16x32_bf16 v[84:87], v[172:175], v[204:207], v[84:87]
	v_mfma_f32_16x16x32_bf16 v[80:83], v[180:183], v[204:207], v[80:83]
	v_mfma_f32_16x16x32_bf16 v[68:71], v[172:175], v[212:215], v[68:71]
	v_mfma_f32_16x16x32_bf16 v[64:67], v[180:183], v[212:215], v[64:67]
	s_setprio 0
	s_barrier
	s_add_i32 s60, s52, s44
	v_lshl_add_u64 v[148:149], s[38:39], 0, v[130:131]
	s_mov_b32 m0, s60
	ds_read_b128 v[184:187], v155 offset:16384
	ds_read_b128 v[188:191], v155 offset:17408
	ds_read_b128 v[192:195], v155 offset:18432
	ds_read_b128 v[196:199], v155 offset:19456
	ds_read_b128 v[200:203], v155 offset:20480
	ds_read_b128 v[204:207], v155 offset:21504
	ds_read_b128 v[208:211], v155 offset:22528
	ds_read_b128 v[212:215], v155 offset:23552
	global_load_lds_dwordx4 v[148:149], off
	s_add_i32 m0, s60, 0x2000
	s_add_u32 s60, s38, 0x80000
	v_lshl_add_u64 v[216:217], s[38:39], 0, v[134:135]
	s_addc_u32 s61, s39, 0
	s_add_i32 s62, s53, s44
	global_load_lds_dwordx4 v[216:217], off
	v_lshl_add_u64 v[218:219], s[60:61], 0, v[130:131]
	s_mov_b32 m0, s62
	v_lshl_add_u64 v[220:221], s[40:41], 0, v[132:133]
	global_load_lds_dwordx4 v[218:219], off
	v_lshl_add_u64 v[218:219], s[60:61], 0, v[134:135]
	s_add_i32 m0, s62, 0x2000
	s_nop 0
	global_load_lds_dwordx4 v[218:219], off
	v_lshl_add_u64 v[218:219], s[40:41], 0, v[128:129]
	s_mov_b32 m0, s31
	s_nop 0
	global_load_lds_dwordx4 v[218:219], off
	s_mov_b32 m0, s45
	s_nop 0
	global_load_lds_dwordx4 v[220:221], off
	s_waitcnt vmcnt(8)
	s_waitcnt lgkmcnt(0)
	s_barrier
; #define PG8_STAGE(bufoff, gbase, voff) do { _Pragma("unroll") for (int _i = 0; _i < 2; ++_i) \
;         __builtin_amdgcn_global_load_lds((const unsigned*)((const char*)(gbase) + (voff)[_i]), (PG8_LAS unsigned*)(lds + (bufoff) + ldsw + _i * 8192), 16, 0, 0); } while (0)
; #define PG8_LDA(dst, b, h) do { _Pragma("unroll") for (int m = 0; m < 4; ++m) _Pragma("unroll") for (int k = 0; k < 2; ++k) dst[m][k] = *(const PG8_LAS bf16x8*)(lds + PG8_SA(b, h) + aoff + m * 2048 + k * 1024); } while (0)
; #define PG8_LDB(dst, b, h) do { _Pragma("unroll") for (int n = 0; n < 2; ++n) _Pragma("unroll") for (int k = 0; k < 2; ++k) dst[n][k] = *(const PG8_LAS bf16x8*)(lds + PG8_SB(b, h) + boff + n * 2048 + k * 1024); } while (0)
; #define PG8_MMA(ai, bj, At, Bt) do { __builtin_amdgcn_s_setprio(1); _Pragma("unroll") for (int m = 0; m < 4; ++m) _Pragma("unroll") for (int n = 0; n < 2; ++n) _Pragma("unroll") for (int k = 0; k < 2; ++k) \
;         acc[ai][bj][m][n] = __builtin_amdgcn_mfma_f32_16x16x32_bf16(Bt[n][k], At[m][k], acc[ai][bj][m][n], 0, 0, 0); __builtin_amdgcn_s_setprio(0); } while (0)
; #define PG8_WAIT_V(n) asm volatile("s_waitcnt vmcnt(" #n ")" ::: "memory")
; #define PG8_WAIT_L(n) asm volatile("s_waitcnt lgkmcnt(" #n ")" ::: "memory")
; #define PG8_BAR __builtin_amdgcn_s_barrier()
; #define PG8_SCHED __builtin_amdgcn_sched_barrier(0)
; template <class Epi, class Sched, bool ALIGN_EPI = false, bool SP2 = false>
; __device__ __forceinline__ void gemm_phase(PG8_LAS unsigned char* lds, const Gemm g, const Sched& S, const Epi& E, int tid_in) {
;     ...
;             PG8_WAIT_V(8); PG8_WAIT_L(0); PG8_BAR; PG8_MMA(1, 0, At, B0); PG8_MMA(1, 1, At, B1); PG8_BAR; PG8_SCHED;
;             PG8_LDB(B0, 1, 0); PG8_LDB(B1, 1, 1); PG8_SCHED; PG8_LDA(At, 1, 0); PG8_STAGE(PG8_SA(0, 1), a2 + hstep, voffA);
;             PG8_WAIT_V(8); PG8_WAIT_L(0); PG8_BAR; PG8_MMA(0, 0, At, B0); PG8_MMA(0, 1, At, B1); PG8_BAR; PG8_SCHED;
	s_setprio 1
	s_waitcnt lgkmcnt(0)
	v_mfma_f32_16x16x32_bf16 v[60:63], v[144:147], v[184:187], v[60:63]
	v_mfma_f32_16x16x32_bf16 v[56:59], v[160:163], v[184:187], v[56:59]
	v_mfma_f32_16x16x32_bf16 v[44:47], v[144:147], v[192:195], v[44:47]
	v_mfma_f32_16x16x32_bf16 v[40:43], v[160:163], v[192:195], v[40:43]
	v_mfma_f32_16x16x32_bf16 v[28:31], v[144:147], v[200:203], v[28:31]
	v_mfma_f32_16x16x32_bf16 v[24:27], v[160:163], v[200:203], v[24:27]
	v_mfma_f32_16x16x32_bf16 v[12:15], v[144:147], v[208:211], v[12:15]
	v_mfma_f32_16x16x32_bf16 v[8:11], v[160:163], v[208:211], v[8:11]
	v_mfma_f32_16x16x32_bf16 v[60:63], v[156:159], v[188:191], v[60:63]
	v_mfma_f32_16x16x32_bf16 v[56:59], v[164:167], v[188:191], v[56:59]
	v_mfma_f32_16x16x32_bf16 v[44:47], v[156:159], v[196:199], v[44:47]
	v_mfma_f32_16x16x32_bf16 v[40:43], v[164:167], v[196:199], v[40:43]
	v_mfma_f32_16x16x32_bf16 v[28:31], v[156:159], v[204:207], v[28:31]
	v_mfma_f32_16x16x32_bf16 v[24:27], v[164:167], v[204:207], v[24:27]
	v_mfma_f32_16x16x32_bf16 v[12:15], v[156:159], v[212:215], v[12:15]
	v_mfma_f32_16x16x32_bf16 v[8:11], v[164:167], v[212:215], v[8:11]
	v_mfma_f32_16x16x32_bf16 v[52:55], v[168:171], v[184:187], v[52:55]
	v_mfma_f32_16x16x32_bf16 v[48:51], v[176:179], v[184:187], v[48:51]
	v_mfma_f32_16x16x32_bf16 v[36:39], v[168:171], v[192:195], v[36:39]
	v_mfma_f32_16x16x32_bf16 v[32:35], v[176:179], v[192:195], v[32:35]
	v_mfma_f32_16x16x32_bf16 v[20:23], v[168:171], v[200:203], v[20:23]
	v_mfma_f32_16x16x32_bf16 v[16:19], v[176:179], v[200:203], v[16:19]
	v_mfma_f32_16x16x32_bf16 v[4:7], v[168:171], v[208:211], v[4:7]
	v_mfma_f32_16x16x32_bf16 v[0:3], v[176:179], v[208:211], v[0:3]
	v_mfma_f32_16x16x32_bf16 v[52:55], v[172:175], v[188:191], v[52:55]
	v_mfma_f32_16x16x32_bf16 v[48:51], v[180:183], v[188:191], v[48:51]
	v_mfma_f32_16x16x32_bf16 v[36:39], v[172:175], v[196:199], v[36:39]
	v_mfma_f32_16x16x32_bf16 v[32:35], v[180:183], v[196:199], v[32:35]
	v_mfma_f32_16x16x32_bf16 v[20:23], v[172:175], v[204:207], v[20:23]
	v_mfma_f32_16x16x32_bf16 v[16:19], v[180:183], v[204:207], v[16:19]
	v_mfma_f32_16x16x32_bf16 v[4:7], v[172:175], v[212:215], v[4:7]
	v_mfma_f32_16x16x32_bf16 v[0:3], v[180:183], v[212:215], v[0:3]
	s_setprio 0
	s_barrier
	s_add_i32 s60, 0, 0x18000
	s_add_i32 s61, 0, 0x1c000
	v_add_u32_e32 v164, s60, v151
	v_add_u32_e32 v180, s61, v151
	ds_read_b128 v[144:147], v164
	ds_read_b128 v[156:159], v164 offset:1024
	ds_read_b128 v[160:163], v164 offset:2048
	ds_read_b128 v[164:167], v164 offset:3072
	ds_read_b128 v[168:171], v180
	ds_read_b128 v[172:175], v180 offset:1024
	ds_read_b128 v[176:179], v180 offset:2048
	ds_read_b128 v[180:183], v180 offset:3072
	s_add_u32 s40, s40, 0x80000
	s_addc_u32 s41, s41, 0
	s_mov_b32 m0, s46
	v_lshl_add_u64 v[222:223], s[40:41], 0, v[128:129]
	ds_read_b128 v[184:187], v155 offset:32768
	ds_read_b128 v[188:191], v155 offset:33792
	ds_read_b128 v[192:195], v155 offset:34816
	ds_read_b128 v[196:199], v155 offset:35840
	ds_read_b128 v[200:203], v155 offset:36864
	ds_read_b128 v[204:207], v155 offset:37888
	ds_read_b128 v[208:211], v155 offset:38912
	ds_read_b128 v[212:215], v155 offset:39936
	global_load_lds_dwordx4 v[222:223], off
	v_lshl_add_u64 v[222:223], s[40:41], 0, v[132:133]
	s_mov_b32 m0, s47
	s_nop 0
	global_load_lds_dwordx4 v[222:223], off
	s_waitcnt vmcnt(8)
	s_waitcnt lgkmcnt(0)
	s_barrier
	s_setprio 1
	s_waitcnt lgkmcnt(0)
	v_mfma_f32_16x16x32_bf16 v[124:127], v[144:147], v[184:187], v[124:127]
	v_mfma_f32_16x16x32_bf16 v[120:123], v[160:163], v[184:187], v[120:123]
	v_mfma_f32_16x16x32_bf16 v[108:111], v[144:147], v[192:195], v[108:111]
	v_mfma_f32_16x16x32_bf16 v[104:107], v[160:163], v[192:195], v[104:107]
	v_mfma_f32_16x16x32_bf16 v[92:95], v[144:147], v[200:203], v[92:95]
	v_mfma_f32_16x16x32_bf16 v[88:91], v[160:163], v[200:203], v[88:91]
	v_mfma_f32_16x16x32_bf16 v[76:79], v[144:147], v[208:211], v[76:79]
	v_mfma_f32_16x16x32_bf16 v[72:75], v[160:163], v[208:211], v[72:75]
	v_mfma_f32_16x16x32_bf16 v[124:127], v[156:159], v[188:191], v[124:127]
	v_mfma_f32_16x16x32_bf16 v[120:123], v[164:167], v[188:191], v[120:123]
	v_mfma_f32_16x16x32_bf16 v[108:111], v[156:159], v[196:199], v[108:111]
	v_mfma_f32_16x16x32_bf16 v[104:107], v[164:167], v[196:199], v[104:107]
	v_mfma_f32_16x16x32_bf16 v[92:95], v[156:159], v[204:207], v[92:95]
	v_mfma_f32_16x16x32_bf16 v[88:91], v[164:167], v[204:207], v[88:91]
	v_mfma_f32_16x16x32_bf16 v[76:79], v[156:159], v[212:215], v[76:79]
	v_mfma_f32_16x16x32_bf16 v[72:75], v[164:167], v[212:215], v[72:75]
	v_mfma_f32_16x16x32_bf16 v[116:119], v[168:171], v[184:187], v[116:119]
	v_mfma_f32_16x16x32_bf16 v[112:115], v[176:179], v[184:187], v[112:115]
	v_mfma_f32_16x16x32_bf16 v[100:103], v[168:171], v[192:195], v[100:103]
	v_mfma_f32_16x16x32_bf16 v[96:99], v[176:179], v[192:195], v[96:99]
	v_mfma_f32_16x16x32_bf16 v[84:87], v[168:171], v[200:203], v[84:87]
	v_mfma_f32_16x16x32_bf16 v[80:83], v[176:179], v[200:203], v[80:83]
	v_mfma_f32_16x16x32_bf16 v[68:71], v[168:171], v[208:211], v[68:71]
	v_mfma_f32_16x16x32_bf16 v[64:67], v[176:179], v[208:211], v[64:67]
	v_mfma_f32_16x16x32_bf16 v[116:119], v[172:175], v[188:191], v[116:119]
	v_mfma_f32_16x16x32_bf16 v[112:115], v[180:183], v[188:191], v[112:115]
	v_mfma_f32_16x16x32_bf16 v[100:103], v[172:175], v[196:199], v[100:103]
	v_mfma_f32_16x16x32_bf16 v[96:99], v[180:183], v[196:199], v[96:99]
	v_mfma_f32_16x16x32_bf16 v[84:87], v[172:175], v[204:207], v[84:87]
	v_mfma_f32_16x16x32_bf16 v[80:83], v[180:183], v[204:207], v[80:83]
	v_mfma_f32_16x16x32_bf16 v[68:71], v[172:175], v[212:215], v[68:71]
	v_mfma_f32_16x16x32_bf16 v[64:67], v[180:183], v[212:215], v[64:67]
	s_setprio 0
	s_barrier
; #define PG8_STAGE(bufoff, gbase, voff) do { _Pragma("unroll") for (int _i = 0; _i < 2; ++_i) \
;         __builtin_amdgcn_global_load_lds((const unsigned*)((const char*)(gbase) + (voff)[_i]), (PG8_LAS unsigned*)(lds + (bufoff) + ldsw + _i * 8192), 16, 0, 0); } while (0)
; #define PG8_LDA(dst, b, h) do { _Pragma("unroll") for (int m = 0; m < 4; ++m) _Pragma("unroll") for (int k = 0; k < 2; ++k) dst[m][k] = *(const PG8_LAS bf16x8*)(lds + PG8_SA(b, h) + aoff + m * 2048 + k * 1024); } while (0)
; #define PG8_MMA(ai, bj, At, Bt) do { __builtin_amdgcn_s_setprio(1); _Pragma("unroll") for (int m = 0; m < 4; ++m) _Pragma("unroll") for (int n = 0; n < 2; ++n) _Pragma("unroll") for (int k = 0; k < 2; ++k) \
;         acc[ai][bj][m][n] = __builtin_amdgcn_mfma_f32_16x16x32_bf16(Bt[n][k], At[m][k], acc[ai][bj][m][n], 0, 0, 0); __builtin_amdgcn_s_setprio(0); } while (0)
; #define PG8_WAIT_V(n) asm volatile("s_waitcnt vmcnt(" #n ")" ::: "memory")
; #define PG8_WAIT_L(n) asm volatile("s_waitcnt lgkmcnt(" #n ")" ::: "memory")
; #define PG8_BAR __builtin_amdgcn_s_barrier()
; #define PG8_SCHED __builtin_amdgcn_sched_barrier(0)
; template <class Epi, class Sched, bool ALIGN_EPI = false, bool SP2 = false>
; __device__ __forceinline__ void gemm_phase(PG8_LAS unsigned char* lds, const Gemm g, const Sched& S, const Epi& E, int tid_in) {
;     ...
;             PG8_LDA(At, 1, 1); PG8_STAGE(PG8_SB(1, 0), b3, voffB); PG8_STAGE(PG8_SB(1, 1), b3 + hstep, voffB); PG8_STAGE(PG8_SA(1, 0), a3, voffA);
;             PG8_WAIT_V(8); PG8_WAIT_L(0); PG8_BAR; PG8_MMA(1, 0, At, B0); PG8_MMA(1, 1, At, B1); PG8_BAR; PG8_SCHED;
;     ...
;         if constexpr (ALIGN_EPI) { if (wr == 0) PG8_BAR; }
	s_add_i32 s40, s60, s44
	v_lshl_add_u64 v[148:149], v[148:149], 0, s[6:7]
	s_mov_b32 m0, s40
	ds_read_b128 v[184:187], v155 offset:49152
	ds_read_b128 v[188:191], v155 offset:50176
	ds_read_b128 v[192:195], v155 offset:51200
	ds_read_b128 v[196:199], v155 offset:52224
	ds_read_b128 v[200:203], v155 offset:53248
	ds_read_b128 v[204:207], v155 offset:54272
	ds_read_b128 v[208:211], v155 offset:55296
	ds_read_b128 v[212:215], v155 offset:56320
	global_load_lds_dwordx4 v[148:149], off
	s_add_i32 m0, s40, 0x2000
	s_add_u32 s38, s38, 0x80080
	v_lshl_add_u64 v[148:149], v[216:217], 0, s[6:7]
	s_addc_u32 s39, s39, 0
	s_add_i32 s40, s61, s44
	global_load_lds_dwordx4 v[148:149], off
	v_lshl_add_u64 v[148:149], s[38:39], 0, v[130:131]
	s_mov_b32 m0, s40
	s_nop 0
	global_load_lds_dwordx4 v[148:149], off
	v_lshl_add_u64 v[148:149], s[38:39], 0, v[134:135]
	s_add_i32 m0, s40, 0x2000
	s_nop 0
	global_load_lds_dwordx4 v[148:149], off
	v_lshl_add_u64 v[148:149], v[218:219], 0, s[6:7]
	s_mov_b32 m0, s49
	s_nop 0
	global_load_lds_dwordx4 v[148:149], off
	v_lshl_add_u64 v[148:149], v[220:221], 0, s[6:7]
	s_mov_b32 m0, s50
	s_nop 0
	global_load_lds_dwordx4 v[148:149], off
	s_waitcnt vmcnt(8)
	s_waitcnt lgkmcnt(0)
	s_barrier
	s_setprio 1
	s_waitcnt lgkmcnt(0)
	v_mfma_f32_16x16x32_bf16 v[60:63], v[144:147], v[184:187], v[60:63]
	v_mfma_f32_16x16x32_bf16 v[56:59], v[160:163], v[184:187], v[56:59]
	v_mfma_f32_16x16x32_bf16 v[44:47], v[144:147], v[192:195], v[44:47]
	v_mfma_f32_16x16x32_bf16 v[40:43], v[160:163], v[192:195], v[40:43]
	v_mfma_f32_16x16x32_bf16 v[28:31], v[144:147], v[200:203], v[28:31]
	v_mfma_f32_16x16x32_bf16 v[24:27], v[160:163], v[200:203], v[24:27]
	v_mfma_f32_16x16x32_bf16 v[12:15], v[144:147], v[208:211], v[12:15]
	v_mfma_f32_16x16x32_bf16 v[8:11], v[160:163], v[208:211], v[8:11]
	v_mfma_f32_16x16x32_bf16 v[60:63], v[156:159], v[188:191], v[60:63]
	v_mfma_f32_16x16x32_bf16 v[56:59], v[164:167], v[188:191], v[56:59]
	v_mfma_f32_16x16x32_bf16 v[44:47], v[156:159], v[196:199], v[44:47]
	v_mfma_f32_16x16x32_bf16 v[40:43], v[164:167], v[196:199], v[40:43]
	v_mfma_f32_16x16x32_bf16 v[28:31], v[156:159], v[204:207], v[28:31]
	v_mfma_f32_16x16x32_bf16 v[24:27], v[164:167], v[204:207], v[24:27]
	v_mfma_f32_16x16x32_bf16 v[12:15], v[156:159], v[212:215], v[12:15]
	v_mfma_f32_16x16x32_bf16 v[8:11], v[164:167], v[212:215], v[8:11]
	v_mfma_f32_16x16x32_bf16 v[52:55], v[168:171], v[184:187], v[52:55]
	v_mfma_f32_16x16x32_bf16 v[48:51], v[176:179], v[184:187], v[48:51]
	v_mfma_f32_16x16x32_bf16 v[36:39], v[168:171], v[192:195], v[36:39]
	v_mfma_f32_16x16x32_bf16 v[32:35], v[176:179], v[192:195], v[32:35]
	v_mfma_f32_16x16x32_bf16 v[20:23], v[168:171], v[200:203], v[20:23]
	v_mfma_f32_16x16x32_bf16 v[16:19], v[176:179], v[200:203], v[16:19]
	v_mfma_f32_16x16x32_bf16 v[4:7], v[168:171], v[208:211], v[4:7]
	v_mfma_f32_16x16x32_bf16 v[0:3], v[176:179], v[208:211], v[0:3]
	v_mfma_f32_16x16x32_bf16 v[52:55], v[172:175], v[188:191], v[52:55]
	v_mfma_f32_16x16x32_bf16 v[48:51], v[180:183], v[188:191], v[48:51]
	v_mfma_f32_16x16x32_bf16 v[36:39], v[172:175], v[196:199], v[36:39]
	v_mfma_f32_16x16x32_bf16 v[32:35], v[180:183], v[196:199], v[32:35]
	v_mfma_f32_16x16x32_bf16 v[20:23], v[172:175], v[204:207], v[20:23]
	v_mfma_f32_16x16x32_bf16 v[16:19], v[180:183], v[204:207], v[16:19]
	v_mfma_f32_16x16x32_bf16 v[4:7], v[172:175], v[212:215], v[4:7]
	v_mfma_f32_16x16x32_bf16 v[0:3], v[180:183], v[212:215], v[0:3]
	s_setprio 0
	s_barrier
	s_add_i32 s59, s59, 2
	s_add_u32 s36, s36, 0x100
	s_addc_u32 s37, s37, 0
	s_add_u32 s57, s57, 0x100
	s_addc_u32 s58, s58, 0
	s_cmp_gt_u32 s59, 29
	s_cbranch_scc0 .LBB0_484
	s_and_b64 vcc, exec, s[8:9]
	s_cbranch_vccz .LBB0_487
	s_barrier
